# also lru_s1/hy_s1/hy_s3 conv taps: predicated ushort loads de-serialized (pre-zeroed temps, one deferred wait)
# speedup vs baseline: 1.0385x; 1.0198x over previous
; __device__ __forceinline__ float bf2f(bf16_t b) { return __uint_as_float(((unsigned)b) << 16); }
; #define p (*kparams())
; __device__ __forceinline__ void lru_s1_item(CParams& p, int layer, int item, LAS unsigned char* lds) {
;     ...
;         const int j = tid & 63, tq = tid >> 6, ch = kb * 64 + j;
;         const float* cw = p.in[5] + layer * 4 * W; const float cb = p.in[6][layer * W + ch];
;         const float w0 = cw[ch], w1 = cw[W + ch], w2 = cw[2 * W + ch], w3 = cw[3 * W + ch];
;         const int t0 = c * 128 + 16 * tq - 112;
;         float xv[19];
; #pragma unroll
;         for (int q = 0; q < 19; ++q) { const int t = t0 - 2 + q; xv[q] = (t >= 0 && t < T) ? bf2f(P[(size_t)row_of(b, t) * NMIX + ch]) : 0.f; }
.LBB0_347:
	s_or_b64 exec, exec, s[14:15]
	s_ashr_i32 s9, s54, 3
	s_mul_hi_i32 s10, s9, 0x7e07e07f
	s_lshr_b32 s11, s10, 31
	s_ashr_i32 s28, s10, 5
	s_load_dwordx4 s[40:43], s[4:5], 0x28
	s_add_i32 s28, s28, s11
	s_mul_i32 s10, s28, 0x41
	s_sub_i32 s30, s9, s10
	v_and_b32_e32 v3, 63, v73
	s_lshl_b32 s29, s8, 6
	v_readlane_b32 s8, v255, 42
	v_or_b32_e32 v9, s29, v3
	v_readlane_b32 s9, v255, 43
	s_waitcnt lgkmcnt(0)
	v_mov_b32_e32 v0, s42
	v_mov_b32_e32 v1, s43
	s_lshl_b64 s[8:9], s[8:9], 2
	v_or_b32_e32 v4, s6, v9
	v_mov_b32_e32 v5, v2
	s_add_u32 s8, s40, s8
	v_lshl_add_u64 v[0:1], v[4:5], 2, v[0:1]
	s_addc_u32 s9, s41, s9
	global_load_dword v4, v[0:1], off
	v_lshlrev_b32_e32 v0, 2, v9
	v_mov_b32_e32 v1, v2
	v_lshl_add_u64 v[6:7], s[8:9], 0, v[0:1]
	s_movk_i32 s10, 0x1000
	v_add_co_u32_e32 v10, vcc, s10, v6
	v_ashrrev_i32_e32 v72, 6, v73
	s_nop 0
	v_addc_co_u32_e32 v11, vcc, 0, v7, vcc
	global_load_dword v7, v0, s[8:9]
	global_load_dword v5, v0, s[8:9] offset:2048
	global_load_dword v8, v[10:11], off
	global_load_dword v6, v[10:11], off offset:2048
	s_lshl_b32 s8, s30, 7
	v_lshlrev_b32_e32 v0, 1, v9
	v_lshlrev_b32_e32 v70, 4, v72
	s_add_i32 s9, s8, 0xffffff8e
	v_lshl_add_u64 v[0:1], s[34:35], 0, v[0:1]
	s_mov_b64 s[10:11], 0x19602000
	v_add_u32_e32 v12, s9, v70
	v_lshl_add_u64 v[0:1], v[0:1], 0, s[10:11]
	s_lshl_b32 s9, s28, 13
	s_lshl_b32 s10, s28, 7
	s_add_i32 s11, s9, -16
	s_add_i32 s31, s10, 0x4070
	v_cmp_gt_u32_e32 vcc, s91, v12
	v_mov_b32_e32 v9, 0
	v_mov_b32_e32 v10, 0
	v_mov_b32_e32 v120, 0
	s_and_saveexec_b64 s[14:15], vcc
	s_cbranch_execz .LBB0_349
	v_mov_b32_e32 v10, s11
	v_mov_b32_e32 v11, s31
	v_cmp_gt_u32_e64 s[40:41], 16, v12
	s_nop 1
	v_cndmask_b32_e64 v10, v10, v11, s[40:41]
	v_add_u32_e32 v10, v10, v12
	v_mad_i64_i32 v[10:11], s[40:41], v10, s26, v[0:1]
	global_load_ushort v120, v[10:11], off
.LBB0_349:
	s_or_b64 exec, exec, s[14:15]
	v_mov_b32_e32 v121, 0
	s_and_saveexec_b64 s[14:15], vcc
	s_cbranch_execz .LBB0_351
	v_mov_b32_e32 v9, s11
	v_mov_b32_e32 v11, s31
	v_cmp_gt_u32_e32 vcc, 16, v12
	s_nop 1
	v_cndmask_b32_e32 v9, v9, v11, vcc
	v_add3_u32 v9, v9, v12, 1
	v_mad_i64_i32 v[14:15], s[40:41], v9, s26, v[0:1]
	global_load_ushort v121, v[14:15], off
.LBB0_351:
	s_or_b64 exec, exec, s[14:15]
	v_add_u32_e32 v14, 2, v12
	v_cmp_gt_u32_e32 vcc, s91, v14
	v_mov_b32_e32 v11, 0
	v_mov_b32_e32 v13, 0
	v_mov_b32_e32 v122, 0
	s_and_saveexec_b64 s[14:15], vcc
	s_cbranch_execz .LBB0_353
	v_mov_b32_e32 v13, s11
	v_mov_b32_e32 v15, s31
	v_cmp_eq_u32_e32 vcc, 0, v14
	s_nop 1
	v_cndmask_b32_e32 v13, v13, v15, vcc
	v_add_u32_e32 v13, v13, v14
	v_mad_i64_i32 v[14:15], s[40:41], v13, s26, v[0:1]
	global_load_ushort v122, v[14:15], off
.LBB0_353:
	s_or_b64 exec, exec, s[14:15]
	v_add_u32_e32 v14, 3, v12
	v_cmp_gt_u32_e32 vcc, s91, v14
	v_mov_b32_e32 v123, 0
	s_and_saveexec_b64 s[14:15], vcc
	s_cbranch_execz .LBB0_355
	v_mov_b32_e32 v11, s11
	v_mov_b32_e32 v15, s31
	v_cmp_gt_u32_e32 vcc, 16, v14
	s_nop 1
	v_cndmask_b32_e32 v11, v11, v15, vcc
	v_add_u32_e32 v11, v11, v14
	v_mad_i64_i32 v[14:15], s[40:41], v11, s26, v[0:1]
	global_load_ushort v123, v[14:15], off
.LBB0_355:
	s_or_b64 exec, exec, s[14:15]
	v_add_u32_e32 v16, 4, v12
	v_cmp_gt_u32_e32 vcc, s91, v16
	v_mov_b32_e32 v14, 0
	v_mov_b32_e32 v15, 0
	v_mov_b32_e32 v124, 0
	s_and_saveexec_b64 s[14:15], vcc
	s_cbranch_execz .LBB0_357
	v_mov_b32_e32 v15, s11
	v_mov_b32_e32 v17, s31
	v_cmp_gt_u32_e32 vcc, 16, v16
	s_nop 1
	v_cndmask_b32_e32 v15, v15, v17, vcc
	v_add_u32_e32 v15, v15, v16
	v_mad_i64_i32 v[16:17], s[40:41], v15, s26, v[0:1]
	global_load_ushort v124, v[16:17], off
.LBB0_357:
	s_or_b64 exec, exec, s[14:15]
	v_add_u32_e32 v16, 5, v12
	v_cmp_gt_u32_e32 vcc, s91, v16
	v_mov_b32_e32 v125, 0
	s_and_saveexec_b64 s[14:15], vcc
	s_cbranch_execz .LBB0_359
	v_mov_b32_e32 v14, s11
	v_mov_b32_e32 v17, s31
	v_cmp_gt_u32_e32 vcc, 16, v16
	s_nop 1
	v_cndmask_b32_e32 v14, v14, v17, vcc
	v_add_u32_e32 v14, v14, v16
	v_mad_i64_i32 v[16:17], s[40:41], v14, s26, v[0:1]
	global_load_ushort v125, v[16:17], off
.LBB0_359:
	s_or_b64 exec, exec, s[14:15]
	v_add_u32_e32 v18, 6, v12
	v_cmp_gt_u32_e32 vcc, s91, v18
	v_mov_b32_e32 v16, 0
	v_mov_b32_e32 v17, 0
	v_mov_b32_e32 v126, 0
	s_and_saveexec_b64 s[14:15], vcc
	s_cbranch_execz .LBB0_361
	v_mov_b32_e32 v17, s11
	v_mov_b32_e32 v19, s31
	v_cmp_gt_u32_e32 vcc, 16, v18
	s_nop 1
	v_cndmask_b32_e32 v17, v17, v19, vcc
	v_add_u32_e32 v17, v17, v18
	v_mad_i64_i32 v[18:19], s[40:41], v17, s26, v[0:1]
	global_load_ushort v126, v[18:19], off
.LBB0_361:
	s_or_b64 exec, exec, s[14:15]
	v_add_u32_e32 v18, 7, v12
	v_cmp_gt_u32_e32 vcc, s91, v18
	v_mov_b32_e32 v127, 0
	s_and_saveexec_b64 s[14:15], vcc
	s_cbranch_execz .LBB0_363
	v_mov_b32_e32 v16, s11
	v_mov_b32_e32 v19, s31
	v_cmp_gt_u32_e32 vcc, 16, v18
	s_nop 1
	v_cndmask_b32_e32 v16, v16, v19, vcc
	v_add_u32_e32 v16, v16, v18
	v_mad_i64_i32 v[18:19], s[40:41], v16, s26, v[0:1]
	global_load_ushort v127, v[18:19], off
.LBB0_363:
	s_or_b64 exec, exec, s[14:15]
	v_add_u32_e32 v20, 8, v12
	v_cmp_gt_u32_e32 vcc, s91, v20
	v_mov_b32_e32 v18, 0
	v_mov_b32_e32 v19, 0
	v_mov_b32_e32 v128, 0
	s_and_saveexec_b64 s[14:15], vcc
	s_cbranch_execz .LBB0_365
	v_mov_b32_e32 v19, s11
	v_mov_b32_e32 v21, s31
	v_cmp_gt_u32_e32 vcc, 16, v20
	s_nop 1
	v_cndmask_b32_e32 v19, v19, v21, vcc
	v_add_u32_e32 v19, v19, v20
	v_mad_i64_i32 v[20:21], s[40:41], v19, s26, v[0:1]
	global_load_ushort v128, v[20:21], off
.LBB0_365:
	s_or_b64 exec, exec, s[14:15]
	v_add_u32_e32 v20, 9, v12
	v_cmp_gt_u32_e32 vcc, s91, v20
	v_mov_b32_e32 v129, 0
	s_and_saveexec_b64 s[14:15], vcc
	s_cbranch_execz .LBB0_367
	v_mov_b32_e32 v18, s11
	v_mov_b32_e32 v21, s31
	v_cmp_gt_u32_e32 vcc, 16, v20
	s_nop 1
	v_cndmask_b32_e32 v18, v18, v21, vcc
	v_add_u32_e32 v18, v18, v20
	v_mad_i64_i32 v[20:21], s[40:41], v18, s26, v[0:1]
	global_load_ushort v129, v[20:21], off
; __device__ __forceinline__ float bf2f(bf16_t b) { return __uint_as_float(((unsigned)b) << 16); }
; __device__ __forceinline__ void lru_s1_item(CParams& p, int layer, int item, LAS unsigned char* lds) {
;     ...
;         for (int q = 0; q < 19; ++q) { const int t = t0 - 2 + q; xv[q] = (t >= 0 && t < T) ? bf2f(P[(size_t)row_of(b, t) * NMIX + ch]) : 0.f; }
; #pragma unroll
;         for (int tt = 0; tt < 16; ++tt) { const float x = cb + w0 * xv[tt] + w1 * xv[tt + 1] + w2 * xv[tt + 2] + w3 * xv[tt + 3];
.LBB0_367:
	s_or_b64 exec, exec, s[14:15]
	v_add_u32_e32 v22, 10, v12
	v_cmp_gt_u32_e32 vcc, s91, v22
	v_mov_b32_e32 v20, 0
	v_mov_b32_e32 v21, 0
	v_mov_b32_e32 v130, 0
	s_and_saveexec_b64 s[14:15], vcc
	s_cbranch_execz .LBB0_369
	v_mov_b32_e32 v21, s11
	v_mov_b32_e32 v23, s31
	v_cmp_gt_u32_e32 vcc, 16, v22
	s_nop 1
	v_cndmask_b32_e32 v21, v21, v23, vcc
	v_add_u32_e32 v21, v21, v22
	v_mad_i64_i32 v[22:23], s[40:41], v21, s26, v[0:1]
	global_load_ushort v130, v[22:23], off
.LBB0_369:
	s_or_b64 exec, exec, s[14:15]
	v_add_u32_e32 v22, 11, v12
	v_cmp_gt_u32_e32 vcc, s91, v22
	v_mov_b32_e32 v131, 0
	s_and_saveexec_b64 s[14:15], vcc
	s_cbranch_execz .LBB0_371
	v_mov_b32_e32 v20, s11
	v_mov_b32_e32 v23, s31
	v_cmp_gt_u32_e32 vcc, 16, v22
	s_nop 1
	v_cndmask_b32_e32 v20, v20, v23, vcc
	v_add_u32_e32 v20, v20, v22
	v_mad_i64_i32 v[22:23], s[40:41], v20, s26, v[0:1]
	global_load_ushort v131, v[22:23], off
.LBB0_371:
	s_or_b64 exec, exec, s[14:15]
	v_add_u32_e32 v24, 12, v12
	v_cmp_gt_u32_e32 vcc, s91, v24
	v_mov_b32_e32 v22, 0
	v_mov_b32_e32 v23, 0
	v_mov_b32_e32 v132, 0
	s_and_saveexec_b64 s[14:15], vcc
	s_cbranch_execz .LBB0_373
	v_mov_b32_e32 v23, s11
	v_mov_b32_e32 v25, s31
	v_cmp_gt_u32_e32 vcc, 16, v24
	s_nop 1
	v_cndmask_b32_e32 v23, v23, v25, vcc
	v_add_u32_e32 v23, v23, v24
	v_mad_i64_i32 v[24:25], s[40:41], v23, s26, v[0:1]
	global_load_ushort v132, v[24:25], off
.LBB0_373:
	s_or_b64 exec, exec, s[14:15]
	v_add_u32_e32 v24, 13, v12
	v_cmp_gt_u32_e32 vcc, s91, v24
	v_mov_b32_e32 v133, 0
	s_and_saveexec_b64 s[14:15], vcc
	s_cbranch_execz .LBB0_375
	v_mov_b32_e32 v22, s11
	v_mov_b32_e32 v25, s31
	v_cmp_gt_u32_e32 vcc, 16, v24
	s_nop 1
	v_cndmask_b32_e32 v22, v22, v25, vcc
	v_add_u32_e32 v22, v22, v24
	v_mad_i64_i32 v[24:25], s[40:41], v22, s26, v[0:1]
	global_load_ushort v133, v[24:25], off
.LBB0_375:
	s_or_b64 exec, exec, s[14:15]
	v_add_u32_e32 v26, 14, v12
	v_cmp_gt_u32_e32 vcc, s91, v26
	v_mov_b32_e32 v24, 0
	v_mov_b32_e32 v25, 0
	v_mov_b32_e32 v134, 0
	s_and_saveexec_b64 s[14:15], vcc
	s_cbranch_execz .LBB0_377
	v_mov_b32_e32 v25, s11
	v_mov_b32_e32 v27, s31
	v_cmp_gt_u32_e32 vcc, 16, v26
	s_nop 1
	v_cndmask_b32_e32 v25, v25, v27, vcc
	v_add_u32_e32 v25, v25, v26
	v_mad_i64_i32 v[26:27], s[40:41], v25, s26, v[0:1]
	global_load_ushort v134, v[26:27], off
.LBB0_377:
	s_or_b64 exec, exec, s[14:15]
	v_add_u32_e32 v26, 15, v12
	v_cmp_gt_u32_e32 vcc, s91, v26
	v_mov_b32_e32 v135, 0
	s_and_saveexec_b64 s[14:15], vcc
	s_cbranch_execz .LBB0_379
	v_mov_b32_e32 v24, s11
	v_mov_b32_e32 v27, s31
	v_cmp_gt_u32_e32 vcc, 16, v26
	s_nop 1
	v_cndmask_b32_e32 v24, v24, v27, vcc
	v_add_u32_e32 v24, v24, v26
	v_mad_i64_i32 v[26:27], s[40:41], v24, s26, v[0:1]
	global_load_ushort v135, v[26:27], off
.LBB0_379:
	s_or_b64 exec, exec, s[14:15]
	v_add_u32_e32 v28, 16, v12
	v_cmp_gt_u32_e32 vcc, s91, v28
	v_mov_b32_e32 v26, 0
	v_mov_b32_e32 v27, 0
	v_mov_b32_e32 v136, 0
	s_and_saveexec_b64 s[14:15], vcc
	s_cbranch_execz .LBB0_381
	s_movk_i32 s36, 0xffef
	v_mov_b32_e32 v27, s11
	v_mov_b32_e32 v29, s31
	v_cmp_lt_u32_e32 vcc, s36, v12
	s_nop 1
	v_cndmask_b32_e32 v27, v27, v29, vcc
	v_add_u32_e32 v27, v27, v28
	v_mad_i64_i32 v[28:29], s[40:41], v27, s26, v[0:1]
	global_load_ushort v136, v[28:29], off
.LBB0_381:
	s_or_b64 exec, exec, s[14:15]
	v_add_u32_e32 v28, 17, v12
	v_cmp_gt_u32_e32 vcc, s91, v28
	v_mov_b32_e32 v137, 0
	s_and_saveexec_b64 s[14:15], vcc
	s_cbranch_execz .LBB0_383
	v_mov_b32_e32 v26, s11
	v_mov_b32_e32 v29, s31
	v_cmp_eq_u32_e32 vcc, 15, v28
	s_nop 1
	v_cndmask_b32_e32 v26, v26, v29, vcc
	v_add_u32_e32 v26, v26, v28
	v_mad_i64_i32 v[28:29], s[40:41], v26, s26, v[0:1]
	global_load_ushort v137, v[28:29], off
.LBB0_383:
	s_or_b64 exec, exec, s[14:15]
	v_add_u32_e32 v28, 18, v12
	v_cmp_gt_u32_e32 vcc, s91, v28
	v_mov_b32_e32 v12, 0
	v_mov_b32_e32 v138, 0
	s_and_saveexec_b64 s[14:15], vcc
	s_cbranch_execz .LBB0_385
	v_mov_b32_e32 v12, s11
	v_mov_b32_e32 v29, s31
	v_cmp_eq_u32_e32 vcc, 0, v28
	s_nop 1
	v_cndmask_b32_e32 v12, v12, v29, vcc
	v_add_u32_e32 v12, v12, v28
	v_mad_i64_i32 v[0:1], s[40:41], v12, s26, v[0:1]
	global_load_ushort v138, v[0:1], off
.LBB0_385:
	s_or_b64 exec, exec, s[14:15]
	s_waitcnt vmcnt(0)
	v_lshlrev_b32_e32 v10, 16, v120
	v_lshlrev_b32_e32 v9, 16, v121
	v_lshlrev_b32_e32 v13, 16, v122
	v_lshlrev_b32_e32 v11, 16, v123
	v_lshlrev_b32_e32 v15, 16, v124
	v_lshlrev_b32_e32 v14, 16, v125
	v_lshlrev_b32_e32 v17, 16, v126
	v_lshlrev_b32_e32 v16, 16, v127
	v_lshlrev_b32_e32 v19, 16, v128
	v_lshlrev_b32_e32 v18, 16, v129
	v_lshlrev_b32_e32 v21, 16, v130
	v_lshlrev_b32_e32 v20, 16, v131
	v_lshlrev_b32_e32 v23, 16, v132
	v_lshlrev_b32_e32 v22, 16, v133
	v_lshlrev_b32_e32 v25, 16, v134
	v_lshlrev_b32_e32 v24, 16, v135
	v_lshlrev_b32_e32 v27, 16, v136
	v_lshlrev_b32_e32 v26, 16, v137
	v_lshlrev_b32_e32 v12, 16, v138
	s_waitcnt vmcnt(3)
	v_fma_f32 v1, v7, v10, v4
	s_waitcnt vmcnt(2)
	v_fmac_f32_e32 v1, v5, v9
	v_lshl_add_u32 v30, v3, 2, 0
	s_waitcnt vmcnt(1)
	v_fmac_f32_e32 v1, v8, v13
	v_lshlrev_b32_e32 v71, 12, v72
	v_lshlrev_b32_e32 v0, 1, v3
	s_waitcnt vmcnt(0)
; #define LAS __attribute__((address_space(3)))
; __device__ __forceinline__ unsigned f2bf(float f) { return pk2(f, 0.f) & 0xffffu; }
; __device__ __forceinline__ void lru_s1_item(CParams& p, int layer, int item, LAS unsigned char* lds) {
;     ...
;         for (int tt = 0; tt < 16; ++tt) { const float x = cb + w0 * xv[tt] + w1 * xv[tt + 1] + w2 * xv[tt + 2] + w3 * xv[tt + 3];
;             XCf[(16 * tq + tt) * 64 + j] = x; XCb[(16 * tq + tt) * XS + j] = (bf16_t)f2bf(x); } }
;     __syncthreads();
;     const int r = lane & 15, h = lane >> 4;
;     f32x4 acc[16];
; #pragma unroll
;     for (int nt = 0; nt < 16; ++nt) acc[nt] = (f32x4){0.f, 0.f, 0.f, 0.f};
; #pragma unroll
;     for (int ks = 0; ks < 2; ++ks) { const bf16x8 a = *(const LAS bf16x8*)(XCb + (16 * wave + r) * XS + 32 * ks + 8 * h);
; #pragma unroll
;         for (int nt = 0; nt < 16; ++nt) { const bf16x8 bw = *(const LAS bf16x8*)(WT + (16 * nt + r) * XS + 32 * ks + 8 * h);
;             acc[nt] = __builtin_amdgcn_mfma_f32_16x16x32_bf16(a, bw, acc[nt], 0, 0, 0); } }
	v_fmac_f32_e32 v1, v6, v11
	v_add_u32_e32 v10, v30, v71
	v_sub_u32_e32 v0, v30, v0
	ds_write_b32 v10, v1 offset:55296
	v_cvt_pk_bf16_f32 v1, v1, s0
	s_movk_i32 s11, 0x900
	v_mad_u64_u32 v[28:29], s[14:15], v72, s11, v[0:1]
	ds_write_b16 v28, v1
	v_fma_f32 v1, v7, v9, v4
	v_fmac_f32_e32 v1, v5, v13
	v_fmac_f32_e32 v1, v8, v11
	v_or_b32_e32 v9, 1, v70
	v_fmac_f32_e32 v1, v6, v15
	v_lshl_add_u32 v10, v9, 8, v30
	ds_write_b32 v10, v1 offset:55296
	v_cvt_pk_bf16_f32 v10, v1, s0
	v_mad_u64_u32 v[0:1], s[14:15], v9, s27, v[0:1]
	v_fma_f32 v1, v7, v13, v4
	v_fmac_f32_e32 v1, v5, v11
	v_fmac_f32_e32 v1, v8, v15
	v_fmac_f32_e32 v1, v6, v14
	ds_write_b16 v0, v10
	v_cvt_pk_bf16_f32 v10, v1, s0
	ds_write_b16 v0, v10 offset:144
	v_fma_f32 v10, v7, v11, v4
	v_fmac_f32_e32 v10, v5, v15
	v_fmac_f32_e32 v10, v8, v14
	v_lshl_add_u32 v9, v70, 8, v30
	v_fmac_f32_e32 v10, v6, v17
	ds_write2st64_b32 v9, v1, v10 offset0:218 offset1:219
	v_cvt_pk_bf16_f32 v1, v10, s0
	ds_write_b16 v0, v1 offset:288
	v_fma_f32 v1, v7, v15, v4
	v_fmac_f32_e32 v1, v5, v14
	v_fmac_f32_e32 v1, v8, v17
	v_fmac_f32_e32 v1, v6, v16
	v_cvt_pk_bf16_f32 v10, v1, s0
	ds_write_b16 v0, v10 offset:432
	v_fma_f32 v10, v7, v14, v4
	v_fmac_f32_e32 v10, v5, v17
	v_fmac_f32_e32 v10, v8, v16
	v_fmac_f32_e32 v10, v6, v19
	ds_write2st64_b32 v9, v1, v10 offset0:220 offset1:221
	v_cvt_pk_bf16_f32 v1, v10, s0
	ds_write_b16 v0, v1 offset:576
	v_fma_f32 v1, v7, v17, v4
	v_fmac_f32_e32 v1, v5, v16
	v_fmac_f32_e32 v1, v8, v19
	v_fmac_f32_e32 v1, v6, v18
	v_cvt_pk_bf16_f32 v10, v1, s0
	ds_write_b16 v0, v10 offset:720
	v_fma_f32 v10, v7, v16, v4
	v_fmac_f32_e32 v10, v5, v19
	v_fmac_f32_e32 v10, v8, v18
	v_fmac_f32_e32 v10, v6, v21
	ds_write2st64_b32 v9, v1, v10 offset0:222 offset1:223
	v_cvt_pk_bf16_f32 v1, v10, s0
	ds_write_b16 v0, v1 offset:864
	v_fma_f32 v1, v7, v19, v4
	v_fmac_f32_e32 v1, v5, v18
	v_fmac_f32_e32 v1, v8, v21
	v_fmac_f32_e32 v1, v6, v20
	v_cvt_pk_bf16_f32 v10, v1, s0
	ds_write_b16 v0, v10 offset:1008
	v_fma_f32 v10, v7, v18, v4
	v_fmac_f32_e32 v10, v5, v21
	v_fmac_f32_e32 v10, v8, v20
	v_fmac_f32_e32 v10, v6, v23
	ds_write2st64_b32 v9, v1, v10 offset0:224 offset1:225
	v_cvt_pk_bf16_f32 v1, v10, s0
	ds_write_b16 v0, v1 offset:1152
	v_fma_f32 v1, v7, v21, v4
	v_fmac_f32_e32 v1, v5, v20
	v_fmac_f32_e32 v1, v8, v23
	v_fmac_f32_e32 v1, v6, v22
	v_cvt_pk_bf16_f32 v10, v1, s0
	ds_write_b16 v0, v10 offset:1296
	v_fma_f32 v10, v7, v20, v4
	v_fmac_f32_e32 v10, v5, v23
	v_fmac_f32_e32 v10, v8, v22
	v_fmac_f32_e32 v10, v6, v25
	ds_write2st64_b32 v9, v1, v10 offset0:226 offset1:227
	v_cvt_pk_bf16_f32 v1, v10, s0
	ds_write_b16 v0, v1 offset:1440
	v_fma_f32 v1, v7, v23, v4
	v_fmac_f32_e32 v1, v5, v22
	v_fmac_f32_e32 v1, v8, v25
	v_fmac_f32_e32 v1, v6, v24
	v_cvt_pk_bf16_f32 v10, v1, s0
	ds_write_b16 v0, v10 offset:1584
	v_fma_f32 v10, v7, v22, v4
	v_fmac_f32_e32 v10, v5, v25
	v_fmac_f32_e32 v10, v8, v24
	v_fmac_f32_e32 v10, v6, v27
	ds_write2st64_b32 v9, v1, v10 offset0:228 offset1:229
	v_cvt_pk_bf16_f32 v1, v10, s0
	ds_write_b16 v0, v1 offset:1728
	v_fma_f32 v1, v7, v25, v4
	v_fmac_f32_e32 v4, v7, v24
	v_fmac_f32_e32 v1, v5, v24
	v_fmac_f32_e32 v4, v5, v27
	v_fmac_f32_e32 v1, v8, v27
	v_fmac_f32_e32 v4, v8, v26
	v_fmac_f32_e32 v1, v6, v26
	v_fmac_f32_e32 v4, v6, v12
	v_cvt_pk_bf16_f32 v10, v1, s0
	ds_write2st64_b32 v9, v1, v4 offset0:230 offset1:231
	v_cvt_pk_bf16_f32 v1, v4, s0
	ds_write_b16 v0, v10 offset:1872
	ds_write_b16 v0, v1 offset:2016
	v_and_b32_e32 v79, 15, v73
	v_and_b32_e32 v0, 48, v3
	v_or_b32_e32 v1, v70, v79
	v_add_u32_e32 v0, 0, v0
	v_mad_u64_u32 v[60:61], s[14:15], v1, s27, v[0:1]
	s_waitcnt lgkmcnt(0)
	s_barrier
	ds_read_b128 v[12:15], v60
	v_mad_u32_u24 v74, v79, s27, v0
	ds_read_b128 v[4:7], v74 offset:18432
	ds_read_b128 v[8:11], v74 offset:46080
	s_waitcnt lgkmcnt(1)
	v_mfma_f32_16x16x32_bf16 v[28:31], v[12:15], v[4:7], 0
	ds_read_b128 v[4:7], v74 offset:20736
	v_or_b32_e32 v80, s29, v79
	v_or_b32_e32 v0, s56, v80
	s_waitcnt lgkmcnt(0)
	v_mfma_f32_16x16x32_bf16 v[32:35], v[12:15], v[4:7], 0
	ds_read_b128 v[4:7], v74 offset:23040
	v_mov_b32_e32 v1, v2
	v_lshlrev_b64 v[0:1], 2, v[0:1]
	s_waitcnt lgkmcnt(0)
	v_mfma_f32_16x16x32_bf16 v[48:51], v[12:15], v[4:7], 0
	ds_read_b128 v[4:7], v74 offset:25344
	s_add_u32 s52, s34, 0x2ba82000
	s_addc_u32 s53, s35, 0
	s_waitcnt lgkmcnt(0)
	v_mfma_f32_16x16x32_bf16 v[56:59], v[12:15], v[4:7], 0
	ds_read_b128 v[4:7], v74 offset:27648
	s_add_u32 s42, s34, 0x2db02000
	s_addc_u32 s43, s35, 0
	s_waitcnt lgkmcnt(0)
	v_mfma_f32_16x16x32_bf16 v[64:67], v[12:15], v[4:7], 0
	ds_read_b128 v[4:7], v74 offset:29952
	s_mov_b32 s11, 0x42ce8ed0
	s_mov_b32 s14, 0xc2b17218
	s_waitcnt lgkmcnt(0)
	v_mfma_f32_16x16x32_bf16 v[82:85], v[12:15], v[4:7], 0
	ds_read_b128 v[4:7], v74 offset:32256
	v_lshlrev_b32_e32 v81, 2, v79
	s_addk_i32 s10, 0x4000
	s_waitcnt lgkmcnt(0)
	v_mfma_f32_16x16x32_bf16 v[86:89], v[12:15], v[4:7], 0
	ds_read_b128 v[4:7], v74 offset:34560
	v_or_b32_e32 v78, 16, v79
	v_or_b32_e32 v77, 32, v79
	v_mfma_f32_16x16x32_bf16 v[40:43], v[12:15], v[8:11], 0
	ds_read_b128 v[8:11], v74 offset:48384
	v_or_b32_e32 v75, 48, v79
	s_waitcnt lgkmcnt(1)
	v_mfma_f32_16x16x32_bf16 v[16:19], v[12:15], v[4:7], 0
	ds_read_b128 v[4:7], v74 offset:36864
	s_waitcnt lgkmcnt(0)
	v_mfma_f32_16x16x32_bf16 v[52:55], v[12:15], v[4:7], 0
	ds_read_b128 v[4:7], v74 offset:39168
	s_waitcnt lgkmcnt(0)
	v_mfma_f32_16x16x32_bf16 v[36:39], v[12:15], v[4:7], 0
	ds_read_b128 v[4:7], v74 offset:41472
	s_waitcnt lgkmcnt(0)
	v_mfma_f32_16x16x32_bf16 v[20:23], v[12:15], v[4:7], 0
	ds_read_b128 v[4:7], v74 offset:43776
	v_mfma_f32_16x16x32_bf16 v[24:27], v[12:15], v[8:11], 0
	ds_read_b128 v[8:11], v74 offset:50688
	ds_read_b128 v[44:47], v74 offset:52992
	ds_read_b128 v[90:93], v60 offset:64
	s_waitcnt lgkmcnt(3)
; #define LAS __attribute__((address_space(3)))
; #define p (*kparams())
; __device__ __forceinline__ void lru_s1_item(CParams& p, int layer, int item, LAS unsigned char* lds) {
;     ...
;     for (int ks = 0; ks < 2; ++ks) { const bf16x8 a = *(const LAS bf16x8*)(XCb + (16 * wave + r) * XS + 32 * ks + 8 * h);
; #pragma unroll
;         for (int nt = 0; nt < 16; ++nt) { const bf16x8 bw = *(const LAS bf16x8*)(WT + (16 * nt + r) * XS + 32 * ks + 8 * h);
;             acc[nt] = __builtin_amdgcn_mfma_f32_16x16x32_bf16(a, bw, acc[nt], 0, 0, 0); } }
;     const int tok0 = 16 * wave + 4 * h, t0 = c * 128 + tok0 - 112;
; #pragma unroll
;     for (int jt = 0; jt < 4; ++jt) { const int j = 16 * jt + r, ch = kb * 64 + j;
; #pragma unroll
;         for (int dir = 0; dir < 2; ++dir) {
;             const float ba = p.in[8][(layer * 2 + dir) * W + ch], bx = p.in[10][(layer * 2 + dir) * W + ch], lam = p.in[11][(layer * 2 + dir) * W + ch];
;             const float sp = log1pf(expf(-lam));
	v_mfma_f32_16x16x32_bf16 v[4:7], v[12:15], v[4:7], 0
	s_waitcnt lgkmcnt(2)
	v_mfma_f32_16x16x32_bf16 v[8:11], v[12:15], v[8:11], 0
	s_waitcnt lgkmcnt(1)
	v_mfma_f32_16x16x32_bf16 v[94:97], v[12:15], v[44:47], 0
	ds_read_b128 v[12:15], v74 offset:18496
	s_waitcnt lgkmcnt(0)
	v_mfma_f32_16x16x32_bf16 v[60:63], v[90:93], v[12:15], v[28:31]
	ds_read_b128 v[12:15], v74 offset:20800
	s_waitcnt lgkmcnt(0)
	v_mfma_f32_16x16x32_bf16 v[44:47], v[90:93], v[12:15], v[32:35]
	ds_read_b128 v[12:15], v74 offset:23104
	s_nop 1
	ds_read_b128 v[32:35], v74 offset:25408
	s_load_dwordx4 s[48:51], s[4:5], 0x50
	s_waitcnt lgkmcnt(0)
	v_lshl_add_u64 v[68:69], s[50:51], 0, v[0:1]
	global_load_dword v76, v[68:69], off
	v_mfma_f32_16x16x32_bf16 v[28:31], v[90:93], v[12:15], v[48:51]
	s_waitcnt vmcnt(0)
	v_cmp_nlt_f32_e32 vcc, s11, v76
	v_mfma_f32_16x16x32_bf16 v[12:15], v[90:93], v[32:35], v[56:59]
	ds_read_b128 v[32:35], v74 offset:27712
	s_nop 1
	ds_read_b128 v[56:59], v74 offset:34624
	s_waitcnt lgkmcnt(1)
	v_mfma_f32_16x16x32_bf16 v[64:67], v[90:93], v[32:35], v[64:67]
	ds_read_b128 v[32:35], v74 offset:30016
	s_waitcnt lgkmcnt(1)
	v_mfma_f32_16x16x32_bf16 v[16:19], v[90:93], v[56:59], v[16:19]
	ds_read_b128 v[56:59], v74 offset:36928
	s_waitcnt lgkmcnt(1)
	v_mfma_f32_16x16x32_bf16 v[48:51], v[90:93], v[32:35], v[82:85]
	ds_read_b128 v[32:35], v74 offset:32320
	s_waitcnt lgkmcnt(1)
	v_mfma_f32_16x16x32_bf16 v[52:55], v[90:93], v[56:59], v[52:55]
	ds_read_b128 v[56:59], v74 offset:39232
	s_waitcnt lgkmcnt(0)
	v_mfma_f32_16x16x32_bf16 v[36:39], v[90:93], v[56:59], v[36:39]
	ds_read_b128 v[56:59], v74 offset:41536
	v_mfma_f32_16x16x32_bf16 v[32:35], v[90:93], v[32:35], v[86:89]
	s_waitcnt lgkmcnt(0)
	v_mfma_f32_16x16x32_bf16 v[20:23], v[90:93], v[56:59], v[20:23]
	ds_read_b128 v[56:59], v74 offset:43840
	ds_read_b128 v[82:85], v74 offset:46144
	ds_read_b128 v[86:89], v74 offset:48448
	ds_read_b128 v[98:101], v74 offset:50752
	ds_read_b128 v[102:105], v74 offset:53056
	s_load_dwordx2 s[4:5], s[4:5], 0x40
	v_lshrrev_b32_e32 v74, 4, v3
	s_waitcnt lgkmcnt(0)
	v_mfma_f32_16x16x32_bf16 v[4:7], v[90:93], v[56:59], v[4:7]
	v_mfma_f32_16x16x32_bf16 v[56:59], v[90:93], v[82:85], v[40:43]
	v_lshl_or_b32 v84, v74, 2, v70
	v_lshl_or_b32 v74, v74, 10, v71
	v_lshl_add_u64 v[70:71], s[4:5], 0, v[0:1]
	v_mfma_f32_16x16x32_bf16 v[40:43], v[90:93], v[86:89], v[24:27]
	v_add_u32_e32 v85, s8, v84
	s_add_i32 s8, s8, s9
	s_mov_b32 s9, 0xbfb8aa3b
	v_mfma_f32_16x16x32_bf16 v[24:27], v[90:93], v[98:101], v[8:11]
	v_lshl_add_u64 v[0:1], s[48:49], 0, v[0:1]
	global_load_dword v98, v[0:1], off
	s_addk_i32 s8, 0xff80
	v_mfma_f32_16x16x32_bf16 v[8:11], v[90:93], v[102:105], v[94:97]
	s_cmp_eq_u32 s30, 0
	s_cselect_b32 s8, s10, s8
	s_nop 0
	global_load_dword v96, v[68:69], off offset:2048
	v_mul_f32_e32 v68, 0xbfb8aa3b, v76
	global_load_dword v97, v[70:71], off
	v_fma_f32 v69, v76, s9, -v68
	v_rndne_f32_e32 v82, v68
	v_fmac_f32_e32 v69, 0xb2a5705f, v76
	v_sub_f32_e32 v68, v68, v82
	v_add_f32_e32 v68, v68, v69
	v_exp_f32_e32 v68, v68
	v_cvt_i32_f32_e32 v69, v82
	v_ldexp_f32 v68, v68, v69
	v_cndmask_b32_e32 v68, 0, v68, vcc
	v_cmp_ngt_f32_e32 vcc, s14, v76
	s_nop 1
	v_cndmask_b32_e32 v76, v213, v68, vcc
	v_add_f32_e32 v82, 1.0, v76
	v_add_f32_e32 v68, -1.0, v82
	v_sub_f32_e32 v69, v68, v82
	v_add_f32_e32 v69, 1.0, v69
	v_sub_f32_e32 v68, v76, v68
	v_add_f32_e32 v83, v68, v69
	v_frexp_mant_f32_e32 v86, v82
	v_cvt_f64_f32_e32 v[68:69], v82
	v_frexp_exp_i32_f64_e32 v68, v[68:69]
	v_cmp_gt_f32_e32 vcc, s12, v86
	s_nop 1
	v_subbrev_co_u32_e32 v90, vcc, 0, v68, vcc
	v_sub_u32_e32 v68, 0, v90
	v_ldexp_f32 v69, v82, v68
	v_add_f32_e32 v82, -1.0, v69
	v_add_f32_e32 v86, 1.0, v69
	v_ldexp_f32 v68, v83, v68
	v_add_f32_e32 v83, 1.0, v82
	v_add_f32_e32 v87, -1.0, v86
	v_sub_f32_e32 v83, v69, v83
	v_sub_f32_e32 v69, v69, v87
	v_add_f32_e32 v83, v68, v83
	v_add_f32_e32 v68, v68, v69
	v_add_f32_e32 v91, v86, v68
	v_rcp_f32_e32 v93, v91
	v_sub_f32_e32 v69, v86, v91
	v_add_f32_e32 v92, v68, v69
	v_add_f32_e32 v69, v82, v83
	v_mul_f32_e32 v95, v69, v93
	v_sub_f32_e32 v68, v82, v69
	v_mul_f32_e32 v82, v91, v95
	v_fma_f32 v86, v95, v91, -v82
	v_fmac_f32_e32 v86, v95, v92
	v_add_f32_e32 v94, v83, v68
	v_add_f32_e32 v68, v82, v86
	v_sub_f32_e32 v83, v69, v68
	v_pk_add_f32 v[88:89], v[68:69], v[82:83] neg_lo:[0,1] neg_hi:[0,1]
	v_mov_b32_e32 v87, v68
	v_pk_add_f32 v[68:69], v[88:89], v[86:87] neg_lo:[0,1] neg_hi:[0,1]
	v_cmp_neq_f32_e32 vcc, s92, v76
	v_add_f32_e32 v69, v94, v69
	v_add_f32_e32 v68, v68, v69
	v_add_f32_e32 v69, v83, v68
	v_mul_f32_e32 v94, v93, v69
	v_mul_f32_e32 v82, v91, v94
	v_fma_f32 v86, v94, v91, -v82
	v_fmac_f32_e32 v86, v94, v92
	v_sub_f32_e32 v83, v83, v69
	v_add_f32_e32 v91, v68, v83
	v_add_f32_e32 v68, v82, v86
	v_sub_f32_e32 v83, v69, v68
	v_pk_add_f32 v[88:89], v[68:69], v[82:83] neg_lo:[0,1] neg_hi:[0,1]
	v_mov_b32_e32 v87, v68
	v_pk_add_f32 v[68:69], v[88:89], v[86:87] neg_lo:[0,1] neg_hi:[0,1]
	s_nop 0
	v_add_f32_e32 v69, v91, v69
	v_add_f32_e32 v68, v68, v69
	v_add_f32_e32 v69, v95, v94
	v_add_f32_e32 v68, v83, v68
	v_sub_f32_e32 v82, v69, v95
	v_mul_f32_e32 v68, v93, v68
	v_sub_f32_e32 v82, v94, v82
	v_add_f32_e32 v82, v82, v68
	v_add_f32_e32 v86, v69, v82
	v_mul_f32_e32 v87, v86, v86
	v_fmamk_f32 v68, v87, 0x3e9b6dac, v211
	v_fmaak_f32 v167, v87, v68, 0x3f2aaada
	v_cvt_f32_i32_e32 v68, v90
	v_sub_f32_e32 v69, v86, v69
	v_sub_f32_e32 v69, v82, v69
	v_ldexp_f32 v88, v69, 1
	v_mul_f32_e32 v69, v86, v87
	v_ldexp_f32 v83, v86, 1
	v_pk_mul_f32 v[86:87], v[68:69], v[166:167]
	s_nop 0
	v_fma_f32 v82, v68, s84, -v86
	v_fmac_f32_e32 v82, 0xb102e308, v68
	v_pk_add_f32 v[68:69], v[86:87], v[82:83]
; __device__ __forceinline__ unsigned f2bf(float f) { return pk2(f, 0.f) & 0xffffu; }
; __device__ __forceinline__ float sigm(float x) { return __builtin_amdgcn_rcpf(1.0f + __expf(-x)); }
; #define p (*kparams())
; __device__ __forceinline__ void lru_s1_item(CParams& p, int layer, int item, LAS unsigned char* lds) {
;     ...
;     for (int jt = 0; jt < 4; ++jt) { const int j = 16 * jt + r, ch = kb * 64 + j;
; #pragma unroll
;         for (int dir = 0; dir < 2; ++dir) {
;             const float ba = p.in[8][(layer * 2 + dir) * W + ch], bx = p.in[10][(layer * 2 + dir) * W + ch], lam = p.in[11][(layer * 2 + dir) * W + ch];
;             const float sp = log1pf(expf(-lam));
;             float Aq = 1.f, Bq = 0.f;
; #pragma unroll
;             for (int s = 0; s < 4; ++s) { const int q = dir ? 3 - s : s;
;                 const float rg = sigm(acc[(2 * dir) * 4 + jt][q] + ba), ig = sigm(acc[(2 * dir + 1) * 4 + jt][q] + bx);
;                 float la = -8.0f * rg * sp; float bv = sqrtf(fmaxf(1.0f - __expf(2.0f * la), 0.f)) * ig * XCf[(tok0 + q) * 64 + j];
;                 if ((t0 + q) < 0) { la = 0.f; bv = 0.f; }
;                 const unsigned lab = f2bf(la), bvb = f2bf(bv);
;                 const size_t ro = (size_t)row_bci(b, c, tok0 + q) * W + ch;
;                 LA[(size_t)dir * MP * W + ro] = (bf16_t)lab; BB[(size_t)dir * MP * W + ro] = (bf16_t)bvb;
;                 const float a = __expf(__uint_as_float(lab << 16)), bq = __uint_as_float(bvb << 16);
;                 Bq = a * Bq + bq; Aq *= a; }
	s_nop 0
	v_sub_f32_e32 v83, v69, v83
	v_sub_f32_e32 v83, v87, v83
	v_add_f32_e32 v89, v88, v83
	v_mov_b32_e32 v88, v86
	v_pk_add_f32 v[86:87], v[68:69], v[86:87] neg_lo:[0,1] neg_hi:[0,1]
	v_pk_add_f32 v[90:91], v[68:69], v[88:89]
	v_mov_b32_e32 v83, v68
	v_mov_b32_e32 v87, v91
	v_pk_add_f32 v[92:93], v[82:83], v[86:87] neg_lo:[0,1] neg_hi:[0,1]
	v_pk_add_f32 v[82:83], v[82:83], v[86:87]
	v_mov_b32_e32 v88, v89
	v_pk_add_f32 v[86:87], v[82:83], v[68:69] op_sel:[1,0] op_sel_hi:[0,1] neg_lo:[0,1] neg_hi:[0,1]
	v_pk_add_f32 v[94:95], v[90:91], v[86:87] op_sel_hi:[1,0] neg_lo:[0,1] neg_hi:[0,1]
	v_mov_b32_e32 v90, v91
	v_mov_b32_e32 v91, v83
	v_pk_mov_b32 v[86:87], v[68:69], v[86:87] op_sel:[1,0]
	v_mov_b32_e32 v89, v68
	v_pk_add_f32 v[86:87], v[90:91], v[86:87] neg_lo:[0,1] neg_hi:[0,1]
	v_mov_b32_e32 v94, v92
	v_pk_add_f32 v[68:69], v[88:89], v[86:87] neg_lo:[0,1] neg_hi:[0,1]
	v_mov_b32_e32 v93, v83
	v_pk_add_f32 v[86:87], v[94:95], v[68:69]
	s_nop 0
	v_pk_add_f32 v[88:89], v[86:87], v[86:87] op_sel:[0,1] op_sel_hi:[1,0]
	s_nop 0
	v_pk_add_f32 v[90:91], v[82:83], v[88:89] op_sel:[1,0] op_sel_hi:[0,1]
	v_mov_b32_e32 v87, v90
	v_pk_add_f32 v[82:83], v[86:87], v[92:93] neg_lo:[0,1] neg_hi:[0,1]
	v_mov_b32_e32 v69, v88
	v_pk_add_f32 v[68:69], v[68:69], v[82:83] neg_lo:[0,1] neg_hi:[0,1]
	v_sub_f32_e32 v82, v86, v82
	v_sub_f32_e32 v83, v92, v82
	global_load_dword v82, v[70:71], off offset:2048
	s_waitcnt vmcnt(1)
	v_add_f32_e32 v60, v60, v97
	v_mul_f32_e32 v60, 0xbfb8aa3b, v60
	v_exp_f32_e32 v60, v60
	v_add_f32_e32 v68, v68, v83
	v_add_f32_e32 v68, v68, v69
	v_add_f32_e32 v68, v90, v68
	v_add_f32_e32 v60, 1.0, v60
	v_rcp_f32_e32 v60, v60
	v_cndmask_b32_e32 v68, v213, v68, vcc
	v_cmp_lt_f32_e64 vcc, |v76|, s85
	global_load_dword v83, v[0:1], off offset:2048
	v_mul_f32_e32 v60, 0xc1000000, v60
	v_cndmask_b32_e32 v76, v68, v76, vcc
	v_mul_f32_e32 v60, v60, v76
	v_add_f32_e32 v68, v60, v60
	v_mul_f32_e32 v68, 0x3fb8aa3b, v68
	v_exp_f32_e32 v68, v68
	v_add_f32_e32 v0, v64, v98
	v_mul_f32_e32 v0, 0xbfb8aa3b, v0
	v_exp_f32_e32 v0, v0
	v_sub_f32_e32 v1, 1.0, v68
	v_max_f32_e32 v1, 0, v1
	v_mul_f32_e32 v64, 0x4f800000, v1
	v_cmp_gt_f32_e32 vcc, s88, v1
	v_add_f32_e32 v0, 1.0, v0
	v_rcp_f32_e32 v0, v0
	v_cndmask_b32_e32 v1, v1, v64, vcc
	v_sqrt_f32_e32 v64, v1
	v_add_u32_e32 v71, 0, v81
	v_or_b32_e32 v88, 2, v84
	v_or_b32_e32 v89, 3, v84
	v_add_u32_e32 v68, -1, v64
	v_fma_f32 v69, -v68, v64, v1
	v_cmp_ge_f32_e64 s[40:41], 0, v69
	v_add_u32_e32 v69, 1, v64
	v_lshl_add_u32 v70, v88, 8, v71
	v_cndmask_b32_e64 v68, v64, v68, s[40:41]
	v_fma_f32 v64, -v69, v64, v1
	v_cmp_lt_f32_e64 s[40:41], 0, v64
	v_add_f32_e32 v65, v65, v98
	v_mul_f32_e32 v65, 0xbfb8aa3b, v65
	v_cndmask_b32_e64 v64, v68, v69, s[40:41]
	v_mul_f32_e32 v68, 0x37800000, v64
	v_cndmask_b32_e32 v64, v64, v68, vcc
	v_cmp_class_f32_e32 vcc, v1, v209
	v_lshl_add_u32 v68, v84, 8, v71
	v_exp_f32_e32 v65, v65
	v_cndmask_b32_e32 v1, v64, v1, vcc
	v_mul_f32_e32 v0, v0, v1
	ds_read_b32 v1, v68 offset:55296
	v_cmp_gt_i32_e32 vcc, s25, v85
	v_or_b32_e32 v64, 1, v84
	v_lshl_add_u32 v69, v64, 8, v71
	v_lshl_add_u32 v71, v89, 8, v71
	s_waitcnt lgkmcnt(0)
	v_mul_f32_e32 v0, v1, v0
	v_cndmask_b32_e64 v0, v0, 0, vcc
	v_cndmask_b32_e64 v1, v60, 0, vcc
	v_cvt_pk_bf16_f32 v94, v0, 0
	v_add_u32_e32 v0, s8, v84
	v_cvt_pk_bf16_f32 v93, v1, 0
	v_ashrrev_i32_e32 v1, 31, v0
	v_lshlrev_b64 v[0:1], 9, v[0:1]
	v_or_b32_e32 v84, v0, v80
	v_mov_b32_e32 v85, v1
	v_lshlrev_b64 v[84:85], 1, v[84:85]
	v_add_f32_e32 v60, v61, v97
	v_lshl_add_u64 v[86:87], s[52:53], 0, v[84:85]
	v_mul_f32_e32 v60, 0xbfb8aa3b, v60
	ds_read_b32 v90, v69 offset:55296
	ds_read_b32 v91, v70 offset:55296
	ds_read_b32 v92, v71 offset:55296
	global_store_short v[86:87], v93, off
	v_exp_f32_e32 v86, v60
	v_lshl_add_u64 v[60:61], s[42:43], 0, v[84:85]
	global_store_short v[60:61], v94, off
	v_lshlrev_b32_e32 v60, 16, v93
	v_add_f32_e32 v61, 1.0, v86
	v_rcp_f32_e32 v61, v61
	v_mul_f32_e32 v60, 0x3fb8aa3b, v60
	v_exp_f32_e32 v86, v60
	v_add_f32_e32 v65, 1.0, v65
	v_mul_f32_e32 v60, 0xc1000000, v61
	v_mul_f32_e32 v60, v60, v76
	v_add_f32_e32 v61, v60, v60
	v_mul_f32_e32 v61, 0x3fb8aa3b, v61
	v_exp_f32_e32 v61, v61
	v_add_f32_e32 v62, v62, v97
	v_rcp_f32_e32 v65, v65
	v_mul_f32_e32 v62, 0xbfb8aa3b, v62
	v_sub_f32_e32 v61, 1.0, v61
	v_max_f32_e32 v61, 0, v61
	v_mul_f32_e32 v84, 0x4f800000, v61
	v_cmp_gt_f32_e64 s[40:41], s88, v61
	v_exp_f32_e32 v62, v62
	v_cndmask_b32_e64 v60, v60, 0, vcc
	v_cndmask_b32_e64 v61, v61, v84, s[40:41]
	v_sqrt_f32_e32 v84, v61
	v_add_f32_e32 v62, 1.0, v62
	v_rcp_f32_e32 v62, v62
	v_lshlrev_b32_e32 v87, 16, v94
	v_add_u32_e32 v85, -1, v84
	v_fma_f32 v93, -v85, v84, v61
	v_cmp_ge_f32_e64 s[46:47], 0, v93
	v_add_u32_e32 v93, 1, v84
	v_mul_f32_e32 v62, 0xc1000000, v62
	v_cndmask_b32_e64 v85, v84, v85, s[46:47]
	v_fma_f32 v84, -v93, v84, v61
	v_cmp_lt_f32_e64 s[46:47], 0, v84
	v_mul_f32_e32 v62, v62, v76
	v_fmac_f32_e32 v87, 0, v86
	v_cndmask_b32_e64 v84, v85, v93, s[46:47]
	v_mul_f32_e32 v85, 0x37800000, v84
	v_cndmask_b32_e64 v84, v84, v85, s[40:41]
	v_cmp_class_f32_e64 s[40:41], v61, v209
	v_add_f32_e32 v63, v63, v97
	v_mul_f32_e32 v63, 0xbfb8aa3b, v63
	v_cndmask_b32_e64 v61, v84, v61, s[40:41]
	v_mul_f32_e32 v61, v65, v61
	s_waitcnt lgkmcnt(2)
; __device__ __forceinline__ unsigned f2bf(float f) { return pk2(f, 0.f) & 0xffffu; }
; __device__ __forceinline__ float sigm(float x) { return __builtin_amdgcn_rcpf(1.0f + __expf(-x)); }
; #define p (*kparams())
; __device__ __forceinline__ void lru_s1_item(CParams& p, int layer, int item, LAS unsigned char* lds) {
;     ...
;     for (int jt = 0; jt < 4; ++jt) { const int j = 16 * jt + r, ch = kb * 64 + j;
; #pragma unroll
;         for (int dir = 0; dir < 2; ++dir) {
;             const float ba = p.in[8][(layer * 2 + dir) * W + ch], bx = p.in[10][(layer * 2 + dir) * W + ch], lam = p.in[11][(layer * 2 + dir) * W + ch];
;             const float sp = log1pf(expf(-lam));
;             float Aq = 1.f, Bq = 0.f;
; #pragma unroll
;             for (int s = 0; s < 4; ++s) { const int q = dir ? 3 - s : s;
;                 const float rg = sigm(acc[(2 * dir) * 4 + jt][q] + ba), ig = sigm(acc[(2 * dir + 1) * 4 + jt][q] + bx);
;                 float la = -8.0f * rg * sp; float bv = sqrtf(fmaxf(1.0f - __expf(2.0f * la), 0.f)) * ig * XCf[(tok0 + q) * 64 + j];
;                 if ((t0 + q) < 0) { la = 0.f; bv = 0.f; }
;                 const unsigned lab = f2bf(la), bvb = f2bf(bv);
;                 const size_t ro = (size_t)row_bci(b, c, tok0 + q) * W + ch;
;                 LA[(size_t)dir * MP * W + ro] = (bf16_t)lab; BB[(size_t)dir * MP * W + ro] = (bf16_t)bvb;
;                 const float a = __expf(__uint_as_float(lab << 16)), bq = __uint_as_float(bvb << 16);
;                 Bq = a * Bq + bq; Aq *= a; }
;             const int g = 4 * wave + h;
;             AG[((g * 2 + dir) * 2 + 0) * 64 + j] = Aq; AG[((g * 2 + dir) * 2 + 1) * 64 + j] = Bq; } }
	v_mul_f32_e32 v61, v90, v61
	v_cndmask_b32_e64 v61, v61, 0, vcc
	v_cvt_pk_bf16_f32 v90, v60, 0
	v_add_u32_e32 v60, s8, v64
	v_cvt_pk_bf16_f32 v93, v61, 0
	v_ashrrev_i32_e32 v61, 31, v60
	v_lshlrev_b64 v[60:61], 9, v[60:61]
	v_or_b32_e32 v64, v60, v80
	v_mov_b32_e32 v65, v61
	v_lshlrev_b64 v[64:65], 1, v[64:65]
	v_lshl_add_u64 v[84:85], s[52:53], 0, v[64:65]
	v_lshl_add_u64 v[64:65], s[42:43], 0, v[64:65]
	global_store_short v[64:65], v93, off
	v_add_f32_e32 v64, v62, v62
	v_mul_f32_e32 v64, 0x3fb8aa3b, v64
	v_exp_f32_e32 v64, v64
	global_store_short v[84:85], v90, off
	v_lshlrev_b32_e32 v84, 16, v90
	v_add_f32_e32 v65, v66, v98
	v_sub_f32_e32 v64, 1.0, v64
	v_max_f32_e32 v64, 0, v64
	v_mul_f32_e32 v66, 0x4f800000, v64
	v_cmp_gt_f32_e64 s[40:41], s88, v64
	v_mul_f32_e32 v84, 0x3fb8aa3b, v84
	v_exp_f32_e32 v84, v84
	v_cndmask_b32_e64 v64, v64, v66, s[40:41]
	v_sqrt_f32_e32 v66, v64
	v_lshlrev_b32_e32 v90, 16, v93
	v_mul_f32_e32 v65, 0xbfb8aa3b, v65
	v_fmac_f32_e32 v90, v84, v87
	v_exp_f32_e32 v65, v65
	v_mul_f32_e32 v93, v86, v84
	v_add_u32_e32 v84, -1, v66
	v_fma_f32 v85, -v84, v66, v64
	v_cmp_ge_f32_e64 s[46:47], 0, v85
	v_add_u32_e32 v85, 1, v66
	v_add_f32_e32 v65, 1.0, v65
	v_cndmask_b32_e64 v84, v66, v84, s[46:47]
	v_fma_f32 v66, -v85, v66, v64
	v_cmp_lt_f32_e64 s[46:47], 0, v66
	v_rcp_f32_e32 v65, v65
	v_exp_f32_e32 v63, v63
	v_cndmask_b32_e64 v66, v84, v85, s[46:47]
	v_mul_f32_e32 v84, 0x37800000, v66
	v_cndmask_b32_e64 v66, v66, v84, s[40:41]
	v_cmp_class_f32_e64 s[40:41], v64, v209
	v_add_f32_e32 v63, 1.0, v63
	v_rcp_f32_e32 v63, v63
	v_cndmask_b32_e64 v64, v66, v64, s[40:41]
	v_mul_f32_e32 v64, v65, v64
	s_waitcnt lgkmcnt(1)
	v_mul_f32_e32 v64, v91, v64
	v_cndmask_b32_e64 v64, v64, 0, vcc
	v_cvt_pk_bf16_f32 v66, v64, 0
	v_add_u32_e32 v64, s8, v88
	v_ashrrev_i32_e32 v65, 31, v64
	v_lshlrev_b64 v[64:65], 9, v[64:65]
	v_or_b32_e32 v84, v64, v80
	v_mov_b32_e32 v85, v65
	v_cndmask_b32_e64 v62, v62, 0, vcc
	v_lshlrev_b64 v[84:85], 1, v[84:85]
	v_mul_f32_e32 v63, 0xc1000000, v63
	v_cvt_pk_bf16_f32 v62, v62, 0
	v_lshl_add_u64 v[86:87], s[52:53], 0, v[84:85]
	v_lshl_add_u64 v[84:85], s[42:43], 0, v[84:85]
	v_mul_f32_e32 v63, v63, v76
	global_store_short v[86:87], v62, off
	global_store_short v[84:85], v66, off
	v_lshlrev_b32_e32 v86, 16, v66
	v_add_f32_e32 v66, v63, v63
	v_mul_f32_e32 v66, 0x3fb8aa3b, v66
	v_exp_f32_e32 v66, v66
	v_lshlrev_b32_e32 v62, 16, v62
	v_add_f32_e32 v67, v67, v98
	v_mul_f32_e32 v62, 0x3fb8aa3b, v62
	v_sub_f32_e32 v66, 1.0, v66
	v_max_f32_e32 v66, 0, v66
	v_mul_f32_e32 v76, 0x4f800000, v66
	v_cmp_gt_f32_e64 s[40:41], s88, v66
	v_mul_f32_e32 v67, 0xbfb8aa3b, v67
	v_exp_f32_e32 v62, v62
	v_cndmask_b32_e64 v66, v66, v76, s[40:41]
	v_exp_f32_e32 v67, v67
	v_sqrt_f32_e32 v76, v66
	v_fmac_f32_e32 v86, v62, v90
	v_mul_f32_e32 v87, v62, v93
	v_add_f32_e32 v62, 1.0, v67
	v_add_u32_e32 v67, -1, v76
	v_fma_f32 v84, -v67, v76, v66
	v_cmp_ge_f32_e64 s[46:47], 0, v84
	v_add_u32_e32 v84, 1, v76
	v_rcp_f32_e32 v62, v62
	v_cndmask_b32_e64 v67, v76, v67, s[46:47]
	v_fma_f32 v76, -v84, v76, v66
	v_cmp_lt_f32_e64 s[46:47], 0, v76
	v_cndmask_b32_e64 v63, v63, 0, vcc
	s_waitcnt vmcnt(7)
	v_add_f32_e32 v55, v55, v82
	v_cndmask_b32_e64 v67, v67, v84, s[46:47]
	v_mul_f32_e32 v76, 0x37800000, v67
	v_cndmask_b32_e64 v67, v67, v76, s[40:41]
	v_cmp_class_f32_e64 s[40:41], v66, v209
	v_cvt_pk_bf16_f32 v76, v63, 0
	v_mul_f32_e32 v55, 0xbfb8aa3b, v55
	v_cndmask_b32_e64 v66, v67, v66, s[40:41]
	v_mul_f32_e32 v62, v62, v66
	s_waitcnt lgkmcnt(0)
	v_mul_f32_e32 v62, v92, v62
	v_cndmask_b32_e64 v62, v62, 0, vcc
	v_cvt_pk_bf16_f32 v88, v62, 0
	v_add_u32_e32 v62, s8, v89
	v_ashrrev_i32_e32 v63, 31, v62
	v_lshlrev_b64 v[62:63], 9, v[62:63]
	v_or_b32_e32 v66, v62, v80
	v_mov_b32_e32 v67, v63
	v_lshlrev_b64 v[66:67], 1, v[66:67]
	v_lshl_add_u64 v[84:85], s[52:53], 0, v[66:67]
	global_store_short v[84:85], v76, off
	v_lshlrev_b32_e32 v76, 16, v76
	v_mul_f32_e32 v76, 0x3fb8aa3b, v76
	v_exp_f32_e32 v76, v76
	v_lshl_add_u64 v[66:67], s[42:43], 0, v[66:67]
	global_store_short v[66:67], v88, off
	v_lshlrev_b32_e32 v66, 16, v88
	v_fmac_f32_e32 v66, v76, v86
	v_mul_f32_e32 v67, v76, v87
	v_mul_f32_e32 v76, 0xbfb8aa3b, v96
	v_fma_f32 v84, v96, s9, -v76
	v_rndne_f32_e32 v85, v76
	v_fmac_f32_e32 v84, 0xb2a5705f, v96
	v_sub_f32_e32 v76, v76, v85
	v_add_f32_e32 v76, v76, v84
	v_exp_f32_e32 v84, v76
	v_cvt_i32_f32_e32 v85, v85
	v_add_u32_e32 v76, s90, v74
	v_add_u32_e32 v81, v76, v81
	ds_write2st64_b32 v81, v67, v66 offset1:1
	v_ldexp_f32 v66, v84, v85
	v_cmp_nlt_f32_e64 s[40:41], s11, v96
	v_exp_f32_e32 v55, v55
	s_waitcnt vmcnt(8)
; __device__ __forceinline__ unsigned f2bf(float f) { return pk2(f, 0.f) & 0xffffu; }
; __device__ __forceinline__ float sigm(float x) { return __builtin_amdgcn_rcpf(1.0f + __expf(-x)); }
; #define p (*kparams())
; __device__ __forceinline__ void lru_s1_item(CParams& p, int layer, int item, LAS unsigned char* lds) {
;     ...
;             const float ba = p.in[8][(layer * 2 + dir) * W + ch], bx = p.in[10][(layer * 2 + dir) * W + ch], lam = p.in[11][(layer * 2 + dir) * W + ch];
;             const float sp = log1pf(expf(-lam));
;             float Aq = 1.f, Bq = 0.f;
; #pragma unroll
;             for (int s = 0; s < 4; ++s) { const int q = dir ? 3 - s : s;
;                 const float rg = sigm(acc[(2 * dir) * 4 + jt][q] + ba), ig = sigm(acc[(2 * dir + 1) * 4 + jt][q] + bx);
;                 float la = -8.0f * rg * sp; float bv = sqrtf(fmaxf(1.0f - __expf(2.0f * la), 0.f)) * ig * XCf[(tok0 + q) * 64 + j];
;                 if ((t0 + q) < 0) { la = 0.f; bv = 0.f; }
;                 const unsigned lab = f2bf(la), bvb = f2bf(bv);
;                 const size_t ro = (size_t)row_bci(b, c, tok0 + q) * W + ch;
;                 LA[(size_t)dir * MP * W + ro] = (bf16_t)lab; BB[(size_t)dir * MP * W + ro] = (bf16_t)bvb;
;                 const float a = __expf(__uint_as_float(lab << 16)), bq = __uint_as_float(bvb << 16);
;                 Bq = a * Bq + bq; Aq *= a; }
	v_add_f32_e32 v59, v59, v83
	v_cndmask_b32_e64 v66, 0, v66, s[40:41]
	v_cmp_ngt_f32_e64 s[40:41], s14, v96
	v_add_f32_e32 v55, 1.0, v55
	v_rcp_f32_e32 v55, v55
	v_cndmask_b32_e64 v96, v213, v66, s[40:41]
	v_add_f32_e32 v84, 1.0, v96
	v_add_f32_e32 v66, -1.0, v84
	v_sub_f32_e32 v67, v66, v84
	v_add_f32_e32 v67, 1.0, v67
	v_sub_f32_e32 v66, v96, v66
	v_add_f32_e32 v85, v66, v67
	v_frexp_mant_f32_e32 v86, v84
	v_cvt_f64_f32_e32 v[66:67], v84
	v_frexp_exp_i32_f64_e32 v66, v[66:67]
	v_cmp_gt_f32_e64 s[40:41], s12, v86
	v_mul_f32_e32 v55, 0xc1000000, v55
	v_mul_f32_e32 v59, 0xbfb8aa3b, v59
	v_subbrev_co_u32_e64 v90, s[40:41], 0, v66, s[40:41]
	v_sub_u32_e32 v66, 0, v90
	v_ldexp_f32 v67, v84, v66
	v_add_f32_e32 v84, -1.0, v67
	v_add_f32_e32 v86, 1.0, v67
	v_ldexp_f32 v66, v85, v66
	v_add_f32_e32 v85, 1.0, v84
	v_add_f32_e32 v87, -1.0, v86
	v_sub_f32_e32 v85, v67, v85
	v_sub_f32_e32 v67, v67, v87
	v_add_f32_e32 v85, v66, v85
	v_add_f32_e32 v66, v66, v67
	v_add_f32_e32 v91, v86, v66
	v_rcp_f32_e32 v93, v91
	v_sub_f32_e32 v67, v86, v91
	v_add_f32_e32 v92, v66, v67
	v_add_f32_e32 v67, v84, v85
	v_mul_f32_e32 v95, v67, v93
	v_sub_f32_e32 v66, v84, v67
	v_mul_f32_e32 v84, v91, v95
	v_fma_f32 v86, v95, v91, -v84
	v_fmac_f32_e32 v86, v95, v92
	v_add_f32_e32 v94, v85, v66
	v_add_f32_e32 v66, v84, v86
	v_sub_f32_e32 v85, v67, v66
	v_pk_add_f32 v[88:89], v[66:67], v[84:85] neg_lo:[0,1] neg_hi:[0,1]
	v_mov_b32_e32 v87, v66
	v_pk_add_f32 v[66:67], v[88:89], v[86:87] neg_lo:[0,1] neg_hi:[0,1]
	v_cmp_neq_f32_e64 s[40:41], s92, v96
	v_add_f32_e32 v67, v94, v67
	v_add_f32_e32 v66, v66, v67
	v_add_f32_e32 v67, v85, v66
	v_mul_f32_e32 v94, v93, v67
	v_mul_f32_e32 v84, v91, v94
	v_fma_f32 v86, v94, v91, -v84
	v_fmac_f32_e32 v86, v94, v92
	v_sub_f32_e32 v85, v85, v67
	v_add_f32_e32 v91, v66, v85
	v_add_f32_e32 v66, v84, v86
	v_sub_f32_e32 v85, v67, v66
	v_pk_add_f32 v[88:89], v[66:67], v[84:85] neg_lo:[0,1] neg_hi:[0,1]
	v_mov_b32_e32 v87, v66
	v_pk_add_f32 v[66:67], v[88:89], v[86:87] neg_lo:[0,1] neg_hi:[0,1]
	v_exp_f32_e32 v59, v59
	v_add_f32_e32 v67, v91, v67
	v_add_f32_e32 v66, v66, v67
	v_add_f32_e32 v67, v95, v94
	v_add_f32_e32 v66, v85, v66
	v_sub_f32_e32 v84, v67, v95
	v_mul_f32_e32 v66, v93, v66
	v_sub_f32_e32 v84, v94, v84
	v_add_f32_e32 v84, v84, v66
	v_add_f32_e32 v86, v67, v84
	v_mul_f32_e32 v87, v86, v86
	v_fmamk_f32 v66, v87, 0x3e9b6dac, v211
	v_fmaak_f32 v167, v87, v66, 0x3f2aaada
	v_cvt_f32_i32_e32 v66, v90
	v_sub_f32_e32 v67, v86, v67
	v_sub_f32_e32 v67, v84, v67
	v_ldexp_f32 v88, v67, 1
	v_mul_f32_e32 v67, v86, v87
	v_ldexp_f32 v85, v86, 1
	v_pk_mul_f32 v[86:87], v[66:67], v[166:167]
	v_add_f32_e32 v59, 1.0, v59
	v_fma_f32 v84, v66, s84, -v86
	v_fmac_f32_e32 v84, 0xb102e308, v66
	v_pk_add_f32 v[66:67], v[86:87], v[84:85]
	v_rcp_f32_e32 v59, v59
	v_sub_f32_e32 v85, v67, v85
	v_sub_f32_e32 v85, v87, v85
	v_add_f32_e32 v89, v88, v85
	v_mov_b32_e32 v88, v86
	v_pk_add_f32 v[86:87], v[66:67], v[86:87] neg_lo:[0,1] neg_hi:[0,1]
	v_pk_add_f32 v[90:91], v[66:67], v[88:89]
	v_mov_b32_e32 v85, v66
	v_mov_b32_e32 v87, v91
	v_pk_add_f32 v[92:93], v[84:85], v[86:87] neg_lo:[0,1] neg_hi:[0,1]
	v_pk_add_f32 v[84:85], v[84:85], v[86:87]
	v_mov_b32_e32 v88, v89
	v_pk_add_f32 v[86:87], v[84:85], v[66:67] op_sel:[1,0] op_sel_hi:[0,1] neg_lo:[0,1] neg_hi:[0,1]
	v_pk_add_f32 v[94:95], v[90:91], v[86:87] op_sel_hi:[1,0] neg_lo:[0,1] neg_hi:[0,1]
	v_mov_b32_e32 v90, v91
	v_mov_b32_e32 v91, v85
	v_pk_mov_b32 v[86:87], v[66:67], v[86:87] op_sel:[1,0]
	v_mov_b32_e32 v89, v66
	v_pk_add_f32 v[86:87], v[90:91], v[86:87] neg_lo:[0,1] neg_hi:[0,1]
	v_mov_b32_e32 v94, v92
	v_pk_add_f32 v[66:67], v[88:89], v[86:87] neg_lo:[0,1] neg_hi:[0,1]
	v_mov_b32_e32 v93, v85
	v_pk_add_f32 v[86:87], v[94:95], v[66:67]
	v_add_f32_e32 v54, v54, v82
	v_pk_add_f32 v[88:89], v[86:87], v[86:87] op_sel:[0,1] op_sel_hi:[1,0]
	v_mul_f32_e32 v54, 0xbfb8aa3b, v54
	v_pk_add_f32 v[84:85], v[84:85], v[88:89] op_sel:[1,0] op_sel_hi:[0,1]
	v_mov_b32_e32 v87, v84
	v_pk_add_f32 v[90:91], v[86:87], v[92:93] neg_lo:[0,1] neg_hi:[0,1]
	v_mov_b32_e32 v67, v88
	v_sub_f32_e32 v85, v86, v90
	v_pk_add_f32 v[66:67], v[66:67], v[90:91] neg_lo:[0,1] neg_hi:[0,1]
	v_sub_f32_e32 v85, v92, v85
	v_add_f32_e32 v66, v66, v85
	v_add_f32_e32 v66, v66, v67
	v_add_f32_e32 v66, v84, v66
	v_cndmask_b32_e64 v66, v213, v66, s[40:41]
	v_cmp_lt_f32_e64 s[40:41], |v96|, s85
	v_add_f32_e32 v58, v58, v83
	v_mul_f32_e32 v58, 0xbfb8aa3b, v58
	v_cndmask_b32_e64 v88, v66, v96, s[40:41]
	v_mul_f32_e32 v55, v55, v88
	v_add_f32_e32 v67, v55, v55
	v_mul_f32_e32 v67, 0x3fb8aa3b, v67
	v_exp_f32_e32 v67, v67
	v_or_b32_e32 v66, 0x820000, v80
	v_cndmask_b32_e64 v55, v55, 0, vcc
	v_cvt_pk_bf16_f32 v89, v55, 0
	v_sub_f32_e32 v67, 1.0, v67
	v_max_f32_e32 v67, 0, v67
	v_mul_f32_e32 v80, 0x4f800000, v67
	v_cmp_gt_f32_e64 s[40:41], s88, v67
	v_exp_f32_e32 v58, v58
	v_add_f32_e32 v53, v53, v82
	v_cndmask_b32_e64 v80, v67, v80, s[40:41]
	v_sqrt_f32_e32 v84, v80
	v_mov_b32_e32 v67, v2
	v_mul_f32_e32 v53, 0xbfb8aa3b, v53
	v_add_f32_e32 v58, 1.0, v58
	v_add_u32_e32 v85, -1, v84
	v_fma_f32 v86, -v85, v84, v80
	v_cmp_ge_f32_e64 s[46:47], 0, v86
	v_add_u32_e32 v86, 1, v84
	v_exp_f32_e32 v53, v53
	v_cndmask_b32_e64 v85, v84, v85, s[46:47]
	v_fma_f32 v84, -v86, v84, v80
	v_cmp_lt_f32_e64 s[46:47], 0, v84
	v_rcp_f32_e32 v58, v58
	v_add_f32_e32 v53, 1.0, v53
	v_cndmask_b32_e64 v84, v85, v86, s[46:47]
	v_mul_f32_e32 v85, 0x37800000, v84
	v_cndmask_b32_e64 v84, v84, v85, s[40:41]
	ds_read_b32 v85, v71 offset:55296
	ds_read_b32 v90, v68 offset:55296
	v_cmp_class_f32_e64 s[40:41], v80, v209
	v_rcp_f32_e32 v53, v53
	s_add_i32 s8, s56, s29
	v_cndmask_b32_e64 v80, v84, v80, s[40:41]
	v_mul_f32_e32 v59, v59, v80
	ds_read_b32 v80, v70 offset:55296
	s_waitcnt lgkmcnt(2)
; __device__ __forceinline__ unsigned f2bf(float f) { return pk2(f, 0.f) & 0xffffu; }
; __device__ __forceinline__ float sigm(float x) { return __builtin_amdgcn_rcpf(1.0f + __expf(-x)); }
; __device__ __forceinline__ void lru_s1_item(CParams& p, int layer, int item, LAS unsigned char* lds) {
;     ...
;             for (int s = 0; s < 4; ++s) { const int q = dir ? 3 - s : s;
;                 const float rg = sigm(acc[(2 * dir) * 4 + jt][q] + ba), ig = sigm(acc[(2 * dir + 1) * 4 + jt][q] + bx);
;                 float la = -8.0f * rg * sp; float bv = sqrtf(fmaxf(1.0f - __expf(2.0f * la), 0.f)) * ig * XCf[(tok0 + q) * 64 + j];
;                 if ((t0 + q) < 0) { la = 0.f; bv = 0.f; }
;                 const unsigned lab = f2bf(la), bvb = f2bf(bv);
;                 const size_t ro = (size_t)row_bci(b, c, tok0 + q) * W + ch;
;                 LA[(size_t)dir * MP * W + ro] = (bf16_t)lab; BB[(size_t)dir * MP * W + ro] = (bf16_t)bvb;
;                 const float a = __expf(__uint_as_float(lab << 16)), bq = __uint_as_float(bvb << 16);
;                 Bq = a * Bq + bq; Aq *= a; }
;             const int g = 4 * wave + h;
;             AG[((g * 2 + dir) * 2 + 0) * 64 + j] = Aq; AG[((g * 2 + dir) * 2 + 1) * 64 + j] = Bq; } }
	v_mul_f32_e32 v59, v85, v59
	v_lshl_add_u64 v[84:85], v[62:63], 0, v[66:67]
	v_lshlrev_b64 v[84:85], 1, v[84:85]
	v_lshl_add_u64 v[86:87], s[52:53], 0, v[84:85]
	global_store_short v[86:87], v89, off
	v_exp_f32_e32 v86, v54
	v_cndmask_b32_e64 v59, v59, 0, vcc
	v_cvt_pk_bf16_f32 v59, v59, 0
	v_lshl_add_u64 v[54:55], s[42:43], 0, v[84:85]
	global_store_short v[54:55], v59, off
	v_add_f32_e32 v55, 1.0, v86
	v_rcp_f32_e32 v55, v55
	v_lshlrev_b32_e32 v54, 16, v89
	v_mul_f32_e32 v54, 0x3fb8aa3b, v54
	v_exp_f32_e32 v84, v54
	v_mul_f32_e32 v54, 0xc1000000, v55
	v_mul_f32_e32 v54, v54, v88
	v_add_f32_e32 v55, v54, v54
	v_mul_f32_e32 v55, 0x3fb8aa3b, v55
	v_exp_f32_e32 v55, v55
	v_lshlrev_b32_e32 v85, 16, v59
	v_cndmask_b32_e64 v54, v54, 0, vcc
	v_mul_f32_e32 v53, 0xc1000000, v53
	v_sub_f32_e32 v55, 1.0, v55
	v_max_f32_e32 v55, 0, v55
	v_mul_f32_e32 v59, 0x4f800000, v55
	v_cmp_gt_f32_e64 s[40:41], s88, v55
	v_mul_f32_e32 v53, v53, v88
	v_fmac_f32_e32 v85, 0, v84
	v_cndmask_b32_e64 v55, v55, v59, s[40:41]
	v_sqrt_f32_e32 v59, v55
	v_add_f32_e32 v52, v52, v82
	v_mul_f32_e32 v52, 0xbfb8aa3b, v52
	v_exp_f32_e32 v52, v52
	v_add_u32_e32 v86, -1, v59
	v_fma_f32 v87, -v86, v59, v55
	v_cmp_ge_f32_e64 s[46:47], 0, v87
	v_add_u32_e32 v87, 1, v59
	v_add_f32_e32 v52, 1.0, v52
	v_cndmask_b32_e64 v86, v59, v86, s[46:47]
	v_fma_f32 v59, -v87, v59, v55
	v_cmp_lt_f32_e64 s[46:47], 0, v59
	v_rcp_f32_e32 v52, v52
	v_add_f32_e32 v56, v56, v83
	v_cndmask_b32_e64 v59, v86, v87, s[46:47]
	v_mul_f32_e32 v86, 0x37800000, v59
	v_cndmask_b32_e64 v59, v59, v86, s[40:41]
	v_cmp_class_f32_e64 s[40:41], v55, v209
	ds_read_b32 v86, v69 offset:55296
	v_mul_f32_e32 v52, 0xc1000000, v52
	v_cndmask_b32_e64 v55, v59, v55, s[40:41]
	v_mul_f32_e32 v55, v58, v55
	s_waitcnt lgkmcnt(1)
	v_mul_f32_e32 v55, v80, v55
	v_cndmask_b32_e64 v55, v55, 0, vcc
	v_cvt_pk_bf16_f32 v80, v54, 0
	v_cvt_pk_bf16_f32 v87, v55, 0
	v_lshl_add_u64 v[54:55], v[64:65], 0, v[66:67]
	v_lshlrev_b64 v[54:55], 1, v[54:55]
	v_lshl_add_u64 v[58:59], s[52:53], 0, v[54:55]
	v_lshl_add_u64 v[54:55], s[42:43], 0, v[54:55]
	global_store_short v[54:55], v87, off
	v_add_f32_e32 v54, v53, v53
	v_mul_f32_e32 v54, 0x3fb8aa3b, v54
	v_exp_f32_e32 v54, v54
	global_store_short v[58:59], v80, off
	v_lshlrev_b32_e32 v58, 16, v80
	v_mul_f32_e32 v58, 0x3fb8aa3b, v58
	v_exp_f32_e32 v58, v58
	v_sub_f32_e32 v54, 1.0, v54
	v_add_f32_e32 v55, v57, v83
	v_max_f32_e32 v54, 0, v54
	v_lshlrev_b32_e32 v80, 16, v87
	v_mul_f32_e32 v55, 0xbfb8aa3b, v55
	v_mul_f32_e32 v57, 0x4f800000, v54
	v_cmp_gt_f32_e64 s[40:41], s88, v54
	v_fmac_f32_e32 v80, v58, v85
	v_exp_f32_e32 v55, v55
	v_cndmask_b32_e64 v85, v54, v57, s[40:41]
	v_sqrt_f32_e32 v54, v85
	v_mul_f32_e32 v89, v84, v58
	v_add_f32_e32 v55, 1.0, v55
	v_rcp_f32_e32 v84, v55
	v_add_u32_e32 v55, -1, v54
	v_fma_f32 v57, -v55, v54, v85
	v_cmp_ge_f32_e64 s[46:47], 0, v57
	v_add_u32_e32 v57, 1, v54
	v_cndmask_b32_e64 v53, v53, 0, vcc
	v_cndmask_b32_e64 v55, v54, v55, s[46:47]
	v_fma_f32 v54, -v57, v54, v85
	v_cmp_lt_f32_e64 s[46:47], 0, v54
	v_cvt_pk_bf16_f32 v53, v53, 0
	v_mul_f32_e32 v52, v52, v88
	v_cndmask_b32_e64 v54, v55, v57, s[46:47]
	v_mul_f32_e32 v55, 0x37800000, v54
	v_cndmask_b32_e64 v87, v54, v55, s[40:41]
	v_add_u32_e32 v54, s8, v79
	v_mov_b32_e32 v55, v2
	v_lshlrev_b64 v[54:55], 2, v[54:55]
	v_lshl_add_u64 v[58:59], s[50:51], 0, v[54:55]
	global_load_dword v57, v[58:59], off offset:64
	v_cmp_class_f32_e64 s[40:41], v85, v209
	v_mul_f32_e32 v56, 0xbfb8aa3b, v56
	v_exp_f32_e32 v56, v56
	v_cndmask_b32_e64 v79, v87, v85, s[40:41]
	v_mul_f32_e32 v79, v84, v79
	v_lshl_add_u64 v[84:85], v[60:61], 0, v[66:67]
	v_lshlrev_b64 v[84:85], 1, v[84:85]
	s_waitcnt lgkmcnt(0)
	v_mul_f32_e32 v79, v86, v79
	v_lshl_add_u64 v[86:87], s[52:53], 0, v[84:85]
	global_store_short v[86:87], v53, off
	v_lshlrev_b32_e32 v53, 16, v53
	v_mul_f32_e32 v53, 0x3fb8aa3b, v53
	v_exp_f32_e32 v53, v53
	v_cndmask_b32_e64 v79, v79, 0, vcc
	v_cvt_pk_bf16_f32 v79, v79, 0
	v_lshl_add_u64 v[84:85], s[42:43], 0, v[84:85]
	global_store_short v[84:85], v79, off
	v_lshlrev_b32_e32 v79, 16, v79
	v_fmac_f32_e32 v79, v53, v80
	v_add_f32_e32 v80, v52, v52
	v_mul_f32_e32 v80, 0x3fb8aa3b, v80
	v_exp_f32_e32 v80, v80
	v_mul_f32_e32 v83, v53, v89
	v_add_f32_e32 v53, 1.0, v56
	v_rcp_f32_e32 v53, v53
	v_sub_f32_e32 v80, 1.0, v80
	v_max_f32_e32 v80, 0, v80
	v_mul_f32_e32 v82, 0x4f800000, v80
	v_cmp_gt_f32_e64 s[40:41], s88, v80
	v_cndmask_b32_e64 v52, v52, 0, vcc
	s_nop 0
	v_cndmask_b32_e64 v80, v80, v82, s[40:41]
	v_sqrt_f32_e32 v82, v80
	s_nop 0
	v_add_u32_e32 v56, -1, v82
	v_fma_f32 v84, -v56, v82, v80
	v_cmp_ge_f32_e64 s[46:47], 0, v84
	v_add_u32_e32 v84, 1, v82
	s_nop 0
	v_cndmask_b32_e64 v56, v82, v56, s[46:47]
	v_fma_f32 v82, -v84, v82, v80
	v_cmp_lt_f32_e64 s[46:47], 0, v82
	s_nop 1
	v_cndmask_b32_e64 v56, v56, v84, s[46:47]
	v_mul_f32_e32 v82, 0x37800000, v56
	v_cndmask_b32_e64 v56, v56, v82, s[40:41]
	v_cmp_class_f32_e64 s[40:41], v80, v209
	s_nop 1
	v_cndmask_b32_e64 v56, v56, v80, s[40:41]
	v_mul_f32_e32 v53, v53, v56
	v_mul_f32_e32 v53, v90, v53
	v_cndmask_b32_e64 v53, v53, 0, vcc
	v_cvt_pk_bf16_f32 v56, v52, 0
	v_cvt_pk_bf16_f32 v80, v53, 0
	v_lshl_add_u64 v[52:53], v[0:1], 0, v[66:67]
	v_lshlrev_b64 v[52:53], 1, v[52:53]
	v_lshl_add_u64 v[66:67], s[52:53], 0, v[52:53]
	global_store_short v[66:67], v56, off
	v_lshlrev_b32_e32 v56, 16, v56
	v_mul_f32_e32 v56, 0x3fb8aa3b, v56
	v_exp_f32_e32 v56, v56
	v_lshl_add_u64 v[52:53], s[42:43], 0, v[52:53]
	global_store_short v[52:53], v80, off
	v_lshlrev_b32_e32 v52, 16, v80
	v_fmac_f32_e32 v52, v56, v79
	v_mul_f32_e32 v53, v56, v83
	ds_write2st64_b32 v81, v53, v52 offset0:2 offset1:3
	v_lshl_add_u64 v[52:53], s[4:5], 0, v[54:55]
	global_load_dword v66, v[58:59], off offset:2112
	global_load_dword v67, v[58:59], off offset:128
	global_load_dword v79, v[58:59], off offset:2176
	global_load_dword v80, v[58:59], off offset:2240
	s_nop 0
	global_load_dword v58, v[58:59], off offset:192
	v_or_b32_e32 v56, s29, v78
	global_load_dword v96, v[52:53], off offset:64
	s_movk_i32 s4, 0x80
	s_waitcnt vmcnt(10)
; __device__ __forceinline__ float sigm(float x) { return __builtin_amdgcn_rcpf(1.0f + __expf(-x)); }
; #define p (*kparams())
; __device__ __forceinline__ void lru_s1_item(CParams& p, int layer, int item, LAS unsigned char* lds) {
;     ...
;             const float ba = p.in[8][(layer * 2 + dir) * W + ch], bx = p.in[10][(layer * 2 + dir) * W + ch], lam = p.in[11][(layer * 2 + dir) * W + ch];
;             const float sp = log1pf(expf(-lam));
;             float Aq = 1.f, Bq = 0.f;
; #pragma unroll
;             for (int s = 0; s < 4; ++s) { const int q = dir ? 3 - s : s;
;                 const float rg = sigm(acc[(2 * dir) * 4 + jt][q] + ba), ig = sigm(acc[(2 * dir + 1) * 4 + jt][q] + bx);
;                 float la = -8.0f * rg * sp; float bv = sqrtf(fmaxf(1.0f - __expf(2.0f * la), 0.f)) * ig * XCf[(tok0 + q) * 64 + j];
	v_mul_f32_e32 v59, 0xbfb8aa3b, v57
	v_fma_f32 v81, v57, s9, -v59
	v_rndne_f32_e32 v82, v59
	v_fmac_f32_e32 v81, 0xb2a5705f, v57
	v_sub_f32_e32 v59, v59, v82
	v_add_f32_e32 v59, v59, v81
	v_exp_f32_e32 v59, v59
	v_cvt_i32_f32_e32 v81, v82
	v_lshl_add_u64 v[82:83], s[48:49], 0, v[54:55]
	v_cmp_nlt_f32_e64 s[40:41], s11, v57
	global_load_dword v97, v[82:83], off offset:64
	v_ldexp_f32 v54, v59, v81
	v_cndmask_b32_e64 v54, 0, v54, s[40:41]
	v_cmp_ngt_f32_e64 s[40:41], s14, v57
	s_waitcnt vmcnt(1)
	v_add_f32_e32 v44, v44, v96
	v_cndmask_b32_e64 v57, v213, v54, s[40:41]
	v_add_f32_e32 v59, 1.0, v57
	v_add_f32_e32 v54, -1.0, v59
	v_sub_f32_e32 v55, v54, v59
	v_add_f32_e32 v55, 1.0, v55
	v_sub_f32_e32 v54, v57, v54
	v_add_f32_e32 v81, v54, v55
	v_frexp_mant_f32_e32 v84, v59
	v_cvt_f64_f32_e32 v[54:55], v59
	v_frexp_exp_i32_f64_e32 v54, v[54:55]
	v_cmp_gt_f32_e64 s[40:41], s12, v84
	v_mul_f32_e32 v44, 0xbfb8aa3b, v44
	v_exp_f32_e32 v44, v44
	v_subbrev_co_u32_e64 v90, s[40:41], 0, v54, s[40:41]
	v_sub_u32_e32 v54, 0, v90
	v_ldexp_f32 v55, v59, v54
	v_add_f32_e32 v59, -1.0, v55
	v_add_f32_e32 v84, 1.0, v55
	v_ldexp_f32 v54, v81, v54
	v_add_f32_e32 v81, 1.0, v59
	v_add_f32_e32 v85, -1.0, v84
	v_sub_f32_e32 v81, v55, v81
	v_sub_f32_e32 v55, v55, v85
	v_add_f32_e32 v81, v54, v81
	v_add_f32_e32 v54, v54, v55
	v_add_f32_e32 v91, v84, v54
	v_rcp_f32_e32 v93, v91
	v_sub_f32_e32 v55, v84, v91
	v_add_f32_e32 v92, v54, v55
	v_add_f32_e32 v55, v59, v81
	v_sub_f32_e32 v54, v59, v55
	v_add_f32_e32 v59, v81, v54
	v_mul_f32_e32 v81, v55, v93
	v_mul_f32_e32 v84, v91, v81
	v_fma_f32 v86, v81, v91, -v84
	v_fmac_f32_e32 v86, v81, v92
	v_add_f32_e32 v54, v84, v86
	v_sub_f32_e32 v85, v55, v54
	v_pk_add_f32 v[88:89], v[54:55], v[84:85] neg_lo:[0,1] neg_hi:[0,1]
	v_mov_b32_e32 v87, v54
	v_pk_add_f32 v[54:55], v[88:89], v[86:87] neg_lo:[0,1] neg_hi:[0,1]
	v_add_f32_e32 v44, 1.0, v44
	v_add_f32_e32 v55, v59, v55
	v_add_f32_e32 v54, v54, v55
	v_add_f32_e32 v55, v85, v54
	v_mul_f32_e32 v59, v93, v55
	v_mul_f32_e32 v84, v91, v59
	v_fma_f32 v86, v59, v91, -v84
	v_fmac_f32_e32 v86, v59, v92
	v_sub_f32_e32 v85, v85, v55
	v_add_f32_e32 v91, v54, v85
	v_add_f32_e32 v54, v84, v86
	v_sub_f32_e32 v85, v55, v54
	v_pk_add_f32 v[88:89], v[54:55], v[84:85] neg_lo:[0,1] neg_hi:[0,1]
	v_mov_b32_e32 v87, v54
	v_pk_add_f32 v[54:55], v[88:89], v[86:87] neg_lo:[0,1] neg_hi:[0,1]
	v_rcp_f32_e32 v44, v44
	v_add_f32_e32 v55, v91, v55
	v_add_f32_e32 v54, v54, v55
	v_add_f32_e32 v55, v81, v59
	v_add_f32_e32 v54, v85, v54
	v_sub_f32_e32 v81, v55, v81
	v_mul_f32_e32 v54, v93, v54
	v_sub_f32_e32 v59, v59, v81
	v_add_f32_e32 v59, v59, v54
	v_add_f32_e32 v81, v55, v59
	v_mul_f32_e32 v84, v81, v81
	v_fmamk_f32 v54, v84, 0x3e9b6dac, v211
	v_fmaak_f32 v167, v84, v54, 0x3f2aaada
	v_cvt_f32_i32_e32 v54, v90
	v_sub_f32_e32 v55, v81, v55
	v_sub_f32_e32 v55, v59, v55
	v_ldexp_f32 v59, v55, 1
	v_mul_f32_e32 v55, v81, v84
	v_pk_mul_f32 v[86:87], v[54:55], v[166:167]
	v_ldexp_f32 v85, v81, 1
	v_fma_f32 v84, v54, s84, -v86
	v_fmac_f32_e32 v84, 0xb102e308, v54
	v_pk_add_f32 v[54:55], v[86:87], v[84:85]
	v_mov_b32_e32 v88, v86
	v_sub_f32_e32 v81, v55, v85
	v_sub_f32_e32 v81, v87, v81
	v_add_f32_e32 v89, v59, v81
	v_pk_add_f32 v[86:87], v[54:55], v[86:87] neg_lo:[0,1] neg_hi:[0,1]
	v_pk_add_f32 v[90:91], v[54:55], v[88:89]
	v_mov_b32_e32 v85, v54
	v_mov_b32_e32 v87, v91
	v_pk_add_f32 v[92:93], v[84:85], v[86:87] neg_lo:[0,1] neg_hi:[0,1]
	v_pk_add_f32 v[84:85], v[84:85], v[86:87]
	v_mov_b32_e32 v88, v89
	v_pk_add_f32 v[86:87], v[84:85], v[54:55] op_sel:[1,0] op_sel_hi:[0,1] neg_lo:[0,1] neg_hi:[0,1]
	v_pk_add_f32 v[94:95], v[90:91], v[86:87] op_sel_hi:[1,0] neg_lo:[0,1] neg_hi:[0,1]
	v_mov_b32_e32 v90, v91
	v_mov_b32_e32 v91, v85
	v_pk_mov_b32 v[86:87], v[54:55], v[86:87] op_sel:[1,0]
	v_mov_b32_e32 v89, v54
	v_pk_add_f32 v[86:87], v[90:91], v[86:87] neg_lo:[0,1] neg_hi:[0,1]
	v_mov_b32_e32 v94, v92
	v_pk_add_f32 v[54:55], v[88:89], v[86:87] neg_lo:[0,1] neg_hi:[0,1]
	v_mov_b32_e32 v93, v85
	v_pk_add_f32 v[86:87], v[94:95], v[54:55]
	v_cmp_neq_f32_e64 s[40:41], s92, v57
	v_pk_add_f32 v[88:89], v[86:87], v[86:87] op_sel:[0,1] op_sel_hi:[1,0]
	v_mul_f32_e32 v44, 0xc1000000, v44
	v_pk_add_f32 v[84:85], v[84:85], v[88:89] op_sel:[1,0] op_sel_hi:[0,1]
	v_mov_b32_e32 v87, v84
	v_pk_add_f32 v[90:91], v[86:87], v[92:93] neg_lo:[0,1] neg_hi:[0,1]
	v_mov_b32_e32 v55, v88
	v_pk_add_f32 v[88:89], v[54:55], v[90:91] neg_lo:[0,1] neg_hi:[0,1]
	v_sub_f32_e32 v54, v86, v90
	v_sub_f32_e32 v81, v92, v54
	global_load_dword v92, v[52:53], off offset:2112
	global_load_dword v59, v[52:53], off offset:128
	global_load_dword v55, v[52:53], off offset:2176
	global_load_dword v54, v[52:53], off offset:2240
	s_nop 0
	global_load_dword v52, v[52:53], off offset:192
	v_add_f32_e32 v53, v88, v81
	v_add_f32_e32 v53, v53, v89
	v_add_f32_e32 v53, v84, v53
	v_cndmask_b32_e64 v53, v213, v53, s[40:41]
	v_cmp_lt_f32_e64 s[40:41], |v57|, s85
	s_waitcnt vmcnt(5)
; __device__ __forceinline__ unsigned f2bf(float f) { return pk2(f, 0.f) & 0xffffu; }
; __device__ __forceinline__ float sigm(float x) { return __builtin_amdgcn_rcpf(1.0f + __expf(-x)); }
; __device__ __forceinline__ void lru_s1_item(CParams& p, int layer, int item, LAS unsigned char* lds) {
;     ...
;             for (int s = 0; s < 4; ++s) { const int q = dir ? 3 - s : s;
;                 const float rg = sigm(acc[(2 * dir) * 4 + jt][q] + ba), ig = sigm(acc[(2 * dir + 1) * 4 + jt][q] + bx);
;                 float la = -8.0f * rg * sp; float bv = sqrtf(fmaxf(1.0f - __expf(2.0f * la), 0.f)) * ig * XCf[(tok0 + q) * 64 + j];
;                 if ((t0 + q) < 0) { la = 0.f; bv = 0.f; }
;                 const unsigned lab = f2bf(la), bvb = f2bf(bv);
;                 const size_t ro = (size_t)row_bci(b, c, tok0 + q) * W + ch;
;                 LA[(size_t)dir * MP * W + ro] = (bf16_t)lab; BB[(size_t)dir * MP * W + ro] = (bf16_t)bvb;
;                 const float a = __expf(__uint_as_float(lab << 16)), bq = __uint_as_float(bvb << 16);
;                 Bq = a * Bq + bq; Aq *= a; }
	v_add_f32_e32 v48, v48, v97
	v_mul_f32_e32 v48, 0xbfb8aa3b, v48
	v_cndmask_b32_e64 v86, v53, v57, s[40:41]
	v_mul_f32_e32 v84, v44, v86
	v_add_f32_e32 v44, v84, v84
	v_mul_f32_e32 v44, 0x3fb8aa3b, v44
	v_exp_f32_e32 v85, v44
	global_load_dword v93, v[82:83], off offset:2112
	global_load_dword v81, v[82:83], off offset:128
	global_load_dword v57, v[82:83], off offset:2176
	global_load_dword v44, v[82:83], off offset:2240
	global_load_dword v53, v[82:83], off offset:192
	v_exp_f32_e32 v82, v48
	v_add_f32_e32 v45, v45, v96
	v_sub_f32_e32 v48, 1.0, v85
	v_max_f32_e32 v48, 0, v48
	v_mul_f32_e32 v83, 0x4f800000, v48
	v_cmp_gt_f32_e64 s[40:41], s88, v48
	v_mul_f32_e32 v45, 0xbfb8aa3b, v45
	v_exp_f32_e32 v45, v45
	v_cndmask_b32_e64 v83, v48, v83, s[40:41]
	v_sqrt_f32_e32 v85, v83
	v_lshlrev_b32_e32 v48, 2, v78
	v_add_f32_e32 v78, 1.0, v82
	v_rcp_f32_e32 v78, v78
	v_add_u32_e32 v82, -1, v85
	v_fma_f32 v87, -v82, v85, v83
	v_cmp_ge_f32_e64 s[46:47], 0, v87
	v_add_u32_e32 v87, 1, v85
	v_add_f32_e32 v45, 1.0, v45
	v_cndmask_b32_e64 v82, v85, v82, s[46:47]
	v_fma_f32 v85, -v87, v85, v83
	v_cmp_lt_f32_e64 s[46:47], 0, v85
	v_rcp_f32_e32 v45, v45
	v_add_f32_e32 v49, v49, v97
	v_cndmask_b32_e64 v82, v82, v87, s[46:47]
	v_mul_f32_e32 v85, 0x37800000, v82
	v_cndmask_b32_e64 v82, v82, v85, s[40:41]
	v_cmp_class_f32_e64 s[40:41], v83, v209
	v_mul_f32_e32 v45, 0xc1000000, v45
	v_mul_f32_e32 v45, v45, v86
	v_cndmask_b32_e64 v82, v82, v83, s[40:41]
	ds_read_b32 v83, v68 offset:55360
	v_mul_f32_e32 v78, v78, v82
	v_cndmask_b32_e64 v82, v84, 0, vcc
	v_cvt_pk_bf16_f32 v90, v82, 0
	v_or_b32_e32 v82, v0, v56
	s_waitcnt lgkmcnt(0)
	v_mul_f32_e32 v78, v83, v78
	v_mov_b32_e32 v83, v1
	v_cndmask_b32_e64 v78, v78, 0, vcc
	v_lshlrev_b64 v[82:83], 1, v[82:83]
	v_cvt_pk_bf16_f32 v78, v78, 0
	v_lshl_add_u64 v[84:85], s[52:53], 0, v[82:83]
	v_lshl_add_u64 v[82:83], s[42:43], 0, v[82:83]
	ds_read_b32 v87, v69 offset:55360
	ds_read_b32 v88, v70 offset:55360
	ds_read_b32 v89, v71 offset:55360
	global_store_short v[82:83], v78, off
	v_lshlrev_b32_e32 v82, 16, v90
	v_mul_f32_e32 v82, 0x3fb8aa3b, v82
	global_store_short v[84:85], v90, off
	v_exp_f32_e32 v90, v82
	v_add_f32_e32 v82, v45, v45
	v_mul_f32_e32 v82, 0x3fb8aa3b, v82
	v_exp_f32_e32 v82, v82
	v_mul_f32_e32 v49, 0xbfb8aa3b, v49
	v_exp_f32_e32 v49, v49
	v_add_f32_e32 v46, v46, v96
	v_sub_f32_e32 v82, 1.0, v82
	v_max_f32_e32 v82, 0, v82
	v_mul_f32_e32 v83, 0x4f800000, v82
	v_cmp_gt_f32_e64 s[40:41], s88, v82
	v_add_f32_e32 v49, 1.0, v49
	v_rcp_f32_e32 v49, v49
	v_cndmask_b32_e64 v82, v82, v83, s[40:41]
	v_sqrt_f32_e32 v83, v82
	v_mul_f32_e32 v46, 0xbfb8aa3b, v46
	v_exp_f32_e32 v46, v46
	v_cndmask_b32_e64 v45, v45, 0, vcc
	v_add_u32_e32 v84, -1, v83
	v_fma_f32 v85, -v84, v83, v82
	v_cmp_ge_f32_e64 s[46:47], 0, v85
	v_add_u32_e32 v85, 1, v83
	v_cvt_pk_bf16_f32 v45, v45, 0
	v_cndmask_b32_e64 v84, v83, v84, s[46:47]
	v_fma_f32 v83, -v85, v83, v82
	v_cmp_lt_f32_e64 s[46:47], 0, v83
	v_add_f32_e32 v46, 1.0, v46
	v_rcp_f32_e32 v46, v46
	v_cndmask_b32_e64 v83, v84, v85, s[46:47]
	v_mul_f32_e32 v84, 0x37800000, v83
	v_cndmask_b32_e64 v83, v83, v84, s[40:41]
	v_cmp_class_f32_e64 s[40:41], v82, v209
	v_lshlrev_b32_e32 v78, 16, v78
	v_mul_f32_e32 v46, 0xc1000000, v46
	v_cndmask_b32_e64 v82, v83, v82, s[40:41]
	v_mul_f32_e32 v49, v49, v82
	v_or_b32_e32 v82, v60, v56
	v_mov_b32_e32 v83, v61
	v_lshlrev_b64 v[82:83], 1, v[82:83]
	v_lshl_add_u64 v[84:85], s[52:53], 0, v[82:83]
	global_store_short v[84:85], v45, off
	v_lshlrev_b32_e32 v45, 16, v45
	v_mul_f32_e32 v45, 0x3fb8aa3b, v45
	s_waitcnt lgkmcnt(2)
	v_mul_f32_e32 v49, v87, v49
	v_exp_f32_e32 v45, v45
	v_cndmask_b32_e64 v49, v49, 0, vcc
	v_cvt_pk_bf16_f32 v49, v49, 0
	v_lshl_add_u64 v[82:83], s[42:43], 0, v[82:83]
	v_fmac_f32_e32 v78, 0, v90
	global_store_short v[82:83], v49, off
	v_lshlrev_b32_e32 v49, 16, v49
	v_mul_f32_e32 v46, v46, v86
	v_fmac_f32_e32 v49, v45, v78
	v_add_f32_e32 v78, v46, v46
	v_mul_f32_e32 v78, 0x3fb8aa3b, v78
	v_exp_f32_e32 v78, v78
	v_add_f32_e32 v50, v50, v97
	v_mul_f32_e32 v50, 0xbfb8aa3b, v50
	v_exp_f32_e32 v50, v50
	v_sub_f32_e32 v78, 1.0, v78
	v_max_f32_e32 v78, 0, v78
	v_mul_f32_e32 v82, 0x4f800000, v78
	v_cmp_gt_f32_e64 s[40:41], s88, v78
	v_add_f32_e32 v47, v47, v96
	v_mul_f32_e32 v47, 0xbfb8aa3b, v47
	v_cndmask_b32_e64 v78, v78, v82, s[40:41]
	v_sqrt_f32_e32 v82, v78
	v_exp_f32_e32 v47, v47
	v_add_f32_e32 v50, 1.0, v50
	v_rcp_f32_e32 v50, v50
	v_add_u32_e32 v83, -1, v82
	v_fma_f32 v84, -v83, v82, v78
	v_cmp_ge_f32_e64 s[46:47], 0, v84
	v_add_u32_e32 v84, 1, v82
	v_cndmask_b32_e64 v46, v46, 0, vcc
	v_cndmask_b32_e64 v83, v82, v83, s[46:47]
	v_fma_f32 v82, -v84, v82, v78
	v_cmp_lt_f32_e64 s[46:47], 0, v82
	v_cvt_pk_bf16_f32 v46, v46, 0
	v_add_f32_e32 v47, 1.0, v47
	v_cndmask_b32_e64 v82, v83, v84, s[46:47]
	v_mul_f32_e32 v83, 0x37800000, v82
	v_cndmask_b32_e64 v82, v82, v83, s[40:41]
	v_cmp_class_f32_e64 s[40:41], v78, v209
	v_mov_b32_e32 v83, v65
	v_rcp_f32_e32 v47, v47
	v_cndmask_b32_e64 v78, v82, v78, s[40:41]
	v_or_b32_e32 v82, v64, v56
	v_lshlrev_b64 v[82:83], 1, v[82:83]
	v_lshl_add_u64 v[84:85], s[52:53], 0, v[82:83]
	global_store_short v[84:85], v46, off
	v_lshlrev_b32_e32 v46, 16, v46
	v_mul_f32_e32 v50, v50, v78
	v_mul_f32_e32 v46, 0x3fb8aa3b, v46
	s_waitcnt lgkmcnt(1)
; __device__ __forceinline__ unsigned f2bf(float f) { return pk2(f, 0.f) & 0xffffu; }
; __device__ __forceinline__ float sigm(float x) { return __builtin_amdgcn_rcpf(1.0f + __expf(-x)); }
; __device__ __forceinline__ void lru_s1_item(CParams& p, int layer, int item, LAS unsigned char* lds) {
;     ...
;             for (int s = 0; s < 4; ++s) { const int q = dir ? 3 - s : s;
;                 const float rg = sigm(acc[(2 * dir) * 4 + jt][q] + ba), ig = sigm(acc[(2 * dir + 1) * 4 + jt][q] + bx);
;                 float la = -8.0f * rg * sp; float bv = sqrtf(fmaxf(1.0f - __expf(2.0f * la), 0.f)) * ig * XCf[(tok0 + q) * 64 + j];
;                 if ((t0 + q) < 0) { la = 0.f; bv = 0.f; }
;                 const unsigned lab = f2bf(la), bvb = f2bf(bv);
;                 const size_t ro = (size_t)row_bci(b, c, tok0 + q) * W + ch;
;                 LA[(size_t)dir * MP * W + ro] = (bf16_t)lab; BB[(size_t)dir * MP * W + ro] = (bf16_t)bvb;
;                 const float a = __expf(__uint_as_float(lab << 16)), bq = __uint_as_float(bvb << 16);
;                 Bq = a * Bq + bq; Aq *= a; }
;             const int g = 4 * wave + h;
;             AG[((g * 2 + dir) * 2 + 0) * 64 + j] = Aq; AG[((g * 2 + dir) * 2 + 1) * 64 + j] = Bq; } }
	v_mul_f32_e32 v50, v88, v50
	v_exp_f32_e32 v46, v46
	v_cndmask_b32_e64 v50, v50, 0, vcc
	v_cvt_pk_bf16_f32 v50, v50, 0
	v_mul_f32_e32 v47, 0xc1000000, v47
	v_lshlrev_b32_e32 v78, 16, v50
	v_mul_f32_e32 v47, v47, v86
	v_fmac_f32_e32 v78, v46, v49
	v_add_f32_e32 v49, v47, v47
	v_mul_f32_e32 v49, 0x3fb8aa3b, v49
	v_exp_f32_e32 v49, v49
	v_lshl_add_u64 v[82:83], s[42:43], 0, v[82:83]
	global_store_short v[82:83], v50, off
	v_add_f32_e32 v50, v51, v97
	v_sub_f32_e32 v49, 1.0, v49
	v_max_f32_e32 v49, 0, v49
	v_mul_f32_e32 v51, 0x4f800000, v49
	v_cmp_gt_f32_e64 s[40:41], s88, v49
	v_mul_f32_e32 v50, 0xbfb8aa3b, v50
	v_exp_f32_e32 v50, v50
	v_cndmask_b32_e64 v49, v49, v51, s[40:41]
	v_sqrt_f32_e32 v51, v49
	v_mul_f32_e32 v45, v90, v45
	v_mul_f32_e32 v45, v46, v45
	v_add_f32_e32 v46, 1.0, v50
	v_add_u32_e32 v50, -1, v51
	v_fma_f32 v82, -v50, v51, v49
	v_cmp_ge_f32_e64 s[46:47], 0, v82
	v_add_u32_e32 v82, 1, v51
	v_rcp_f32_e32 v46, v46
	v_cndmask_b32_e64 v50, v51, v50, s[46:47]
	v_fma_f32 v51, -v82, v51, v49
	v_cmp_lt_f32_e64 s[46:47], 0, v51
	v_cndmask_b32_e64 v47, v47, 0, vcc
	s_waitcnt vmcnt(15)
	v_add_f32_e32 v39, v39, v92
	v_cndmask_b32_e64 v50, v50, v82, s[46:47]
	v_mul_f32_e32 v51, 0x37800000, v50
	v_cndmask_b32_e64 v50, v50, v51, s[40:41]
	v_cmp_class_f32_e64 s[40:41], v49, v209
	v_mul_f32_e32 v39, 0xbfb8aa3b, v39
	v_exp_f32_e32 v39, v39
	v_cndmask_b32_e64 v49, v50, v49, s[40:41]
	v_mul_f32_e32 v46, v46, v49
	s_waitcnt lgkmcnt(0)
	v_mul_f32_e32 v46, v89, v46
	v_cndmask_b32_e64 v46, v46, 0, vcc
	v_cvt_pk_bf16_f32 v49, v47, 0
	v_cvt_pk_bf16_f32 v82, v46, 0
	v_or_b32_e32 v46, v62, v56
	v_mov_b32_e32 v47, v63
	v_lshlrev_b64 v[46:47], 1, v[46:47]
	v_lshl_add_u64 v[50:51], s[52:53], 0, v[46:47]
	v_lshl_add_u64 v[46:47], s[42:43], 0, v[46:47]
	global_store_short v[46:47], v82, off
	v_mul_f32_e32 v47, 0xbfb8aa3b, v66
	global_store_short v[50:51], v49, off
	v_lshlrev_b32_e32 v49, 16, v49
	v_fma_f32 v50, v66, s9, -v47
	v_rndne_f32_e32 v51, v47
	v_mul_f32_e32 v49, 0x3fb8aa3b, v49
	v_fmac_f32_e32 v50, 0xb2a5705f, v66
	v_sub_f32_e32 v47, v47, v51
	v_exp_f32_e32 v49, v49
	v_add_f32_e32 v47, v47, v50
	v_exp_f32_e32 v47, v47
	v_cvt_i32_f32_e32 v50, v51
	v_lshlrev_b32_e32 v46, 16, v82
	v_fmac_f32_e32 v46, v49, v78
	v_mul_f32_e32 v45, v49, v45
	v_add_u32_e32 v49, v76, v48
	ds_write2st64_b32 v49, v45, v46 offset1:1
	v_ldexp_f32 v45, v47, v50
	v_cmp_nlt_f32_e64 s[40:41], s11, v66
	v_add_f32_e32 v39, 1.0, v39
	v_rcp_f32_e32 v39, v39
	v_cndmask_b32_e64 v45, 0, v45, s[40:41]
	v_cmp_ngt_f32_e64 s[40:41], s14, v66
	s_waitcnt vmcnt(12)
	v_add_f32_e32 v43, v43, v93
	v_mul_f32_e32 v39, 0xc1000000, v39
	v_cndmask_b32_e64 v45, v213, v45, s[40:41]
	v_add_f32_e32 v49, 1.0, v45
	v_add_f32_e32 v46, -1.0, v49
	v_sub_f32_e32 v47, v46, v49
	v_add_f32_e32 v47, 1.0, v47
	v_sub_f32_e32 v46, v45, v46
	v_add_f32_e32 v50, v46, v47
	v_frexp_mant_f32_e32 v51, v49
	v_cvt_f64_f32_e32 v[46:47], v49
	v_frexp_exp_i32_f64_e32 v46, v[46:47]
	v_cmp_gt_f32_e64 s[40:41], s12, v51
	v_mul_f32_e32 v43, 0xbfb8aa3b, v43
	v_exp_f32_e32 v43, v43
	v_subbrev_co_u32_e64 v66, s[40:41], 0, v46, s[40:41]
	v_sub_u32_e32 v46, 0, v66
	v_ldexp_f32 v47, v49, v46
	v_add_f32_e32 v49, -1.0, v47
	v_add_f32_e32 v51, 1.0, v47
	v_ldexp_f32 v46, v50, v46
	v_add_f32_e32 v50, 1.0, v49
	v_add_f32_e32 v78, -1.0, v51
	v_sub_f32_e32 v50, v47, v50
	v_sub_f32_e32 v47, v47, v78
	v_add_f32_e32 v50, v46, v50
	v_add_f32_e32 v46, v46, v47
	v_add_f32_e32 v78, v51, v46
	v_rcp_f32_e32 v87, v78
	v_sub_f32_e32 v47, v51, v78
	v_add_f32_e32 v86, v46, v47
	v_add_f32_e32 v47, v49, v50
	v_sub_f32_e32 v46, v49, v47
	v_mul_f32_e32 v88, v47, v87
	v_add_f32_e32 v49, v50, v46
	v_mul_f32_e32 v50, v78, v88
	v_fma_f32 v82, v88, v78, -v50
	v_fmac_f32_e32 v82, v88, v86
	v_add_f32_e32 v46, v50, v82
	v_sub_f32_e32 v51, v47, v46
	v_pk_add_f32 v[84:85], v[46:47], v[50:51] neg_lo:[0,1] neg_hi:[0,1]
	v_mov_b32_e32 v83, v46
	v_pk_add_f32 v[46:47], v[84:85], v[82:83] neg_lo:[0,1] neg_hi:[0,1]
	v_cmp_neq_f32_e64 s[40:41], s92, v45
	v_add_f32_e32 v47, v49, v47
	v_add_f32_e32 v46, v46, v47
	v_add_f32_e32 v47, v51, v46
	v_mul_f32_e32 v49, v87, v47
	v_mul_f32_e32 v50, v78, v49
	v_fma_f32 v82, v49, v78, -v50
	v_fmac_f32_e32 v82, v49, v86
	v_sub_f32_e32 v51, v51, v47
	v_add_f32_e32 v78, v46, v51
	v_add_f32_e32 v46, v50, v82
	v_sub_f32_e32 v51, v47, v46
	v_pk_add_f32 v[84:85], v[46:47], v[50:51] neg_lo:[0,1] neg_hi:[0,1]
	v_mov_b32_e32 v83, v46
	v_pk_add_f32 v[46:47], v[84:85], v[82:83] neg_lo:[0,1] neg_hi:[0,1]
	v_add_f32_e32 v43, 1.0, v43
	v_add_f32_e32 v47, v78, v47
	v_add_f32_e32 v46, v46, v47
	v_add_f32_e32 v47, v88, v49
	v_add_f32_e32 v46, v51, v46
	v_sub_f32_e32 v50, v47, v88
	v_mul_f32_e32 v46, v87, v46
	v_sub_f32_e32 v49, v49, v50
	v_add_f32_e32 v49, v49, v46
	v_add_f32_e32 v50, v47, v49
	v_mul_f32_e32 v78, v50, v50
	v_fmamk_f32 v46, v78, 0x3e9b6dac, v211
	v_fmaak_f32 v167, v78, v46, 0x3f2aaada
	v_cvt_f32_i32_e32 v46, v66
	v_sub_f32_e32 v47, v50, v47
	v_sub_f32_e32 v47, v49, v47
	v_ldexp_f32 v49, v47, 1
	v_mul_f32_e32 v47, v50, v78
	v_pk_mul_f32 v[82:83], v[46:47], v[166:167]
	v_ldexp_f32 v51, v50, 1
	v_fma_f32 v50, v46, s84, -v82
	v_fmac_f32_e32 v50, 0xb102e308, v46
	v_pk_add_f32 v[46:47], v[82:83], v[50:51]
	v_mov_b32_e32 v84, v82
	v_sub_f32_e32 v51, v47, v51
	v_sub_f32_e32 v51, v83, v51
	v_add_f32_e32 v85, v49, v51
	v_pk_add_f32 v[82:83], v[46:47], v[82:83] neg_lo:[0,1] neg_hi:[0,1]
	v_pk_add_f32 v[86:87], v[46:47], v[84:85]
	v_mov_b32_e32 v51, v46
	v_mov_b32_e32 v83, v87
	v_pk_add_f32 v[88:89], v[50:51], v[82:83] neg_lo:[0,1] neg_hi:[0,1]
	v_pk_add_f32 v[50:51], v[50:51], v[82:83]
	v_mov_b32_e32 v84, v85
; __device__ __forceinline__ unsigned f2bf(float f) { return pk2(f, 0.f) & 0xffffu; }
; __device__ __forceinline__ float sigm(float x) { return __builtin_amdgcn_rcpf(1.0f + __expf(-x)); }
; __device__ __forceinline__ void lru_s1_item(CParams& p, int layer, int item, LAS unsigned char* lds) {
;     ...
;             for (int s = 0; s < 4; ++s) { const int q = dir ? 3 - s : s;
;                 const float rg = sigm(acc[(2 * dir) * 4 + jt][q] + ba), ig = sigm(acc[(2 * dir + 1) * 4 + jt][q] + bx);
;                 float la = -8.0f * rg * sp; float bv = sqrtf(fmaxf(1.0f - __expf(2.0f * la), 0.f)) * ig * XCf[(tok0 + q) * 64 + j];
;                 if ((t0 + q) < 0) { la = 0.f; bv = 0.f; }
;                 const unsigned lab = f2bf(la), bvb = f2bf(bv);
;                 const size_t ro = (size_t)row_bci(b, c, tok0 + q) * W + ch;
;                 LA[(size_t)dir * MP * W + ro] = (bf16_t)lab; BB[(size_t)dir * MP * W + ro] = (bf16_t)bvb;
;                 const float a = __expf(__uint_as_float(lab << 16)), bq = __uint_as_float(bvb << 16);
;                 Bq = a * Bq + bq; Aq *= a; }
	v_pk_add_f32 v[82:83], v[50:51], v[46:47] op_sel:[1,0] op_sel_hi:[0,1] neg_lo:[0,1] neg_hi:[0,1]
	v_pk_add_f32 v[90:91], v[86:87], v[82:83] op_sel_hi:[1,0] neg_lo:[0,1] neg_hi:[0,1]
	v_mov_b32_e32 v86, v87
	v_mov_b32_e32 v87, v51
	v_pk_mov_b32 v[82:83], v[46:47], v[82:83] op_sel:[1,0]
	v_mov_b32_e32 v85, v46
	v_pk_add_f32 v[82:83], v[86:87], v[82:83] neg_lo:[0,1] neg_hi:[0,1]
	v_mov_b32_e32 v90, v88
	v_pk_add_f32 v[46:47], v[84:85], v[82:83] neg_lo:[0,1] neg_hi:[0,1]
	v_mov_b32_e32 v89, v51
	v_pk_add_f32 v[82:83], v[90:91], v[46:47]
	v_rcp_f32_e32 v43, v43
	v_pk_add_f32 v[84:85], v[82:83], v[82:83] op_sel:[0,1] op_sel_hi:[1,0]
	v_add_f32_e32 v38, v38, v92
	v_pk_add_f32 v[50:51], v[50:51], v[84:85] op_sel:[1,0] op_sel_hi:[0,1]
	v_mov_b32_e32 v83, v50
	v_pk_add_f32 v[86:87], v[82:83], v[88:89] neg_lo:[0,1] neg_hi:[0,1]
	v_mov_b32_e32 v47, v84
	v_sub_f32_e32 v49, v82, v86
	v_pk_add_f32 v[46:47], v[46:47], v[86:87] neg_lo:[0,1] neg_hi:[0,1]
	v_sub_f32_e32 v49, v88, v49
	v_add_f32_e32 v46, v46, v49
	v_add_f32_e32 v46, v46, v47
	v_add_f32_e32 v46, v50, v46
	v_cndmask_b32_e64 v46, v213, v46, s[40:41]
	v_cmp_lt_f32_e64 s[40:41], |v45|, s85
	v_mul_f32_e32 v38, 0xbfb8aa3b, v38
	v_exp_f32_e32 v66, v38
	v_cndmask_b32_e64 v45, v46, v45, s[40:41]
	v_mul_f32_e32 v39, v39, v45
	v_add_f32_e32 v47, v39, v39
	v_mul_f32_e32 v47, 0x3fb8aa3b, v47
	v_exp_f32_e32 v47, v47
	v_or_b32_e32 v46, 0x820000, v56
	v_cndmask_b32_e64 v39, v39, 0, vcc
	v_add_f32_e32 v42, v42, v93
	v_sub_f32_e32 v47, 1.0, v47
	v_max_f32_e32 v47, 0, v47
	v_mul_f32_e32 v49, 0x4f800000, v47
	v_cmp_gt_f32_e64 s[40:41], s88, v47
	v_mul_f32_e32 v42, 0xbfb8aa3b, v42
	v_exp_f32_e32 v42, v42
	v_cndmask_b32_e64 v49, v47, v49, s[40:41]
	v_sqrt_f32_e32 v50, v49
	v_mov_b32_e32 v47, v2
	v_add_f32_e32 v37, v37, v92
	v_mul_f32_e32 v37, 0xbfb8aa3b, v37
	v_add_u32_e32 v51, -1, v50
	v_fma_f32 v56, -v51, v50, v49
	v_cmp_ge_f32_e64 s[46:47], 0, v56
	v_add_u32_e32 v56, 1, v50
	v_add_f32_e32 v42, 1.0, v42
	v_cndmask_b32_e64 v51, v50, v51, s[46:47]
	v_fma_f32 v50, -v56, v50, v49
	v_cmp_lt_f32_e64 s[46:47], 0, v50
	v_exp_f32_e32 v37, v37
	v_rcp_f32_e32 v42, v42
	v_cndmask_b32_e64 v50, v51, v56, s[46:47]
	v_mul_f32_e32 v51, 0x37800000, v50
	v_cndmask_b32_e64 v50, v50, v51, s[40:41]
	ds_read_b32 v51, v71 offset:55360
	v_cmp_class_f32_e64 s[40:41], v49, v209
	v_cvt_pk_bf16_f32 v56, v39, 0
	v_add_f32_e32 v37, 1.0, v37
	v_cndmask_b32_e64 v49, v50, v49, s[40:41]
	v_mul_f32_e32 v43, v43, v49
	ds_read_b32 v49, v70 offset:55360
	s_waitcnt lgkmcnt(1)
	v_mul_f32_e32 v43, v51, v43
	v_lshl_add_u64 v[50:51], v[62:63], 0, v[46:47]
	v_cndmask_b32_e64 v43, v43, 0, vcc
	v_lshlrev_b64 v[50:51], 1, v[50:51]
	v_cvt_pk_bf16_f32 v43, v43, 0
	v_lshl_add_u64 v[38:39], s[42:43], 0, v[50:51]
	global_store_short v[38:39], v43, off
	v_add_f32_e32 v39, 1.0, v66
	v_rcp_f32_e32 v39, v39
	v_lshlrev_b32_e32 v38, 16, v56
	v_mul_f32_e32 v38, 0x3fb8aa3b, v38
	v_lshl_add_u64 v[82:83], s[52:53], 0, v[50:51]
	v_exp_f32_e32 v50, v38
	v_mul_f32_e32 v38, 0xc1000000, v39
	v_mul_f32_e32 v38, v38, v45
	v_add_f32_e32 v39, v38, v38
	v_mul_f32_e32 v39, 0x3fb8aa3b, v39
	v_exp_f32_e32 v39, v39
	v_lshlrev_b32_e32 v51, 16, v43
	global_store_short v[82:83], v56, off
	v_rcp_f32_e32 v37, v37
	v_sub_f32_e32 v39, 1.0, v39
	v_max_f32_e32 v39, 0, v39
	v_mul_f32_e32 v43, 0x4f800000, v39
	v_cmp_gt_f32_e64 s[40:41], s88, v39
	v_cndmask_b32_e64 v38, v38, 0, vcc
	v_mul_f32_e32 v37, 0xc1000000, v37
	v_cndmask_b32_e64 v39, v39, v43, s[40:41]
	v_sqrt_f32_e32 v43, v39
	v_mul_f32_e32 v37, v37, v45
	v_fmac_f32_e32 v51, 0, v50
	v_add_f32_e32 v36, v36, v92
	v_add_u32_e32 v56, -1, v43
	v_fma_f32 v66, -v56, v43, v39
	v_cmp_ge_f32_e64 s[46:47], 0, v66
	v_add_u32_e32 v66, 1, v43
	v_mul_f32_e32 v36, 0xbfb8aa3b, v36
	v_cndmask_b32_e64 v56, v43, v56, s[46:47]
	v_fma_f32 v43, -v66, v43, v39
	v_cmp_lt_f32_e64 s[46:47], 0, v43
	v_exp_f32_e32 v36, v36
	v_add_f32_e32 v28, v28, v59
	v_cndmask_b32_e64 v43, v56, v66, s[46:47]
	v_mul_f32_e32 v56, 0x37800000, v43
	v_cndmask_b32_e64 v43, v43, v56, s[40:41]
	v_cmp_class_f32_e64 s[40:41], v39, v209
	ds_read_b32 v56, v69 offset:55360
	v_add_f32_e32 v36, 1.0, v36
	v_cndmask_b32_e64 v39, v43, v39, s[40:41]
	v_mul_f32_e32 v39, v42, v39
	s_waitcnt lgkmcnt(1)
	v_mul_f32_e32 v39, v49, v39
	v_cndmask_b32_e64 v39, v39, 0, vcc
	v_cvt_pk_bf16_f32 v49, v38, 0
	v_cvt_pk_bf16_f32 v66, v39, 0
	v_lshl_add_u64 v[38:39], v[64:65], 0, v[46:47]
	v_lshlrev_b64 v[38:39], 1, v[38:39]
	v_lshl_add_u64 v[42:43], s[52:53], 0, v[38:39]
	v_lshl_add_u64 v[38:39], s[42:43], 0, v[38:39]
	global_store_short v[38:39], v66, off
	v_add_f32_e32 v38, v37, v37
	v_mul_f32_e32 v38, 0x3fb8aa3b, v38
	v_exp_f32_e32 v38, v38
	global_store_short v[42:43], v49, off
	v_lshlrev_b32_e32 v42, 16, v49
	v_add_f32_e32 v39, v41, v93
	v_sub_f32_e32 v38, 1.0, v38
	v_max_f32_e32 v38, 0, v38
	v_mul_f32_e32 v41, 0x4f800000, v38
	v_cmp_gt_f32_e64 s[40:41], s88, v38
	v_mul_f32_e32 v42, 0x3fb8aa3b, v42
	v_exp_f32_e32 v42, v42
	v_cndmask_b32_e64 v38, v38, v41, s[40:41]
	v_sqrt_f32_e32 v41, v38
	v_lshlrev_b32_e32 v49, 16, v66
	v_mul_f32_e32 v39, 0xbfb8aa3b, v39
	v_fmac_f32_e32 v49, v42, v51
	v_exp_f32_e32 v39, v39
	v_mul_f32_e32 v50, v50, v42
	v_add_u32_e32 v42, -1, v41
	v_fma_f32 v43, -v42, v41, v38
	v_cmp_ge_f32_e64 s[46:47], 0, v43
	v_add_u32_e32 v43, 1, v41
	v_add_f32_e32 v39, 1.0, v39
	v_cndmask_b32_e64 v42, v41, v42, s[46:47]
	v_fma_f32 v41, -v43, v41, v38
	v_cmp_lt_f32_e64 s[46:47], 0, v41
	v_rcp_f32_e32 v39, v39
	v_rcp_f32_e32 v36, v36
	v_cndmask_b32_e64 v41, v42, v43, s[46:47]
	v_mul_f32_e32 v42, 0x37800000, v41
	v_cndmask_b32_e64 v41, v41, v42, s[40:41]
	v_cmp_class_f32_e64 s[40:41], v38, v209
	v_mul_f32_e32 v36, 0xc1000000, v36
	v_mul_f32_e32 v36, v36, v45
	v_cndmask_b32_e64 v38, v41, v38, s[40:41]
	v_mul_f32_e32 v38, v39, v38
	ds_read_b32 v41, v68 offset:55360
	s_waitcnt lgkmcnt(1)
; __device__ __forceinline__ unsigned f2bf(float f) { return pk2(f, 0.f) & 0xffffu; }
; __device__ __forceinline__ float sigm(float x) { return __builtin_amdgcn_rcpf(1.0f + __expf(-x)); }
; __device__ __forceinline__ void lru_s1_item(CParams& p, int layer, int item, LAS unsigned char* lds) {
;     ...
;             const float sp = log1pf(expf(-lam));
;     ...
;             for (int s = 0; s < 4; ++s) { const int q = dir ? 3 - s : s;
;                 const float rg = sigm(acc[(2 * dir) * 4 + jt][q] + ba), ig = sigm(acc[(2 * dir + 1) * 4 + jt][q] + bx);
;                 float la = -8.0f * rg * sp; float bv = sqrtf(fmaxf(1.0f - __expf(2.0f * la), 0.f)) * ig * XCf[(tok0 + q) * 64 + j];
;                 if ((t0 + q) < 0) { la = 0.f; bv = 0.f; }
;                 const unsigned lab = f2bf(la), bvb = f2bf(bv);
;                 const size_t ro = (size_t)row_bci(b, c, tok0 + q) * W + ch;
;                 LA[(size_t)dir * MP * W + ro] = (bf16_t)lab; BB[(size_t)dir * MP * W + ro] = (bf16_t)bvb;
;                 const float a = __expf(__uint_as_float(lab << 16)), bq = __uint_as_float(bvb << 16);
;                 Bq = a * Bq + bq; Aq *= a; }
;             const int g = 4 * wave + h;
;             AG[((g * 2 + dir) * 2 + 0) * 64 + j] = Aq; AG[((g * 2 + dir) * 2 + 1) * 64 + j] = Bq; } }
	v_mul_f32_e32 v38, v56, v38
	v_cndmask_b32_e64 v38, v38, 0, vcc
	v_cvt_pk_bf16_f32 v51, v38, 0
	v_lshl_add_u64 v[38:39], v[60:61], 0, v[46:47]
	v_lshlrev_b64 v[38:39], 1, v[38:39]
	v_lshl_add_u64 v[42:43], s[52:53], 0, v[38:39]
	v_lshl_add_u64 v[38:39], s[42:43], 0, v[38:39]
	global_store_short v[38:39], v51, off
	v_add_f32_e32 v38, v36, v36
	v_mul_f32_e32 v38, 0x3fb8aa3b, v38
	v_exp_f32_e32 v38, v38
	v_cndmask_b32_e64 v37, v37, 0, vcc
	v_cvt_pk_bf16_f32 v37, v37, 0
	global_store_short v[42:43], v37, off
	v_sub_f32_e32 v38, 1.0, v38
	v_max_f32_e32 v38, 0, v38
	v_lshlrev_b32_e32 v37, 16, v37
	v_add_f32_e32 v39, v40, v93
	v_mul_f32_e32 v40, 0x4f800000, v38
	v_cmp_gt_f32_e64 s[40:41], s88, v38
	v_mul_f32_e32 v37, 0x3fb8aa3b, v37
	v_mul_f32_e32 v39, 0xbfb8aa3b, v39
	v_cndmask_b32_e64 v38, v38, v40, s[40:41]
	v_exp_f32_e32 v37, v37
	v_exp_f32_e32 v39, v39
	v_sqrt_f32_e32 v40, v38
	v_lshlrev_b32_e32 v42, 16, v51
	v_fmac_f32_e32 v42, v37, v49
	v_mul_f32_e32 v43, v37, v50
	v_add_f32_e32 v37, 1.0, v39
	v_add_u32_e32 v39, -1, v40
	v_fma_f32 v45, -v39, v40, v38
	v_cmp_ge_f32_e64 s[46:47], 0, v45
	v_add_u32_e32 v45, 1, v40
	v_rcp_f32_e32 v37, v37
	v_cndmask_b32_e64 v39, v40, v39, s[46:47]
	v_fma_f32 v40, -v45, v40, v38
	v_cmp_lt_f32_e64 s[46:47], 0, v40
	v_cndmask_b32_e64 v36, v36, 0, vcc
	v_mul_f32_e32 v28, 0xbfb8aa3b, v28
	v_cndmask_b32_e64 v39, v39, v45, s[46:47]
	v_mul_f32_e32 v40, 0x37800000, v39
	v_cndmask_b32_e64 v39, v39, v40, s[40:41]
	v_cmp_class_f32_e64 s[40:41], v38, v209
	v_cvt_pk_bf16_f32 v40, v36, 0
	v_exp_f32_e32 v28, v28
	v_cndmask_b32_e64 v38, v39, v38, s[40:41]
	v_mul_f32_e32 v37, v37, v38
	s_waitcnt lgkmcnt(0)
	v_mul_f32_e32 v37, v41, v37
	v_cndmask_b32_e64 v37, v37, 0, vcc
	v_cvt_pk_bf16_f32 v41, v37, 0
	v_lshl_add_u64 v[36:37], v[0:1], 0, v[46:47]
	v_lshlrev_b64 v[36:37], 1, v[36:37]
	v_lshl_add_u64 v[38:39], s[52:53], 0, v[36:37]
	global_store_short v[38:39], v40, off
	v_lshlrev_b32_e32 v38, 16, v40
	v_mul_f32_e32 v38, 0x3fb8aa3b, v38
	v_exp_f32_e32 v38, v38
	v_lshl_add_u64 v[36:37], s[42:43], 0, v[36:37]
	global_store_short v[36:37], v41, off
	v_lshlrev_b32_e32 v36, 16, v41
	v_fmac_f32_e32 v36, v38, v42
	v_mul_f32_e32 v37, v38, v43
	v_mul_f32_e32 v38, 0xbfb8aa3b, v67
	v_fma_f32 v39, v67, s9, -v38
	v_rndne_f32_e32 v40, v38
	v_fmac_f32_e32 v39, 0xb2a5705f, v67
	v_sub_f32_e32 v38, v38, v40
	v_add_f32_e32 v38, v38, v39
	v_exp_f32_e32 v38, v38
	v_cvt_i32_f32_e32 v39, v40
	v_add3_u32 v40, s90, v48, v74
	ds_write2st64_b32 v40, v37, v36 offset0:2 offset1:3
	v_cmp_nlt_f32_e64 s[40:41], s11, v67
	v_ldexp_f32 v36, v38, v39
	v_add_f32_e32 v28, 1.0, v28
	v_cndmask_b32_e64 v36, 0, v36, s[40:41]
	v_cmp_ngt_f32_e64 s[40:41], s14, v67
	v_rcp_f32_e32 v28, v28
	s_waitcnt vmcnt(19)
	v_add_f32_e32 v32, v32, v81
	v_cndmask_b32_e64 v56, v213, v36, s[40:41]
	v_add_f32_e32 v38, 1.0, v56
	v_add_f32_e32 v36, -1.0, v38
	v_sub_f32_e32 v37, v36, v38
	v_add_f32_e32 v37, 1.0, v37
	v_sub_f32_e32 v36, v56, v36
	v_add_f32_e32 v39, v36, v37
	v_frexp_mant_f32_e32 v40, v38
	v_cvt_f64_f32_e32 v[36:37], v38
	v_frexp_exp_i32_f64_e32 v36, v[36:37]
	v_cmp_gt_f32_e64 s[40:41], s12, v40
	v_mul_f32_e32 v28, 0xc1000000, v28
	v_mul_f32_e32 v32, 0xbfb8aa3b, v32
	v_subbrev_co_u32_e64 v46, s[40:41], 0, v36, s[40:41]
	v_sub_u32_e32 v36, 0, v46
	v_ldexp_f32 v37, v38, v36
	v_add_f32_e32 v38, -1.0, v37
	v_add_f32_e32 v40, 1.0, v37
	v_ldexp_f32 v36, v39, v36
	v_add_f32_e32 v39, 1.0, v38
	v_add_f32_e32 v41, -1.0, v40
	v_sub_f32_e32 v39, v37, v39
	v_sub_f32_e32 v37, v37, v41
	v_add_f32_e32 v39, v36, v39
	v_add_f32_e32 v36, v36, v37
	v_add_f32_e32 v47, v40, v36
	v_rcp_f32_e32 v49, v47
	v_sub_f32_e32 v37, v40, v47
	v_add_f32_e32 v48, v36, v37
	v_add_f32_e32 v37, v38, v39
	v_mul_f32_e32 v51, v37, v49
	v_sub_f32_e32 v36, v38, v37
	v_mul_f32_e32 v38, v47, v51
	v_fma_f32 v40, v51, v47, -v38
	v_fmac_f32_e32 v40, v51, v48
	v_add_f32_e32 v50, v39, v36
	v_add_f32_e32 v36, v38, v40
	v_sub_f32_e32 v39, v37, v36
	v_pk_add_f32 v[42:43], v[36:37], v[38:39] neg_lo:[0,1] neg_hi:[0,1]
	v_mov_b32_e32 v41, v36
	v_pk_add_f32 v[36:37], v[42:43], v[40:41] neg_lo:[0,1] neg_hi:[0,1]
	v_cmp_neq_f32_e64 s[40:41], s92, v56
	v_add_f32_e32 v37, v50, v37
	v_add_f32_e32 v36, v36, v37
	v_add_f32_e32 v37, v39, v36
	v_mul_f32_e32 v50, v49, v37
	v_mul_f32_e32 v38, v47, v50
	v_fma_f32 v40, v50, v47, -v38
	v_fmac_f32_e32 v40, v50, v48
	v_sub_f32_e32 v39, v39, v37
	v_add_f32_e32 v47, v36, v39
	v_add_f32_e32 v36, v38, v40
	v_sub_f32_e32 v39, v37, v36
	v_pk_add_f32 v[42:43], v[36:37], v[38:39] neg_lo:[0,1] neg_hi:[0,1]
	v_mov_b32_e32 v41, v36
	v_pk_add_f32 v[36:37], v[42:43], v[40:41] neg_lo:[0,1] neg_hi:[0,1]
	v_exp_f32_e32 v32, v32
	v_add_f32_e32 v37, v47, v37
	v_add_f32_e32 v36, v36, v37
	v_add_f32_e32 v37, v51, v50
	v_add_f32_e32 v36, v39, v36
	v_sub_f32_e32 v38, v37, v51
	v_mul_f32_e32 v36, v49, v36
	v_sub_f32_e32 v38, v50, v38
	v_add_f32_e32 v38, v38, v36
	v_add_f32_e32 v40, v37, v38
	v_mul_f32_e32 v41, v40, v40
	v_fmamk_f32 v36, v41, 0x3e9b6dac, v211
	v_fmaak_f32 v167, v41, v36, 0x3f2aaada
	v_cvt_f32_i32_e32 v36, v46
	v_sub_f32_e32 v37, v40, v37
	v_sub_f32_e32 v37, v38, v37
	v_ldexp_f32 v42, v37, 1
	v_mul_f32_e32 v37, v40, v41
	v_ldexp_f32 v39, v40, 1
	v_pk_mul_f32 v[40:41], v[36:37], v[166:167]
	v_add_f32_e32 v29, v29, v59
	v_fma_f32 v38, v36, s84, -v40
	v_fmac_f32_e32 v38, 0xb102e308, v36
	v_pk_add_f32 v[36:37], v[40:41], v[38:39]
	v_mul_f32_e32 v29, 0xbfb8aa3b, v29
	v_sub_f32_e32 v39, v37, v39
	v_sub_f32_e32 v39, v41, v39
	v_add_f32_e32 v43, v42, v39
	v_mov_b32_e32 v42, v40
	v_pk_add_f32 v[40:41], v[36:37], v[40:41] neg_lo:[0,1] neg_hi:[0,1]
	v_pk_add_f32 v[46:47], v[36:37], v[42:43]
	v_mov_b32_e32 v39, v36
; __device__ __forceinline__ unsigned f2bf(float f) { return pk2(f, 0.f) & 0xffffu; }
; __device__ __forceinline__ float sigm(float x) { return __builtin_amdgcn_rcpf(1.0f + __expf(-x)); }
; #define p (*kparams())
; __device__ __forceinline__ void lru_s1_item(CParams& p, int layer, int item, LAS unsigned char* lds) {
;     ...
;     for (int jt = 0; jt < 4; ++jt) { const int j = 16 * jt + r, ch = kb * 64 + j;
; #pragma unroll
;         for (int dir = 0; dir < 2; ++dir) {
;             const float ba = p.in[8][(layer * 2 + dir) * W + ch], bx = p.in[10][(layer * 2 + dir) * W + ch], lam = p.in[11][(layer * 2 + dir) * W + ch];
;             const float sp = log1pf(expf(-lam));
;             float Aq = 1.f, Bq = 0.f;
; #pragma unroll
;             for (int s = 0; s < 4; ++s) { const int q = dir ? 3 - s : s;
;                 const float rg = sigm(acc[(2 * dir) * 4 + jt][q] + ba), ig = sigm(acc[(2 * dir + 1) * 4 + jt][q] + bx);
;                 float la = -8.0f * rg * sp; float bv = sqrtf(fmaxf(1.0f - __expf(2.0f * la), 0.f)) * ig * XCf[(tok0 + q) * 64 + j];
;                 if ((t0 + q) < 0) { la = 0.f; bv = 0.f; }
;                 const unsigned lab = f2bf(la), bvb = f2bf(bv);
;                 const size_t ro = (size_t)row_bci(b, c, tok0 + q) * W + ch;
;                 LA[(size_t)dir * MP * W + ro] = (bf16_t)lab; BB[(size_t)dir * MP * W + ro] = (bf16_t)bvb;
;                 const float a = __expf(__uint_as_float(lab << 16)), bq = __uint_as_float(bvb << 16);
;                 Bq = a * Bq + bq; Aq *= a; }
;             const int g = 4 * wave + h;
;             AG[((g * 2 + dir) * 2 + 0) * 64 + j] = Aq; AG[((g * 2 + dir) * 2 + 1) * 64 + j] = Bq; } }
	v_mov_b32_e32 v41, v47
	v_pk_add_f32 v[48:49], v[38:39], v[40:41] neg_lo:[0,1] neg_hi:[0,1]
	v_pk_add_f32 v[38:39], v[38:39], v[40:41]
	v_mov_b32_e32 v42, v43
	v_pk_add_f32 v[40:41], v[38:39], v[36:37] op_sel:[1,0] op_sel_hi:[0,1] neg_lo:[0,1] neg_hi:[0,1]
	v_pk_add_f32 v[50:51], v[46:47], v[40:41] op_sel_hi:[1,0] neg_lo:[0,1] neg_hi:[0,1]
	v_mov_b32_e32 v46, v47
	v_mov_b32_e32 v47, v39
	v_pk_mov_b32 v[40:41], v[36:37], v[40:41] op_sel:[1,0]
	v_mov_b32_e32 v43, v36
	v_pk_add_f32 v[40:41], v[46:47], v[40:41] neg_lo:[0,1] neg_hi:[0,1]
	v_mov_b32_e32 v50, v48
	v_pk_add_f32 v[36:37], v[42:43], v[40:41] neg_lo:[0,1] neg_hi:[0,1]
	v_mov_b32_e32 v49, v39
	v_pk_add_f32 v[40:41], v[50:51], v[36:37]
	v_exp_f32_e32 v29, v29
	v_pk_add_f32 v[42:43], v[40:41], v[40:41] op_sel:[0,1] op_sel_hi:[1,0]
	v_add_f32_e32 v32, 1.0, v32
	v_pk_add_f32 v[38:39], v[38:39], v[42:43] op_sel:[1,0] op_sel_hi:[0,1]
	v_mov_b32_e32 v41, v38
	v_pk_add_f32 v[46:47], v[40:41], v[48:49] neg_lo:[0,1] neg_hi:[0,1]
	v_mov_b32_e32 v37, v42
	v_sub_f32_e32 v39, v40, v46
	v_pk_add_f32 v[36:37], v[36:37], v[46:47] neg_lo:[0,1] neg_hi:[0,1]
	v_sub_f32_e32 v39, v48, v39
	v_add_f32_e32 v36, v36, v39
	v_add_f32_e32 v36, v36, v37
	v_add_f32_e32 v36, v38, v36
	v_cndmask_b32_e64 v36, v213, v36, s[40:41]
	v_cmp_lt_f32_e64 s[40:41], |v56|, s85
	v_rcp_f32_e32 v32, v32
	v_add_f32_e32 v29, 1.0, v29
	v_cndmask_b32_e64 v40, v36, v56, s[40:41]
	v_mul_f32_e32 v36, v28, v40
	v_add_f32_e32 v28, v36, v36
	v_mul_f32_e32 v28, 0x3fb8aa3b, v28
	v_exp_f32_e32 v28, v28
	v_rcp_f32_e32 v29, v29
	v_or_b32_e32 v45, s29, v77
	v_cndmask_b32_e64 v36, v36, 0, vcc
	v_sub_f32_e32 v28, 1.0, v28
	v_max_f32_e32 v28, 0, v28
	v_mul_f32_e32 v37, 0x4f800000, v28
	v_cmp_gt_f32_e64 s[40:41], s88, v28
	v_cvt_pk_bf16_f32 v46, v36, 0
	v_or_b32_e32 v36, v0, v45
	v_cndmask_b32_e64 v37, v28, v37, s[40:41]
	v_sqrt_f32_e32 v38, v37
	v_mul_f32_e32 v29, 0xc1000000, v29
	v_mul_f32_e32 v29, v29, v40
	v_add_f32_e32 v33, v33, v81
	v_add_u32_e32 v39, -1, v38
	v_fma_f32 v41, -v39, v38, v37
	v_cmp_ge_f32_e64 s[46:47], 0, v41
	v_add_u32_e32 v41, 1, v38
	v_mul_f32_e32 v33, 0xbfb8aa3b, v33
	v_cndmask_b32_e64 v39, v38, v39, s[46:47]
	v_fma_f32 v38, -v41, v38, v37
	v_cmp_lt_f32_e64 s[46:47], 0, v38
	v_exp_f32_e32 v33, v33
	v_add_f32_e32 v30, v30, v59
	v_cndmask_b32_e64 v38, v39, v41, s[46:47]
	v_mul_f32_e32 v39, 0x37800000, v38
	v_cndmask_b32_e64 v38, v38, v39, s[40:41]
	v_cmp_class_f32_e64 s[40:41], v37, v209
	v_mul_f32_e32 v30, 0xbfb8aa3b, v30
	v_add_f32_e32 v33, 1.0, v33
	v_cndmask_b32_e64 v37, v38, v37, s[40:41]
	ds_read_b32 v38, v68 offset:55424
	v_mul_f32_e32 v32, v32, v37
	v_mov_b32_e32 v37, v1
	v_lshlrev_b64 v[36:37], 1, v[36:37]
	ds_read_b32 v41, v69 offset:55424
	ds_read_b32 v42, v70 offset:55424
	ds_read_b32 v43, v71 offset:55424
	s_waitcnt lgkmcnt(3)
	v_mul_f32_e32 v32, v38, v32
	v_cndmask_b32_e64 v32, v32, 0, vcc
	v_cvt_pk_bf16_f32 v32, v32, 0
	v_lshl_add_u64 v[38:39], s[52:53], 0, v[36:37]
	v_lshl_add_u64 v[36:37], s[42:43], 0, v[36:37]
	global_store_short v[38:39], v46, off
	global_store_short v[36:37], v32, off
	v_lshlrev_b32_e32 v39, 16, v32
	v_add_f32_e32 v32, v29, v29
	v_mul_f32_e32 v32, 0x3fb8aa3b, v32
	v_exp_f32_e32 v32, v32
	v_lshlrev_b32_e32 v36, 16, v46
	v_mul_f32_e32 v36, 0x3fb8aa3b, v36
	v_exp_f32_e32 v38, v36
	v_sub_f32_e32 v32, 1.0, v32
	v_max_f32_e32 v32, 0, v32
	v_mul_f32_e32 v36, 0x4f800000, v32
	v_cmp_gt_f32_e64 s[40:41], s88, v32
	v_exp_f32_e32 v30, v30
	v_rcp_f32_e32 v33, v33
	v_cndmask_b32_e64 v32, v32, v36, s[40:41]
	v_sqrt_f32_e32 v36, v32
	v_add_f32_e32 v30, 1.0, v30
	v_rcp_f32_e32 v30, v30
	v_cndmask_b32_e64 v29, v29, 0, vcc
	v_add_u32_e32 v37, -1, v36
	v_fma_f32 v46, -v37, v36, v32
	v_cmp_ge_f32_e64 s[46:47], 0, v46
	v_add_u32_e32 v46, 1, v36
	v_mul_f32_e32 v30, 0xc1000000, v30
	v_cndmask_b32_e64 v37, v36, v37, s[46:47]
	v_fma_f32 v36, -v46, v36, v32
	v_cmp_lt_f32_e64 s[46:47], 0, v36
	v_mul_f32_e32 v30, v30, v40
	v_cvt_pk_bf16_f32 v29, v29, 0
	v_cndmask_b32_e64 v36, v37, v46, s[46:47]
	v_mul_f32_e32 v37, 0x37800000, v36
	v_cndmask_b32_e64 v36, v36, v37, s[40:41]
	v_cmp_class_f32_e64 s[40:41], v32, v209
	v_add_f32_e32 v31, v31, v59
	v_mul_f32_e32 v31, 0xbfb8aa3b, v31
	v_cndmask_b32_e64 v32, v36, v32, s[40:41]
	v_mul_f32_e32 v32, v33, v32
	s_waitcnt lgkmcnt(2)
	v_mul_f32_e32 v32, v41, v32
	v_cndmask_b32_e64 v32, v32, 0, vcc
	v_cvt_pk_bf16_f32 v41, v32, 0
	v_or_b32_e32 v32, v60, v45
	v_mov_b32_e32 v33, v61
	v_lshlrev_b64 v[32:33], 1, v[32:33]
	v_lshl_add_u64 v[36:37], s[52:53], 0, v[32:33]
	v_lshl_add_u64 v[32:33], s[42:43], 0, v[32:33]
	global_store_short v[32:33], v41, off
	v_add_f32_e32 v32, v30, v30
	v_mul_f32_e32 v32, 0x3fb8aa3b, v32
	v_exp_f32_e32 v32, v32
	v_add_f32_e32 v33, v34, v81
	v_mul_f32_e32 v33, 0xbfb8aa3b, v33
	global_store_short v[36:37], v29, off
	v_sub_f32_e32 v32, 1.0, v32
	v_max_f32_e32 v32, 0, v32
	v_mul_f32_e32 v34, 0x4f800000, v32
	v_cmp_gt_f32_e64 s[40:41], s88, v32
	v_exp_f32_e32 v33, v33
	v_exp_f32_e32 v31, v31
	v_cndmask_b32_e64 v32, v32, v34, s[40:41]
	v_sqrt_f32_e32 v34, v32
	v_add_f32_e32 v33, 1.0, v33
	v_rcp_f32_e32 v33, v33
	v_add_f32_e32 v31, 1.0, v31
	v_add_u32_e32 v36, -1, v34
	v_fma_f32 v37, -v36, v34, v32
	v_cmp_ge_f32_e64 s[46:47], 0, v37
	v_add_u32_e32 v37, 1, v34
	v_rcp_f32_e32 v31, v31
	v_cndmask_b32_e64 v36, v34, v36, s[46:47]
	v_fma_f32 v34, -v37, v34, v32
	v_cmp_lt_f32_e64 s[46:47], 0, v34
	v_mul_f32_e32 v31, 0xc1000000, v31
	v_mul_f32_e32 v31, v31, v40
	v_cndmask_b32_e64 v34, v36, v37, s[46:47]
	v_mul_f32_e32 v36, 0x37800000, v34
	v_cndmask_b32_e64 v34, v34, v36, s[40:41]
	v_cmp_class_f32_e64 s[40:41], v32, v209
	v_cndmask_b32_e64 v30, v30, 0, vcc
	v_lshlrev_b32_e32 v29, 16, v29
	v_cndmask_b32_e64 v32, v34, v32, s[40:41]
	v_mul_f32_e32 v32, v33, v32
	s_waitcnt lgkmcnt(1)
; __device__ __forceinline__ unsigned f2bf(float f) { return pk2(f, 0.f) & 0xffffu; }
; __device__ __forceinline__ float sigm(float x) { return __builtin_amdgcn_rcpf(1.0f + __expf(-x)); }
; #define p (*kparams())
; __device__ __forceinline__ void lru_s1_item(CParams& p, int layer, int item, LAS unsigned char* lds) {
;     ...
;     for (int jt = 0; jt < 4; ++jt) { const int j = 16 * jt + r, ch = kb * 64 + j;
; #pragma unroll
;         for (int dir = 0; dir < 2; ++dir) {
;             const float ba = p.in[8][(layer * 2 + dir) * W + ch], bx = p.in[10][(layer * 2 + dir) * W + ch], lam = p.in[11][(layer * 2 + dir) * W + ch];
;             const float sp = log1pf(expf(-lam));
;             float Aq = 1.f, Bq = 0.f;
; #pragma unroll
;             for (int s = 0; s < 4; ++s) { const int q = dir ? 3 - s : s;
;                 const float rg = sigm(acc[(2 * dir) * 4 + jt][q] + ba), ig = sigm(acc[(2 * dir + 1) * 4 + jt][q] + bx);
;                 float la = -8.0f * rg * sp; float bv = sqrtf(fmaxf(1.0f - __expf(2.0f * la), 0.f)) * ig * XCf[(tok0 + q) * 64 + j];
;                 if ((t0 + q) < 0) { la = 0.f; bv = 0.f; }
;                 const unsigned lab = f2bf(la), bvb = f2bf(bv);
;                 const size_t ro = (size_t)row_bci(b, c, tok0 + q) * W + ch;
;                 LA[(size_t)dir * MP * W + ro] = (bf16_t)lab; BB[(size_t)dir * MP * W + ro] = (bf16_t)bvb;
;                 const float a = __expf(__uint_as_float(lab << 16)), bq = __uint_as_float(bvb << 16);
;                 Bq = a * Bq + bq; Aq *= a; }
;             const int g = 4 * wave + h;
;             AG[((g * 2 + dir) * 2 + 0) * 64 + j] = Aq; AG[((g * 2 + dir) * 2 + 1) * 64 + j] = Bq; } }
	v_mul_f32_e32 v32, v42, v32
	v_cndmask_b32_e64 v32, v32, 0, vcc
	v_cvt_pk_bf16_f32 v34, v32, 0
	v_or_b32_e32 v32, v64, v45
	v_mov_b32_e32 v33, v65
	v_lshlrev_b64 v[32:33], 1, v[32:33]
	v_lshl_add_u64 v[36:37], s[52:53], 0, v[32:33]
	v_lshl_add_u64 v[32:33], s[42:43], 0, v[32:33]
	global_store_short v[32:33], v34, off
	v_add_f32_e32 v32, v31, v31
	v_mul_f32_e32 v32, 0x3fb8aa3b, v32
	v_exp_f32_e32 v32, v32
	v_cvt_pk_bf16_f32 v30, v30, 0
	v_mul_f32_e32 v29, 0x3fb8aa3b, v29
	global_store_short v[36:37], v30, off
	v_sub_f32_e32 v32, 1.0, v32
	v_max_f32_e32 v32, 0, v32
	v_lshlrev_b32_e32 v30, 16, v30
	v_add_f32_e32 v33, v35, v81
	v_mul_f32_e32 v35, 0x4f800000, v32
	v_cmp_gt_f32_e64 s[40:41], s88, v32
	v_exp_f32_e32 v29, v29
	v_mul_f32_e32 v30, 0x3fb8aa3b, v30
	v_mul_f32_e32 v33, 0xbfb8aa3b, v33
	v_cndmask_b32_e64 v32, v32, v35, s[40:41]
	v_exp_f32_e32 v30, v30
	v_exp_f32_e32 v33, v33
	v_sqrt_f32_e32 v35, v32
	v_fmac_f32_e32 v39, 0, v38
	v_lshlrev_b32_e32 v41, 16, v41
	v_fmac_f32_e32 v41, v29, v39
	v_mul_f32_e32 v29, v38, v29
	v_lshlrev_b32_e32 v34, 16, v34
	v_fmac_f32_e32 v34, v30, v41
	v_mul_f32_e32 v29, v30, v29
	v_add_f32_e32 v30, 1.0, v33
	v_add_u32_e32 v33, -1, v35
	v_fma_f32 v36, -v33, v35, v32
	v_cmp_ge_f32_e64 s[46:47], 0, v36
	v_add_u32_e32 v36, 1, v35
	v_rcp_f32_e32 v30, v30
	v_cndmask_b32_e64 v33, v35, v33, s[46:47]
	v_fma_f32 v35, -v36, v35, v32
	v_cmp_lt_f32_e64 s[46:47], 0, v35
	v_cndmask_b32_e64 v31, v31, 0, vcc
	v_lshlrev_b32_e32 v28, 2, v77
	v_cndmask_b32_e64 v33, v33, v36, s[46:47]
	v_mul_f32_e32 v35, 0x37800000, v33
	v_cndmask_b32_e64 v33, v33, v35, s[40:41]
	v_cmp_class_f32_e64 s[40:41], v32, v209
	v_cvt_pk_bf16_f32 v35, v31, 0
	v_mov_b32_e32 v31, v63
	v_cndmask_b32_e64 v32, v33, v32, s[40:41]
	v_mul_f32_e32 v30, v30, v32
	s_waitcnt lgkmcnt(0)
	v_mul_f32_e32 v30, v43, v30
	v_cndmask_b32_e64 v30, v30, 0, vcc
	v_cvt_pk_bf16_f32 v36, v30, 0
	v_or_b32_e32 v30, v62, v45
	v_lshlrev_b64 v[30:31], 1, v[30:31]
	v_lshl_add_u64 v[32:33], s[52:53], 0, v[30:31]
	global_store_short v[32:33], v35, off
	v_lshlrev_b32_e32 v32, 16, v35
	v_mul_f32_e32 v32, 0x3fb8aa3b, v32
	v_exp_f32_e32 v32, v32
	v_lshl_add_u64 v[30:31], s[42:43], 0, v[30:31]
	global_store_short v[30:31], v36, off
	v_lshlrev_b32_e32 v30, 16, v36
	v_mul_f32_e32 v31, 0xbfb8aa3b, v79
	v_fmac_f32_e32 v30, v32, v34
	v_fma_f32 v33, v79, s9, -v31
	v_rndne_f32_e32 v34, v31
	v_fmac_f32_e32 v33, 0xb2a5705f, v79
	v_sub_f32_e32 v31, v31, v34
	v_add_f32_e32 v31, v31, v33
	v_exp_f32_e32 v31, v31
	v_cvt_i32_f32_e32 v33, v34
	v_mul_f32_e32 v29, v32, v29
	v_add_u32_e32 v32, v76, v28
	ds_write2st64_b32 v32, v29, v30 offset1:1
	v_ldexp_f32 v29, v31, v33
	v_cmp_nlt_f32_e64 s[40:41], s11, v79
	v_add_f32_e32 v23, v23, v55
	v_mul_f32_e32 v23, 0xbfb8aa3b, v23
	v_cndmask_b32_e64 v29, 0, v29, s[40:41]
	v_cmp_ngt_f32_e64 s[40:41], s14, v79
	v_exp_f32_e32 v23, v23
	s_waitcnt vmcnt(26)
	v_add_f32_e32 v27, v27, v57
	v_cndmask_b32_e64 v29, v213, v29, s[40:41]
	v_add_f32_e32 v32, 1.0, v29
	v_add_f32_e32 v30, -1.0, v32
	v_sub_f32_e32 v31, v30, v32
	v_add_f32_e32 v31, 1.0, v31
	v_sub_f32_e32 v30, v29, v30
	v_add_f32_e32 v33, v30, v31
	v_frexp_mant_f32_e32 v34, v32
	v_cvt_f64_f32_e32 v[30:31], v32
	v_frexp_exp_i32_f64_e32 v30, v[30:31]
	v_cmp_gt_f32_e64 s[40:41], s12, v34
	v_add_f32_e32 v23, 1.0, v23
	v_rcp_f32_e32 v23, v23
	v_subbrev_co_u32_e64 v38, s[40:41], 0, v30, s[40:41]
	v_sub_u32_e32 v30, 0, v38
	v_ldexp_f32 v31, v32, v30
	v_add_f32_e32 v32, -1.0, v31
	v_add_f32_e32 v34, 1.0, v31
	v_ldexp_f32 v30, v33, v30
	v_add_f32_e32 v33, 1.0, v32
	v_add_f32_e32 v35, -1.0, v34
	v_sub_f32_e32 v33, v31, v33
	v_sub_f32_e32 v31, v31, v35
	v_add_f32_e32 v33, v30, v33
	v_add_f32_e32 v30, v30, v31
	v_add_f32_e32 v39, v34, v30
	v_rcp_f32_e32 v41, v39
	v_sub_f32_e32 v31, v34, v39
	v_add_f32_e32 v40, v30, v31
	v_add_f32_e32 v31, v32, v33
	v_mul_f32_e32 v43, v31, v41
	v_sub_f32_e32 v30, v32, v31
	v_mul_f32_e32 v32, v39, v43
	v_fma_f32 v34, v43, v39, -v32
	v_fmac_f32_e32 v34, v43, v40
	v_add_f32_e32 v42, v33, v30
	v_add_f32_e32 v30, v32, v34
	v_sub_f32_e32 v33, v31, v30
	v_pk_add_f32 v[36:37], v[30:31], v[32:33] neg_lo:[0,1] neg_hi:[0,1]
	v_mov_b32_e32 v35, v30
	v_pk_add_f32 v[30:31], v[36:37], v[34:35] neg_lo:[0,1] neg_hi:[0,1]
	v_cmp_neq_f32_e64 s[40:41], s92, v29
	v_add_f32_e32 v31, v42, v31
	v_add_f32_e32 v30, v30, v31
	v_add_f32_e32 v31, v33, v30
	v_mul_f32_e32 v42, v41, v31
	v_mul_f32_e32 v32, v39, v42
	v_fma_f32 v34, v42, v39, -v32
	v_fmac_f32_e32 v34, v42, v40
	v_sub_f32_e32 v33, v33, v31
	v_add_f32_e32 v39, v30, v33
	v_add_f32_e32 v30, v32, v34
	v_sub_f32_e32 v33, v31, v30
	v_pk_add_f32 v[36:37], v[30:31], v[32:33] neg_lo:[0,1] neg_hi:[0,1]
	v_mov_b32_e32 v35, v30
	v_pk_add_f32 v[30:31], v[36:37], v[34:35] neg_lo:[0,1] neg_hi:[0,1]
	v_mul_f32_e32 v23, 0xc1000000, v23
	v_add_f32_e32 v31, v39, v31
	v_add_f32_e32 v30, v30, v31
	v_add_f32_e32 v31, v43, v42
	v_add_f32_e32 v30, v33, v30
	v_sub_f32_e32 v32, v31, v43
	v_mul_f32_e32 v30, v41, v30
	v_sub_f32_e32 v32, v42, v32
	v_add_f32_e32 v32, v32, v30
	v_add_f32_e32 v34, v31, v32
	v_mul_f32_e32 v35, v34, v34
	v_fmamk_f32 v30, v35, 0x3e9b6dac, v211
	v_fmaak_f32 v167, v35, v30, 0x3f2aaada
	v_cvt_f32_i32_e32 v30, v38
	v_sub_f32_e32 v31, v34, v31
	v_sub_f32_e32 v31, v32, v31
	v_ldexp_f32 v36, v31, 1
	v_mul_f32_e32 v31, v34, v35
	v_ldexp_f32 v33, v34, 1
	v_pk_mul_f32 v[34:35], v[30:31], v[166:167]
	v_mul_f32_e32 v27, 0xbfb8aa3b, v27
	v_fma_f32 v32, v30, s84, -v34
	v_fmac_f32_e32 v32, 0xb102e308, v30
	v_pk_add_f32 v[30:31], v[34:35], v[32:33]
	v_exp_f32_e32 v27, v27
	v_sub_f32_e32 v33, v31, v33
	v_sub_f32_e32 v33, v35, v33
	v_add_f32_e32 v37, v36, v33
	v_mov_b32_e32 v36, v34
; __device__ __forceinline__ unsigned f2bf(float f) { return pk2(f, 0.f) & 0xffffu; }
; __device__ __forceinline__ float sigm(float x) { return __builtin_amdgcn_rcpf(1.0f + __expf(-x)); }
; #define p (*kparams())
; __device__ __forceinline__ void lru_s1_item(CParams& p, int layer, int item, LAS unsigned char* lds) {
;     ...
;     for (int jt = 0; jt < 4; ++jt) { const int j = 16 * jt + r, ch = kb * 64 + j;
; #pragma unroll
;         for (int dir = 0; dir < 2; ++dir) {
;             const float ba = p.in[8][(layer * 2 + dir) * W + ch], bx = p.in[10][(layer * 2 + dir) * W + ch], lam = p.in[11][(layer * 2 + dir) * W + ch];
;             const float sp = log1pf(expf(-lam));
;             float Aq = 1.f, Bq = 0.f;
; #pragma unroll
;             for (int s = 0; s < 4; ++s) { const int q = dir ? 3 - s : s;
;                 const float rg = sigm(acc[(2 * dir) * 4 + jt][q] + ba), ig = sigm(acc[(2 * dir + 1) * 4 + jt][q] + bx);
;                 float la = -8.0f * rg * sp; float bv = sqrtf(fmaxf(1.0f - __expf(2.0f * la), 0.f)) * ig * XCf[(tok0 + q) * 64 + j];
;                 if ((t0 + q) < 0) { la = 0.f; bv = 0.f; }
;                 const unsigned lab = f2bf(la), bvb = f2bf(bv);
;                 const size_t ro = (size_t)row_bci(b, c, tok0 + q) * W + ch;
;                 LA[(size_t)dir * MP * W + ro] = (bf16_t)lab; BB[(size_t)dir * MP * W + ro] = (bf16_t)bvb;
;                 const float a = __expf(__uint_as_float(lab << 16)), bq = __uint_as_float(bvb << 16);
;                 Bq = a * Bq + bq; Aq *= a; }
;             const int g = 4 * wave + h;
;             AG[((g * 2 + dir) * 2 + 0) * 64 + j] = Aq; AG[((g * 2 + dir) * 2 + 1) * 64 + j] = Bq; } }
	v_pk_add_f32 v[34:35], v[30:31], v[34:35] neg_lo:[0,1] neg_hi:[0,1]
	v_pk_add_f32 v[38:39], v[30:31], v[36:37]
	v_mov_b32_e32 v33, v30
	v_mov_b32_e32 v35, v39
	v_pk_add_f32 v[40:41], v[32:33], v[34:35] neg_lo:[0,1] neg_hi:[0,1]
	v_pk_add_f32 v[32:33], v[32:33], v[34:35]
	v_mov_b32_e32 v36, v37
	v_pk_add_f32 v[34:35], v[32:33], v[30:31] op_sel:[1,0] op_sel_hi:[0,1] neg_lo:[0,1] neg_hi:[0,1]
	v_pk_add_f32 v[42:43], v[38:39], v[34:35] op_sel_hi:[1,0] neg_lo:[0,1] neg_hi:[0,1]
	v_mov_b32_e32 v38, v39
	v_mov_b32_e32 v39, v33
	v_pk_mov_b32 v[34:35], v[30:31], v[34:35] op_sel:[1,0]
	v_mov_b32_e32 v37, v30
	v_pk_add_f32 v[34:35], v[38:39], v[34:35] neg_lo:[0,1] neg_hi:[0,1]
	v_mov_b32_e32 v42, v40
	v_pk_add_f32 v[30:31], v[36:37], v[34:35] neg_lo:[0,1] neg_hi:[0,1]
	v_mov_b32_e32 v41, v33
	v_pk_add_f32 v[34:35], v[42:43], v[30:31]
	v_add_f32_e32 v27, 1.0, v27
	v_pk_add_f32 v[36:37], v[34:35], v[34:35] op_sel:[0,1] op_sel_hi:[1,0]
	v_rcp_f32_e32 v27, v27
	v_pk_add_f32 v[32:33], v[32:33], v[36:37] op_sel:[1,0] op_sel_hi:[0,1]
	v_mov_b32_e32 v35, v32
	v_pk_add_f32 v[38:39], v[34:35], v[40:41] neg_lo:[0,1] neg_hi:[0,1]
	v_mov_b32_e32 v31, v36
	v_sub_f32_e32 v33, v34, v38
	v_pk_add_f32 v[30:31], v[30:31], v[38:39] neg_lo:[0,1] neg_hi:[0,1]
	v_sub_f32_e32 v33, v40, v33
	v_add_f32_e32 v30, v30, v33
	v_add_f32_e32 v30, v30, v31
	v_add_f32_e32 v30, v32, v30
	v_cndmask_b32_e64 v30, v213, v30, s[40:41]
	v_cmp_lt_f32_e64 s[40:41], |v29|, s85
	v_add_f32_e32 v22, v22, v55
	ds_read_b32 v36, v70 offset:55424
	v_cndmask_b32_e64 v29, v30, v29, s[40:41]
	v_mul_f32_e32 v23, v23, v29
	v_add_f32_e32 v31, v23, v23
	v_mul_f32_e32 v31, 0x3fb8aa3b, v31
	v_exp_f32_e32 v31, v31
	v_or_b32_e32 v30, 0x820000, v45
	v_cndmask_b32_e64 v23, v23, 0, vcc
	v_cvt_pk_bf16_f32 v37, v23, 0
	v_sub_f32_e32 v31, 1.0, v31
	v_max_f32_e32 v31, 0, v31
	v_mul_f32_e32 v32, 0x4f800000, v31
	v_cmp_gt_f32_e64 s[40:41], s88, v31
	v_mul_f32_e32 v22, 0xbfb8aa3b, v22
	v_add_f32_e32 v26, v26, v57
	v_cndmask_b32_e64 v32, v31, v32, s[40:41]
	v_sqrt_f32_e32 v33, v32
	v_mov_b32_e32 v31, v2
	v_mul_f32_e32 v26, 0xbfb8aa3b, v26
	v_exp_f32_e32 v26, v26
	v_add_u32_e32 v34, -1, v33
	v_fma_f32 v35, -v34, v33, v32
	v_cmp_ge_f32_e64 s[46:47], 0, v35
	v_add_u32_e32 v35, 1, v33
	v_add_f32_e32 v21, v21, v55
	v_cndmask_b32_e64 v34, v33, v34, s[46:47]
	v_fma_f32 v33, -v35, v33, v32
	v_cmp_lt_f32_e64 s[46:47], 0, v33
	v_mul_f32_e32 v21, 0xbfb8aa3b, v21
	v_add_f32_e32 v26, 1.0, v26
	v_cndmask_b32_e64 v33, v34, v35, s[46:47]
	v_mul_f32_e32 v34, 0x37800000, v33
	v_cndmask_b32_e64 v33, v33, v34, s[40:41]
	ds_read_b32 v34, v71 offset:55424
	v_cmp_class_f32_e64 s[40:41], v32, v209
	v_exp_f32_e32 v21, v21
	v_rcp_f32_e32 v26, v26
	v_cndmask_b32_e64 v32, v33, v32, s[40:41]
	v_mul_f32_e32 v27, v27, v32
	v_lshl_add_u64 v[32:33], v[62:63], 0, v[30:31]
	v_lshlrev_b64 v[32:33], 1, v[32:33]
	s_waitcnt lgkmcnt(0)
	v_mul_f32_e32 v27, v34, v27
	v_lshl_add_u64 v[34:35], s[52:53], 0, v[32:33]
	global_store_short v[34:35], v37, off
	v_exp_f32_e32 v34, v22
	v_cndmask_b32_e64 v27, v27, 0, vcc
	v_cvt_pk_bf16_f32 v27, v27, 0
	v_lshl_add_u64 v[22:23], s[42:43], 0, v[32:33]
	global_store_short v[22:23], v27, off
	v_add_f32_e32 v23, 1.0, v34
	v_rcp_f32_e32 v23, v23
	v_lshlrev_b32_e32 v22, 16, v37
	v_mul_f32_e32 v22, 0x3fb8aa3b, v22
	v_exp_f32_e32 v32, v22
	v_mul_f32_e32 v22, 0xc1000000, v23
	v_mul_f32_e32 v22, v22, v29
	v_add_f32_e32 v23, v22, v22
	v_mul_f32_e32 v23, 0x3fb8aa3b, v23
	v_exp_f32_e32 v23, v23
	v_lshlrev_b32_e32 v33, 16, v27
	v_add_f32_e32 v21, 1.0, v21
	v_rcp_f32_e32 v21, v21
	v_sub_f32_e32 v23, 1.0, v23
	v_max_f32_e32 v23, 0, v23
	v_mul_f32_e32 v27, 0x4f800000, v23
	v_cmp_gt_f32_e64 s[40:41], s88, v23
	v_cndmask_b32_e64 v22, v22, 0, vcc
	v_mul_f32_e32 v21, 0xc1000000, v21
	v_cndmask_b32_e64 v23, v23, v27, s[40:41]
	v_sqrt_f32_e32 v27, v23
	v_mul_f32_e32 v21, v21, v29
	v_fmac_f32_e32 v33, 0, v32
	v_add_f32_e32 v20, v20, v55
	v_add_u32_e32 v34, -1, v27
	v_fma_f32 v35, -v34, v27, v23
	v_cmp_ge_f32_e64 s[46:47], 0, v35
	v_add_u32_e32 v35, 1, v27
	v_mul_f32_e32 v20, 0xbfb8aa3b, v20
	v_cndmask_b32_e64 v34, v27, v34, s[46:47]
	v_fma_f32 v27, -v35, v27, v23
	v_cmp_lt_f32_e64 s[46:47], 0, v27
	v_exp_f32_e32 v20, v20
	v_add_f32_e32 v12, v12, v52
	v_cndmask_b32_e64 v27, v34, v35, s[46:47]
	v_mul_f32_e32 v34, 0x37800000, v27
	v_cndmask_b32_e64 v27, v27, v34, s[40:41]
	v_cmp_class_f32_e64 s[40:41], v23, v209
	ds_read_b32 v34, v69 offset:55424
	v_cvt_pk_bf16_f32 v35, v22, 0
	v_cndmask_b32_e64 v23, v27, v23, s[40:41]
	v_mul_f32_e32 v23, v26, v23
	v_mul_f32_e32 v23, v36, v23
	v_cndmask_b32_e64 v23, v23, 0, vcc
	v_cvt_pk_bf16_f32 v36, v23, 0
	v_lshl_add_u64 v[22:23], v[64:65], 0, v[30:31]
	v_lshlrev_b64 v[22:23], 1, v[22:23]
	v_lshl_add_u64 v[26:27], s[52:53], 0, v[22:23]
	v_lshl_add_u64 v[22:23], s[42:43], 0, v[22:23]
	global_store_short v[22:23], v36, off
	v_add_f32_e32 v22, v21, v21
	v_mul_f32_e32 v22, 0x3fb8aa3b, v22
	v_exp_f32_e32 v22, v22
	global_store_short v[26:27], v35, off
	v_lshlrev_b32_e32 v26, 16, v35
	v_add_f32_e32 v23, v25, v57
	v_sub_f32_e32 v22, 1.0, v22
	v_max_f32_e32 v22, 0, v22
	v_mul_f32_e32 v25, 0x4f800000, v22
	v_cmp_gt_f32_e64 s[40:41], s88, v22
	v_mul_f32_e32 v26, 0x3fb8aa3b, v26
	v_exp_f32_e32 v26, v26
	v_cndmask_b32_e64 v22, v22, v25, s[40:41]
	v_sqrt_f32_e32 v25, v22
	v_lshlrev_b32_e32 v35, 16, v36
	v_mul_f32_e32 v23, 0xbfb8aa3b, v23
	v_fmac_f32_e32 v35, v26, v33
	v_exp_f32_e32 v23, v23
	v_mul_f32_e32 v32, v32, v26
	v_add_u32_e32 v26, -1, v25
	v_fma_f32 v27, -v26, v25, v22
	v_cmp_ge_f32_e64 s[46:47], 0, v27
	v_add_u32_e32 v27, 1, v25
	v_add_f32_e32 v23, 1.0, v23
	v_cndmask_b32_e64 v26, v25, v26, s[46:47]
	v_fma_f32 v25, -v27, v25, v22
	v_cmp_lt_f32_e64 s[46:47], 0, v25
	v_rcp_f32_e32 v23, v23
	v_add_f32_e32 v20, 1.0, v20
	v_cndmask_b32_e64 v25, v26, v27, s[46:47]
	v_mul_f32_e32 v26, 0x37800000, v25
	v_cndmask_b32_e64 v25, v25, v26, s[40:41]
	v_cmp_class_f32_e64 s[40:41], v22, v209
	v_rcp_f32_e32 v20, v20
	v_cndmask_b32_e64 v21, v21, 0, vcc
	v_cndmask_b32_e64 v22, v25, v22, s[40:41]
	v_mul_f32_e32 v22, v23, v22
	ds_read_b32 v25, v68 offset:55424
	s_waitcnt lgkmcnt(1)
; __device__ __forceinline__ unsigned f2bf(float f) { return pk2(f, 0.f) & 0xffffu; }
; __device__ __forceinline__ float sigm(float x) { return __builtin_amdgcn_rcpf(1.0f + __expf(-x)); }
; #define p (*kparams())
; __device__ __forceinline__ void lru_s1_item(CParams& p, int layer, int item, LAS unsigned char* lds) {
;     ...
;     for (int jt = 0; jt < 4; ++jt) { const int j = 16 * jt + r, ch = kb * 64 + j;
; #pragma unroll
;         for (int dir = 0; dir < 2; ++dir) {
;             const float ba = p.in[8][(layer * 2 + dir) * W + ch], bx = p.in[10][(layer * 2 + dir) * W + ch], lam = p.in[11][(layer * 2 + dir) * W + ch];
;             const float sp = log1pf(expf(-lam));
;             float Aq = 1.f, Bq = 0.f;
; #pragma unroll
;             for (int s = 0; s < 4; ++s) { const int q = dir ? 3 - s : s;
;                 const float rg = sigm(acc[(2 * dir) * 4 + jt][q] + ba), ig = sigm(acc[(2 * dir + 1) * 4 + jt][q] + bx);
;                 float la = -8.0f * rg * sp; float bv = sqrtf(fmaxf(1.0f - __expf(2.0f * la), 0.f)) * ig * XCf[(tok0 + q) * 64 + j];
;                 if ((t0 + q) < 0) { la = 0.f; bv = 0.f; }
;                 const unsigned lab = f2bf(la), bvb = f2bf(bv);
;                 const size_t ro = (size_t)row_bci(b, c, tok0 + q) * W + ch;
;                 LA[(size_t)dir * MP * W + ro] = (bf16_t)lab; BB[(size_t)dir * MP * W + ro] = (bf16_t)bvb;
;                 const float a = __expf(__uint_as_float(lab << 16)), bq = __uint_as_float(bvb << 16);
;                 Bq = a * Bq + bq; Aq *= a; }
;             const int g = 4 * wave + h;
;             AG[((g * 2 + dir) * 2 + 0) * 64 + j] = Aq; AG[((g * 2 + dir) * 2 + 1) * 64 + j] = Bq; } }
	v_mul_f32_e32 v22, v34, v22
	v_cndmask_b32_e64 v22, v22, 0, vcc
	v_cvt_pk_bf16_f32 v33, v22, 0
	v_lshl_add_u64 v[22:23], v[60:61], 0, v[30:31]
	v_lshlrev_b64 v[22:23], 1, v[22:23]
	v_mul_f32_e32 v20, 0xc1000000, v20
	v_lshl_add_u64 v[26:27], s[52:53], 0, v[22:23]
	v_lshl_add_u64 v[22:23], s[42:43], 0, v[22:23]
	v_mul_f32_e32 v20, v20, v29
	global_store_short v[22:23], v33, off
	v_add_f32_e32 v22, v20, v20
	v_mul_f32_e32 v22, 0x3fb8aa3b, v22
	v_exp_f32_e32 v22, v22
	v_cvt_pk_bf16_f32 v21, v21, 0
	global_store_short v[26:27], v21, off
	v_lshlrev_b32_e32 v21, 16, v21
	v_sub_f32_e32 v22, 1.0, v22
	v_max_f32_e32 v22, 0, v22
	v_add_f32_e32 v23, v24, v57
	v_mul_f32_e32 v24, 0x4f800000, v22
	v_cmp_gt_f32_e64 s[40:41], s88, v22
	v_mul_f32_e32 v21, 0x3fb8aa3b, v21
	v_mul_f32_e32 v23, 0xbfb8aa3b, v23
	v_cndmask_b32_e64 v22, v22, v24, s[40:41]
	v_exp_f32_e32 v21, v21
	v_exp_f32_e32 v23, v23
	v_sqrt_f32_e32 v24, v22
	v_lshlrev_b32_e32 v26, 16, v33
	v_fmac_f32_e32 v26, v21, v35
	v_mul_f32_e32 v27, v21, v32
	v_add_f32_e32 v21, 1.0, v23
	v_add_u32_e32 v23, -1, v24
	v_fma_f32 v29, -v23, v24, v22
	v_cmp_ge_f32_e64 s[46:47], 0, v29
	v_add_u32_e32 v29, 1, v24
	v_rcp_f32_e32 v21, v21
	v_cndmask_b32_e64 v23, v24, v23, s[46:47]
	v_fma_f32 v24, -v29, v24, v22
	v_cmp_lt_f32_e64 s[46:47], 0, v24
	v_cndmask_b32_e64 v20, v20, 0, vcc
	v_mul_f32_e32 v12, 0xbfb8aa3b, v12
	v_cndmask_b32_e64 v23, v23, v29, s[46:47]
	v_mul_f32_e32 v24, 0x37800000, v23
	v_cndmask_b32_e64 v23, v23, v24, s[40:41]
	v_cmp_class_f32_e64 s[40:41], v22, v209
	v_cvt_pk_bf16_f32 v24, v20, 0
	v_exp_f32_e32 v12, v12
	v_cndmask_b32_e64 v22, v23, v22, s[40:41]
	v_mul_f32_e32 v21, v21, v22
	s_waitcnt lgkmcnt(0)
	v_mul_f32_e32 v21, v25, v21
	v_cndmask_b32_e64 v21, v21, 0, vcc
	v_cvt_pk_bf16_f32 v25, v21, 0
	v_lshl_add_u64 v[20:21], v[0:1], 0, v[30:31]
	v_lshlrev_b64 v[20:21], 1, v[20:21]
	v_lshl_add_u64 v[22:23], s[52:53], 0, v[20:21]
	global_store_short v[22:23], v24, off
	v_lshlrev_b32_e32 v22, 16, v24
	v_mul_f32_e32 v22, 0x3fb8aa3b, v22
	v_exp_f32_e32 v22, v22
	v_lshl_add_u64 v[20:21], s[42:43], 0, v[20:21]
	global_store_short v[20:21], v25, off
	v_lshlrev_b32_e32 v20, 16, v25
	v_fmac_f32_e32 v20, v22, v26
	v_mul_f32_e32 v21, v22, v27
	v_mul_f32_e32 v22, 0xbfb8aa3b, v58
	v_fma_f32 v23, v58, s9, -v22
	v_rndne_f32_e32 v24, v22
	v_fmac_f32_e32 v23, 0xb2a5705f, v58
	v_sub_f32_e32 v22, v22, v24
	v_add_f32_e32 v22, v22, v23
	v_exp_f32_e32 v22, v22
	v_cvt_i32_f32_e32 v23, v24
	v_add3_u32 v24, s90, v28, v74
	ds_write2st64_b32 v24, v21, v20 offset0:2 offset1:3
	v_cmp_nlt_f32_e64 s[40:41], s11, v58
	v_ldexp_f32 v20, v22, v23
	v_add_f32_e32 v12, 1.0, v12
	v_cndmask_b32_e64 v20, 0, v20, s[40:41]
	v_cmp_ngt_f32_e64 s[40:41], s14, v58
	v_rcp_f32_e32 v12, v12
	s_waitcnt vmcnt(32)
	v_add_f32_e32 v16, v16, v53
	v_cndmask_b32_e64 v35, v213, v20, s[40:41]
	v_add_f32_e32 v22, 1.0, v35
	v_add_f32_e32 v20, -1.0, v22
	v_sub_f32_e32 v21, v20, v22
	v_add_f32_e32 v21, 1.0, v21
	v_sub_f32_e32 v20, v35, v20
	v_add_f32_e32 v23, v20, v21
	v_frexp_mant_f32_e32 v24, v22
	v_cvt_f64_f32_e32 v[20:21], v22
	v_frexp_exp_i32_f64_e32 v20, v[20:21]
	v_cmp_gt_f32_e64 s[40:41], s12, v24
	v_mul_f32_e32 v12, 0xc1000000, v12
	v_mul_f32_e32 v16, 0xbfb8aa3b, v16
	v_subbrev_co_u32_e64 v28, s[40:41], 0, v20, s[40:41]
	v_sub_u32_e32 v20, 0, v28
	v_ldexp_f32 v21, v22, v20
	v_add_f32_e32 v22, -1.0, v21
	v_add_f32_e32 v24, 1.0, v21
	v_ldexp_f32 v20, v23, v20
	v_add_f32_e32 v23, 1.0, v22
	v_add_f32_e32 v25, -1.0, v24
	v_sub_f32_e32 v23, v21, v23
	v_sub_f32_e32 v21, v21, v25
	v_add_f32_e32 v23, v20, v23
	v_add_f32_e32 v20, v20, v21
	v_add_f32_e32 v29, v24, v20
	v_rcp_f32_e32 v31, v29
	v_sub_f32_e32 v21, v24, v29
	v_add_f32_e32 v30, v20, v21
	v_add_f32_e32 v21, v22, v23
	v_mul_f32_e32 v33, v21, v31
	v_sub_f32_e32 v20, v22, v21
	v_mul_f32_e32 v22, v29, v33
	v_fma_f32 v24, v33, v29, -v22
	v_fmac_f32_e32 v24, v33, v30
	v_add_f32_e32 v32, v23, v20
	v_add_f32_e32 v20, v22, v24
	v_sub_f32_e32 v23, v21, v20
	v_pk_add_f32 v[26:27], v[20:21], v[22:23] neg_lo:[0,1] neg_hi:[0,1]
	v_mov_b32_e32 v25, v20
	v_pk_add_f32 v[20:21], v[26:27], v[24:25] neg_lo:[0,1] neg_hi:[0,1]
	v_cmp_neq_f32_e64 s[40:41], s92, v35
	v_add_f32_e32 v21, v32, v21
	v_add_f32_e32 v20, v20, v21
	v_add_f32_e32 v21, v23, v20
	v_mul_f32_e32 v32, v31, v21
	v_mul_f32_e32 v22, v29, v32
	v_fma_f32 v24, v32, v29, -v22
	v_fmac_f32_e32 v24, v32, v30
	v_sub_f32_e32 v23, v23, v21
	v_add_f32_e32 v29, v20, v23
	v_add_f32_e32 v20, v22, v24
	v_sub_f32_e32 v23, v21, v20
	v_pk_add_f32 v[26:27], v[20:21], v[22:23] neg_lo:[0,1] neg_hi:[0,1]
	v_mov_b32_e32 v25, v20
	v_pk_add_f32 v[20:21], v[26:27], v[24:25] neg_lo:[0,1] neg_hi:[0,1]
	v_or_b32_e32 v34, s29, v75
	v_add_f32_e32 v21, v29, v21
	v_add_f32_e32 v20, v20, v21
	v_add_f32_e32 v21, v33, v32
	v_add_f32_e32 v20, v23, v20
	v_sub_f32_e32 v22, v21, v33
	v_mul_f32_e32 v20, v31, v20
	v_sub_f32_e32 v22, v32, v22
	v_add_f32_e32 v22, v22, v20
	v_add_f32_e32 v24, v21, v22
	v_mul_f32_e32 v25, v24, v24
	v_fmamk_f32 v20, v25, 0x3e9b6dac, v211
	v_fmaak_f32 v167, v25, v20, 0x3f2aaada
	v_cvt_f32_i32_e32 v20, v28
	v_sub_f32_e32 v21, v24, v21
	v_sub_f32_e32 v21, v22, v21
	v_ldexp_f32 v26, v21, 1
	v_mul_f32_e32 v21, v24, v25
	v_ldexp_f32 v23, v24, 1
	v_pk_mul_f32 v[24:25], v[20:21], v[166:167]
	v_add_f32_e32 v17, v17, v53
	v_fma_f32 v22, v20, s84, -v24
	v_fmac_f32_e32 v22, 0xb102e308, v20
	v_pk_add_f32 v[20:21], v[24:25], v[22:23]
	v_mul_f32_e32 v17, 0xbfb8aa3b, v17
	v_sub_f32_e32 v23, v21, v23
	v_sub_f32_e32 v23, v25, v23
	v_add_f32_e32 v27, v26, v23
	v_mov_b32_e32 v26, v24
	v_pk_add_f32 v[24:25], v[20:21], v[24:25] neg_lo:[0,1] neg_hi:[0,1]
	v_pk_add_f32 v[28:29], v[20:21], v[26:27]
; __device__ __forceinline__ unsigned f2bf(float f) { return pk2(f, 0.f) & 0xffffu; }
; __device__ __forceinline__ float sigm(float x) { return __builtin_amdgcn_rcpf(1.0f + __expf(-x)); }
; #define p (*kparams())
; __device__ __forceinline__ void lru_s1_item(CParams& p, int layer, int item, LAS unsigned char* lds) {
;     ...
;     for (int jt = 0; jt < 4; ++jt) { const int j = 16 * jt + r, ch = kb * 64 + j;
; #pragma unroll
;         for (int dir = 0; dir < 2; ++dir) {
;             const float ba = p.in[8][(layer * 2 + dir) * W + ch], bx = p.in[10][(layer * 2 + dir) * W + ch], lam = p.in[11][(layer * 2 + dir) * W + ch];
;             const float sp = log1pf(expf(-lam));
;             float Aq = 1.f, Bq = 0.f;
; #pragma unroll
;             for (int s = 0; s < 4; ++s) { const int q = dir ? 3 - s : s;
;                 const float rg = sigm(acc[(2 * dir) * 4 + jt][q] + ba), ig = sigm(acc[(2 * dir + 1) * 4 + jt][q] + bx);
;                 float la = -8.0f * rg * sp; float bv = sqrtf(fmaxf(1.0f - __expf(2.0f * la), 0.f)) * ig * XCf[(tok0 + q) * 64 + j];
;                 if ((t0 + q) < 0) { la = 0.f; bv = 0.f; }
;                 const unsigned lab = f2bf(la), bvb = f2bf(bv);
;                 const size_t ro = (size_t)row_bci(b, c, tok0 + q) * W + ch;
;                 LA[(size_t)dir * MP * W + ro] = (bf16_t)lab; BB[(size_t)dir * MP * W + ro] = (bf16_t)bvb;
;                 const float a = __expf(__uint_as_float(lab << 16)), bq = __uint_as_float(bvb << 16);
;                 Bq = a * Bq + bq; Aq *= a; }
;             const int g = 4 * wave + h;
;             AG[((g * 2 + dir) * 2 + 0) * 64 + j] = Aq; AG[((g * 2 + dir) * 2 + 1) * 64 + j] = Bq; } }
	v_mov_b32_e32 v23, v20
	v_mov_b32_e32 v25, v29
	v_pk_add_f32 v[30:31], v[22:23], v[24:25] neg_lo:[0,1] neg_hi:[0,1]
	v_pk_add_f32 v[22:23], v[22:23], v[24:25]
	v_mov_b32_e32 v26, v27
	v_pk_add_f32 v[24:25], v[22:23], v[20:21] op_sel:[1,0] op_sel_hi:[0,1] neg_lo:[0,1] neg_hi:[0,1]
	v_pk_add_f32 v[32:33], v[28:29], v[24:25] op_sel_hi:[1,0] neg_lo:[0,1] neg_hi:[0,1]
	v_mov_b32_e32 v28, v29
	v_mov_b32_e32 v29, v23
	v_pk_mov_b32 v[24:25], v[20:21], v[24:25] op_sel:[1,0]
	v_mov_b32_e32 v27, v20
	v_pk_add_f32 v[24:25], v[28:29], v[24:25] neg_lo:[0,1] neg_hi:[0,1]
	v_mov_b32_e32 v32, v30
	v_pk_add_f32 v[20:21], v[26:27], v[24:25] neg_lo:[0,1] neg_hi:[0,1]
	v_mov_b32_e32 v31, v23
	v_pk_add_f32 v[24:25], v[32:33], v[20:21]
	v_exp_f32_e32 v17, v17
	v_pk_add_f32 v[26:27], v[24:25], v[24:25] op_sel:[0,1] op_sel_hi:[1,0]
	v_add_f32_e32 v14, v14, v52
	v_pk_add_f32 v[22:23], v[22:23], v[26:27] op_sel:[1,0] op_sel_hi:[0,1]
	v_mov_b32_e32 v25, v22
	v_pk_add_f32 v[28:29], v[24:25], v[30:31] neg_lo:[0,1] neg_hi:[0,1]
	v_mov_b32_e32 v21, v26
	v_sub_f32_e32 v23, v24, v28
	v_pk_add_f32 v[20:21], v[20:21], v[28:29] neg_lo:[0,1] neg_hi:[0,1]
	v_sub_f32_e32 v23, v30, v23
	v_add_f32_e32 v20, v20, v23
	v_add_f32_e32 v20, v20, v21
	v_add_f32_e32 v20, v22, v20
	v_cndmask_b32_e64 v20, v213, v20, s[40:41]
	v_cmp_lt_f32_e64 s[40:41], |v35|, s85
	v_exp_f32_e32 v21, v16
	v_add_f32_e32 v17, 1.0, v17
	v_cndmask_b32_e64 v24, v20, v35, s[40:41]
	v_mul_f32_e32 v12, v12, v24
	v_add_f32_e32 v20, v12, v12
	v_mul_f32_e32 v20, 0x3fb8aa3b, v20
	v_exp_f32_e32 v20, v20
	v_add_f32_e32 v21, 1.0, v21
	v_rcp_f32_e32 v21, v21
	v_cndmask_b32_e64 v12, v12, 0, vcc
	v_sub_f32_e32 v16, 1.0, v20
	v_max_f32_e32 v16, 0, v16
	v_mul_f32_e32 v20, 0x4f800000, v16
	v_cmp_gt_f32_e64 s[40:41], s88, v16
	v_cvt_pk_bf16_f32 v28, v12, 0
	v_add_f32_e32 v12, v13, v52
	v_cndmask_b32_e64 v20, v16, v20, s[40:41]
	v_sqrt_f32_e32 v22, v20
	v_mul_f32_e32 v12, 0xbfb8aa3b, v12
	v_rcp_f32_e32 v17, v17
	v_mul_f32_e32 v14, 0xbfb8aa3b, v14
	v_add_u32_e32 v23, -1, v22
	v_fma_f32 v25, -v23, v22, v20
	v_cmp_ge_f32_e64 s[46:47], 0, v25
	v_add_u32_e32 v25, 1, v22
	v_exp_f32_e32 v14, v14
	v_cndmask_b32_e64 v23, v22, v23, s[46:47]
	v_fma_f32 v22, -v25, v22, v20
	v_cmp_lt_f32_e64 s[46:47], 0, v22
	v_add_f32_e32 v14, 1.0, v14
	v_rcp_f32_e32 v14, v14
	v_cndmask_b32_e64 v22, v23, v25, s[46:47]
	v_mul_f32_e32 v23, 0x37800000, v22
	v_cndmask_b32_e64 v22, v22, v23, s[40:41]
	v_cmp_class_f32_e64 s[40:41], v20, v209
	v_add_f32_e32 v15, v15, v52
	v_mul_f32_e32 v15, 0xbfb8aa3b, v15
	v_cndmask_b32_e64 v20, v22, v20, s[40:41]
	ds_read_b32 v22, v68 offset:55488
	v_mul_f32_e32 v20, v21, v20
	v_mov_b32_e32 v21, v1
	ds_read_b32 v25, v69 offset:55488
	ds_read_b32 v26, v70 offset:55488
	ds_read_b32 v27, v71 offset:55488
	v_exp_f32_e32 v15, v15
	s_waitcnt lgkmcnt(3)
	v_mul_f32_e32 v20, v22, v20
	v_cndmask_b32_e64 v20, v20, 0, vcc
	v_cvt_pk_bf16_f32 v29, v20, 0
	v_or_b32_e32 v20, v0, v34
	v_lshlrev_b64 v[20:21], 1, v[20:21]
	v_lshl_add_u64 v[22:23], s[52:53], 0, v[20:21]
	global_store_short v[22:23], v28, off
	v_exp_f32_e32 v22, v12
	v_lshl_add_u64 v[12:13], s[42:43], 0, v[20:21]
	global_store_short v[12:13], v29, off
	v_lshlrev_b32_e32 v12, 16, v28
	v_add_f32_e32 v13, 1.0, v22
	v_rcp_f32_e32 v13, v13
	v_mul_f32_e32 v12, 0x3fb8aa3b, v12
	v_exp_f32_e32 v22, v12
	v_add_f32_e32 v15, 1.0, v15
	v_mul_f32_e32 v12, 0xc1000000, v13
	v_mul_f32_e32 v12, v12, v24
	v_add_f32_e32 v13, v12, v12
	v_mul_f32_e32 v13, 0x3fb8aa3b, v13
	v_exp_f32_e32 v13, v13
	v_cndmask_b32_e64 v12, v12, 0, vcc
	v_rcp_f32_e32 v15, v15
	v_lshlrev_b32_e32 v23, 16, v29
	v_sub_f32_e32 v13, 1.0, v13
	v_max_f32_e32 v13, 0, v13
	v_mul_f32_e32 v20, 0x4f800000, v13
	v_cmp_gt_f32_e64 s[40:41], s88, v13
	v_fmac_f32_e32 v23, 0, v22
	v_lshlrev_b32_e32 v16, 2, v75
	v_cndmask_b32_e64 v13, v13, v20, s[40:41]
	v_sqrt_f32_e32 v20, v13
	v_add_f32_e32 v7, v7, v54
	v_mul_f32_e32 v7, 0xbfb8aa3b, v7
	v_exp_f32_e32 v7, v7
	v_add_u32_e32 v21, -1, v20
	v_fma_f32 v28, -v21, v20, v13
	v_cmp_ge_f32_e64 s[46:47], 0, v28
	v_add_u32_e32 v28, 1, v20
	v_add_f32_e32 v7, 1.0, v7
	v_cndmask_b32_e64 v21, v20, v21, s[46:47]
	v_fma_f32 v20, -v28, v20, v13
	v_cmp_lt_f32_e64 s[46:47], 0, v20
	v_rcp_f32_e32 v7, v7
	v_add_f32_e32 v11, v11, v44
	v_cndmask_b32_e64 v20, v21, v28, s[46:47]
	v_mul_f32_e32 v21, 0x37800000, v20
	v_cndmask_b32_e64 v20, v20, v21, s[40:41]
	v_cmp_class_f32_e64 s[40:41], v13, v209
	v_mul_f32_e32 v7, 0xc1000000, v7
	v_mul_f32_e32 v11, 0xbfb8aa3b, v11
	v_cndmask_b32_e64 v13, v20, v13, s[40:41]
	v_mul_f32_e32 v13, v17, v13
	s_waitcnt lgkmcnt(2)
	v_mul_f32_e32 v13, v25, v13
	v_cndmask_b32_e64 v13, v13, 0, vcc
	v_cvt_pk_bf16_f32 v17, v12, 0
	v_cvt_pk_bf16_f32 v25, v13, 0
	v_or_b32_e32 v12, v60, v34
	v_mov_b32_e32 v13, v61
	v_lshlrev_b64 v[12:13], 1, v[12:13]
	v_lshl_add_u64 v[20:21], s[52:53], 0, v[12:13]
	v_lshl_add_u64 v[12:13], s[42:43], 0, v[12:13]
	global_store_short v[12:13], v25, off
	v_mul_f32_e32 v12, 0xc1000000, v14
	v_mul_f32_e32 v12, v12, v24
	v_add_f32_e32 v13, v12, v12
	v_mul_f32_e32 v13, 0x3fb8aa3b, v13
	v_exp_f32_e32 v13, v13
	v_add_f32_e32 v14, v18, v53
	v_mul_f32_e32 v14, 0xbfb8aa3b, v14
	global_store_short v[20:21], v17, off
	v_sub_f32_e32 v13, 1.0, v13
	v_max_f32_e32 v13, 0, v13
	v_mul_f32_e32 v18, 0x4f800000, v13
	v_cmp_gt_f32_e64 s[40:41], s88, v13
	v_exp_f32_e32 v14, v14
	v_cndmask_b32_e64 v12, v12, 0, vcc
	v_cndmask_b32_e64 v13, v13, v18, s[40:41]
	v_sqrt_f32_e32 v18, v13
	v_add_f32_e32 v14, 1.0, v14
	v_rcp_f32_e32 v14, v14
	v_lshlrev_b32_e32 v17, 16, v17
	v_add_u32_e32 v20, -1, v18
	v_fma_f32 v21, -v20, v18, v13
	v_cmp_ge_f32_e64 s[46:47], 0, v21
	v_add_u32_e32 v21, 1, v18
	v_mul_f32_e32 v17, 0x3fb8aa3b, v17
	v_cndmask_b32_e64 v20, v18, v20, s[46:47]
	v_fma_f32 v18, -v21, v18, v13
	v_cmp_lt_f32_e64 s[46:47], 0, v18
	v_exp_f32_e32 v17, v17
	v_lshlrev_b32_e32 v25, 16, v25
	v_cndmask_b32_e64 v18, v20, v21, s[46:47]
	v_mul_f32_e32 v20, 0x37800000, v18
	v_cndmask_b32_e64 v18, v18, v20, s[40:41]
	v_cmp_class_f32_e64 s[40:41], v13, v209
	v_fmac_f32_e32 v25, v17, v23
	v_mul_f32_e32 v17, v22, v17
	v_cndmask_b32_e64 v13, v18, v13, s[40:41]
	v_mul_f32_e32 v13, v14, v13
	s_waitcnt lgkmcnt(1)
; __device__ __forceinline__ unsigned f2bf(float f) { return pk2(f, 0.f) & 0xffffu; }
; __device__ __forceinline__ float sigm(float x) { return __builtin_amdgcn_rcpf(1.0f + __expf(-x)); }
; #define p (*kparams())
; __device__ __forceinline__ void lru_s1_item(CParams& p, int layer, int item, LAS unsigned char* lds) {
;     ...
;     for (int jt = 0; jt < 4; ++jt) { const int j = 16 * jt + r, ch = kb * 64 + j;
; #pragma unroll
;         for (int dir = 0; dir < 2; ++dir) {
;             const float ba = p.in[8][(layer * 2 + dir) * W + ch], bx = p.in[10][(layer * 2 + dir) * W + ch], lam = p.in[11][(layer * 2 + dir) * W + ch];
;             const float sp = log1pf(expf(-lam));
;             float Aq = 1.f, Bq = 0.f;
; #pragma unroll
;             for (int s = 0; s < 4; ++s) { const int q = dir ? 3 - s : s;
;                 const float rg = sigm(acc[(2 * dir) * 4 + jt][q] + ba), ig = sigm(acc[(2 * dir + 1) * 4 + jt][q] + bx);
;                 float la = -8.0f * rg * sp; float bv = sqrtf(fmaxf(1.0f - __expf(2.0f * la), 0.f)) * ig * XCf[(tok0 + q) * 64 + j];
;                 if ((t0 + q) < 0) { la = 0.f; bv = 0.f; }
;                 const unsigned lab = f2bf(la), bvb = f2bf(bv);
;                 const size_t ro = (size_t)row_bci(b, c, tok0 + q) * W + ch;
;                 LA[(size_t)dir * MP * W + ro] = (bf16_t)lab; BB[(size_t)dir * MP * W + ro] = (bf16_t)bvb;
;                 const float a = __expf(__uint_as_float(lab << 16)), bq = __uint_as_float(bvb << 16);
;                 Bq = a * Bq + bq; Aq *= a; }
;             const int g = 4 * wave + h;
;             AG[((g * 2 + dir) * 2 + 0) * 64 + j] = Aq; AG[((g * 2 + dir) * 2 + 1) * 64 + j] = Bq; } }
	v_mul_f32_e32 v13, v26, v13
	v_cndmask_b32_e64 v13, v13, 0, vcc
	v_cvt_pk_bf16_f32 v14, v12, 0
	v_cvt_pk_bf16_f32 v18, v13, 0
	v_or_b32_e32 v12, v64, v34
	v_mov_b32_e32 v13, v65
	v_lshlrev_b64 v[12:13], 1, v[12:13]
	v_lshl_add_u64 v[20:21], s[52:53], 0, v[12:13]
	v_lshl_add_u64 v[12:13], s[42:43], 0, v[12:13]
	global_store_short v[12:13], v18, off
	v_mul_f32_e32 v12, 0xc1000000, v15
	v_mul_f32_e32 v12, v12, v24
	v_add_f32_e32 v13, v12, v12
	v_mul_f32_e32 v13, 0x3fb8aa3b, v13
	v_exp_f32_e32 v13, v13
	global_store_short v[20:21], v14, off
	v_lshlrev_b32_e32 v14, 16, v14
	v_add_f32_e32 v15, v19, v53
	v_sub_f32_e32 v13, 1.0, v13
	v_max_f32_e32 v13, 0, v13
	v_mul_f32_e32 v19, 0x4f800000, v13
	v_cmp_gt_f32_e64 s[40:41], s88, v13
	v_mul_f32_e32 v14, 0x3fb8aa3b, v14
	v_mul_f32_e32 v15, 0xbfb8aa3b, v15
	v_cndmask_b32_e64 v13, v13, v19, s[40:41]
	v_exp_f32_e32 v14, v14
	v_exp_f32_e32 v15, v15
	v_sqrt_f32_e32 v19, v13
	v_lshlrev_b32_e32 v18, 16, v18
	v_fmac_f32_e32 v18, v14, v25
	v_mul_f32_e32 v17, v14, v17
	v_add_f32_e32 v14, 1.0, v15
	v_add_u32_e32 v15, -1, v19
	v_fma_f32 v20, -v15, v19, v13
	v_cmp_ge_f32_e64 s[46:47], 0, v20
	v_add_u32_e32 v20, 1, v19
	v_rcp_f32_e32 v14, v14
	v_cndmask_b32_e64 v15, v19, v15, s[46:47]
	v_fma_f32 v19, -v20, v19, v13
	v_cmp_lt_f32_e64 s[46:47], 0, v19
	v_cndmask_b32_e64 v12, v12, 0, vcc
	v_exp_f32_e32 v11, v11
	v_cndmask_b32_e64 v15, v15, v20, s[46:47]
	v_mul_f32_e32 v19, 0x37800000, v15
	v_cndmask_b32_e64 v15, v15, v19, s[40:41]
	v_cmp_class_f32_e64 s[40:41], v13, v209
	v_cvt_pk_bf16_f32 v19, v12, 0
	v_or_b32_e32 v12, v62, v34
	v_cndmask_b32_e64 v13, v15, v13, s[40:41]
	v_mul_f32_e32 v13, v14, v13
	s_waitcnt lgkmcnt(0)
	v_mul_f32_e32 v13, v27, v13
	v_cndmask_b32_e64 v13, v13, 0, vcc
	v_cvt_pk_bf16_f32 v20, v13, 0
	v_mov_b32_e32 v13, v63
	v_lshlrev_b64 v[12:13], 1, v[12:13]
	v_lshl_add_u64 v[14:15], s[52:53], 0, v[12:13]
	global_store_short v[14:15], v19, off
	v_lshlrev_b32_e32 v14, 16, v19
	v_mul_f32_e32 v14, 0x3fb8aa3b, v14
	v_exp_f32_e32 v14, v14
	v_lshl_add_u64 v[12:13], s[42:43], 0, v[12:13]
	global_store_short v[12:13], v20, off
	v_lshlrev_b32_e32 v12, 16, v20
	v_mul_f32_e32 v13, 0xbfb8aa3b, v80
	v_fmac_f32_e32 v12, v14, v18
	v_fma_f32 v15, v80, s9, -v13
	v_rndne_f32_e32 v18, v13
	v_fmac_f32_e32 v15, 0xb2a5705f, v80
	v_sub_f32_e32 v13, v13, v18
	v_add_f32_e32 v13, v13, v15
	v_exp_f32_e32 v13, v13
	v_cvt_i32_f32_e32 v15, v18
	v_mul_f32_e32 v14, v14, v17
	v_add_u32_e32 v17, v76, v16
	ds_write2st64_b32 v17, v14, v12 offset1:1
	v_ldexp_f32 v12, v13, v15
	v_cmp_nlt_f32_e64 s[40:41], s11, v80
	v_add_f32_e32 v11, 1.0, v11
	v_rcp_f32_e32 v11, v11
	v_cndmask_b32_e64 v12, 0, v12, s[40:41]
	v_cmp_ngt_f32_e64 s[40:41], s14, v80
	v_add_f32_e32 v6, v6, v54
	v_mul_f32_e32 v6, 0xbfb8aa3b, v6
	v_cndmask_b32_e64 v17, v213, v12, s[40:41]
	v_add_f32_e32 v14, 1.0, v17
	v_add_f32_e32 v12, -1.0, v14
	v_sub_f32_e32 v13, v12, v14
	v_add_f32_e32 v13, 1.0, v13
	v_sub_f32_e32 v12, v17, v12
	v_add_f32_e32 v15, v12, v13
	v_frexp_mant_f32_e32 v18, v14
	v_cvt_f64_f32_e32 v[12:13], v14
	v_frexp_exp_i32_f64_e32 v12, v[12:13]
	v_cmp_gt_f32_e64 s[40:41], s12, v18
	v_add_f32_e32 v10, v10, v44
	v_mul_f32_e32 v10, 0xbfb8aa3b, v10
	v_subbrev_co_u32_e64 v22, s[40:41], 0, v12, s[40:41]
	v_sub_u32_e32 v12, 0, v22
	v_ldexp_f32 v13, v14, v12
	v_add_f32_e32 v14, -1.0, v13
	v_add_f32_e32 v18, 1.0, v13
	v_ldexp_f32 v12, v15, v12
	v_add_f32_e32 v15, 1.0, v14
	v_add_f32_e32 v19, -1.0, v18
	v_sub_f32_e32 v15, v13, v15
	v_sub_f32_e32 v13, v13, v19
	v_add_f32_e32 v15, v12, v15
	v_add_f32_e32 v12, v12, v13
	v_add_f32_e32 v23, v18, v12
	v_rcp_f32_e32 v25, v23
	v_sub_f32_e32 v13, v18, v23
	v_add_f32_e32 v24, v12, v13
	v_add_f32_e32 v13, v14, v15
	v_mul_f32_e32 v27, v13, v25
	v_sub_f32_e32 v12, v14, v13
	v_mul_f32_e32 v14, v23, v27
	v_fma_f32 v18, v27, v23, -v14
	v_fmac_f32_e32 v18, v27, v24
	v_add_f32_e32 v26, v15, v12
	v_add_f32_e32 v12, v14, v18
	v_sub_f32_e32 v15, v13, v12
	v_pk_add_f32 v[20:21], v[12:13], v[14:15] neg_lo:[0,1] neg_hi:[0,1]
	v_mov_b32_e32 v19, v12
	v_pk_add_f32 v[12:13], v[20:21], v[18:19] neg_lo:[0,1] neg_hi:[0,1]
	v_cmp_neq_f32_e64 s[40:41], s92, v17
	v_add_f32_e32 v13, v26, v13
	v_add_f32_e32 v12, v12, v13
	v_add_f32_e32 v13, v15, v12
	v_mul_f32_e32 v26, v25, v13
	v_mul_f32_e32 v14, v23, v26
	v_fma_f32 v18, v26, v23, -v14
	v_fmac_f32_e32 v18, v26, v24
	v_sub_f32_e32 v15, v15, v13
	v_add_f32_e32 v23, v12, v15
	v_add_f32_e32 v12, v14, v18
	v_sub_f32_e32 v15, v13, v12
	v_pk_add_f32 v[20:21], v[12:13], v[14:15] neg_lo:[0,1] neg_hi:[0,1]
	v_mov_b32_e32 v19, v12
	v_pk_add_f32 v[12:13], v[20:21], v[18:19] neg_lo:[0,1] neg_hi:[0,1]
	v_exp_f32_e32 v10, v10
	v_add_f32_e32 v13, v23, v13
	v_add_f32_e32 v12, v12, v13
	v_add_f32_e32 v13, v27, v26
	v_add_f32_e32 v12, v15, v12
	v_sub_f32_e32 v14, v13, v27
	v_mul_f32_e32 v12, v25, v12
	v_sub_f32_e32 v14, v26, v14
	v_add_f32_e32 v14, v14, v12
	v_add_f32_e32 v18, v13, v14
	v_mul_f32_e32 v19, v18, v18
	v_fmamk_f32 v12, v19, 0x3e9b6dac, v211
	v_fmaak_f32 v167, v19, v12, 0x3f2aaada
	v_cvt_f32_i32_e32 v12, v22
	v_sub_f32_e32 v13, v18, v13
	v_sub_f32_e32 v13, v14, v13
	v_ldexp_f32 v20, v13, 1
	v_mul_f32_e32 v13, v18, v19
	v_ldexp_f32 v15, v18, 1
	v_pk_mul_f32 v[18:19], v[12:13], v[166:167]
	v_add_f32_e32 v5, v5, v54
	v_fma_f32 v14, v12, s84, -v18
	v_fmac_f32_e32 v14, 0xb102e308, v12
	v_pk_add_f32 v[12:13], v[18:19], v[14:15]
	v_mul_f32_e32 v5, 0xbfb8aa3b, v5
	v_sub_f32_e32 v15, v13, v15
	v_sub_f32_e32 v15, v19, v15
	v_add_f32_e32 v21, v20, v15
	v_mov_b32_e32 v20, v18
	v_pk_add_f32 v[18:19], v[12:13], v[18:19] neg_lo:[0,1] neg_hi:[0,1]
	v_pk_add_f32 v[22:23], v[12:13], v[20:21]
	v_mov_b32_e32 v15, v12
; __device__ __forceinline__ unsigned f2bf(float f) { return pk2(f, 0.f) & 0xffffu; }
; __device__ __forceinline__ float sigm(float x) { return __builtin_amdgcn_rcpf(1.0f + __expf(-x)); }
; #define p (*kparams())
; __device__ __forceinline__ void lru_s1_item(CParams& p, int layer, int item, LAS unsigned char* lds) {
;     ...
;     for (int jt = 0; jt < 4; ++jt) { const int j = 16 * jt + r, ch = kb * 64 + j;
; #pragma unroll
;         for (int dir = 0; dir < 2; ++dir) {
;             const float ba = p.in[8][(layer * 2 + dir) * W + ch], bx = p.in[10][(layer * 2 + dir) * W + ch], lam = p.in[11][(layer * 2 + dir) * W + ch];
;             const float sp = log1pf(expf(-lam));
;             float Aq = 1.f, Bq = 0.f;
; #pragma unroll
;             for (int s = 0; s < 4; ++s) { const int q = dir ? 3 - s : s;
;                 const float rg = sigm(acc[(2 * dir) * 4 + jt][q] + ba), ig = sigm(acc[(2 * dir + 1) * 4 + jt][q] + bx);
;                 float la = -8.0f * rg * sp; float bv = sqrtf(fmaxf(1.0f - __expf(2.0f * la), 0.f)) * ig * XCf[(tok0 + q) * 64 + j];
;                 if ((t0 + q) < 0) { la = 0.f; bv = 0.f; }
;                 const unsigned lab = f2bf(la), bvb = f2bf(bv);
;                 const size_t ro = (size_t)row_bci(b, c, tok0 + q) * W + ch;
;                 LA[(size_t)dir * MP * W + ro] = (bf16_t)lab; BB[(size_t)dir * MP * W + ro] = (bf16_t)bvb;
;                 const float a = __expf(__uint_as_float(lab << 16)), bq = __uint_as_float(bvb << 16);
;                 Bq = a * Bq + bq; Aq *= a; }
;             const int g = 4 * wave + h;
;             AG[((g * 2 + dir) * 2 + 0) * 64 + j] = Aq; AG[((g * 2 + dir) * 2 + 1) * 64 + j] = Bq; } }
	v_mov_b32_e32 v19, v23
	v_pk_add_f32 v[24:25], v[14:15], v[18:19] neg_lo:[0,1] neg_hi:[0,1]
	v_pk_add_f32 v[14:15], v[14:15], v[18:19]
	v_mov_b32_e32 v20, v21
	v_pk_add_f32 v[18:19], v[14:15], v[12:13] op_sel:[1,0] op_sel_hi:[0,1] neg_lo:[0,1] neg_hi:[0,1]
	v_pk_add_f32 v[26:27], v[22:23], v[18:19] op_sel_hi:[1,0] neg_lo:[0,1] neg_hi:[0,1]
	v_mov_b32_e32 v22, v23
	v_mov_b32_e32 v23, v15
	v_pk_mov_b32 v[18:19], v[12:13], v[18:19] op_sel:[1,0]
	v_mov_b32_e32 v21, v12
	v_pk_add_f32 v[18:19], v[22:23], v[18:19] neg_lo:[0,1] neg_hi:[0,1]
	v_mov_b32_e32 v26, v24
	v_pk_add_f32 v[12:13], v[20:21], v[18:19] neg_lo:[0,1] neg_hi:[0,1]
	v_mov_b32_e32 v25, v15
	v_pk_add_f32 v[18:19], v[26:27], v[12:13]
	v_add_f32_e32 v10, 1.0, v10
	v_pk_add_f32 v[20:21], v[18:19], v[18:19] op_sel:[0,1] op_sel_hi:[1,0]
	v_exp_f32_e32 v5, v5
	v_pk_add_f32 v[14:15], v[14:15], v[20:21] op_sel:[1,0] op_sel_hi:[0,1]
	v_mov_b32_e32 v19, v14
	v_pk_add_f32 v[22:23], v[18:19], v[24:25] neg_lo:[0,1] neg_hi:[0,1]
	v_mov_b32_e32 v13, v20
	v_sub_f32_e32 v15, v18, v22
	v_pk_add_f32 v[12:13], v[12:13], v[22:23] neg_lo:[0,1] neg_hi:[0,1]
	v_sub_f32_e32 v15, v24, v15
	v_add_f32_e32 v12, v12, v15
	v_add_f32_e32 v12, v12, v13
	v_add_f32_e32 v12, v14, v12
	v_cndmask_b32_e64 v12, v213, v12, s[40:41]
	v_cmp_lt_f32_e64 s[40:41], |v17|, s85
	ds_read_b32 v20, v70 offset:55488
	v_rcp_f32_e32 v10, v10
	v_cndmask_b32_e64 v17, v12, v17, s[40:41]
	v_mul_f32_e32 v7, v7, v17
	v_add_f32_e32 v13, v7, v7
	v_mul_f32_e32 v13, 0x3fb8aa3b, v13
	v_exp_f32_e32 v13, v13
	v_or_b32_e32 v12, 0x820000, v34
	v_cndmask_b32_e64 v7, v7, 0, vcc
	v_cvt_pk_bf16_f32 v21, v7, 0
	v_sub_f32_e32 v13, 1.0, v13
	v_max_f32_e32 v13, 0, v13
	v_mul_f32_e32 v14, 0x4f800000, v13
	v_cmp_gt_f32_e64 s[40:41], s88, v13
	v_add_f32_e32 v5, 1.0, v5
	v_rcp_f32_e32 v5, v5
	v_cndmask_b32_e64 v14, v13, v14, s[40:41]
	v_sqrt_f32_e32 v15, v14
	v_mov_b32_e32 v13, v2
	v_mul_f32_e32 v5, 0xc1000000, v5
	v_mul_f32_e32 v5, v5, v17
	v_add_u32_e32 v18, -1, v15
	v_fma_f32 v19, -v18, v15, v14
	v_cmp_ge_f32_e64 s[46:47], 0, v19
	v_add_u32_e32 v19, 1, v15
	v_add_f32_e32 v4, v4, v54
	v_cndmask_b32_e64 v18, v15, v18, s[46:47]
	v_fma_f32 v15, -v19, v15, v14
	v_cmp_lt_f32_e64 s[46:47], 0, v15
	v_mul_f32_e32 v4, 0xbfb8aa3b, v4
	v_exp_f32_e32 v4, v4
	v_cndmask_b32_e64 v15, v18, v19, s[46:47]
	v_mul_f32_e32 v18, 0x37800000, v15
	v_cndmask_b32_e64 v15, v15, v18, s[40:41]
	ds_read_b32 v18, v71 offset:55488
	v_cmp_class_f32_e64 s[40:41], v14, v209
	v_add_f32_e32 v4, 1.0, v4
	v_rcp_f32_e32 v4, v4
	v_cndmask_b32_e64 v14, v15, v14, s[40:41]
	v_mul_f32_e32 v11, v11, v14
	v_lshl_add_u64 v[14:15], v[62:63], 0, v[12:13]
	v_lshlrev_b64 v[14:15], 1, v[14:15]
	s_waitcnt lgkmcnt(0)
	v_mul_f32_e32 v11, v18, v11
	v_lshl_add_u64 v[18:19], s[52:53], 0, v[14:15]
	global_store_short v[18:19], v21, off
	v_exp_f32_e32 v18, v6
	v_cndmask_b32_e64 v11, v11, 0, vcc
	v_cvt_pk_bf16_f32 v11, v11, 0
	v_lshl_add_u64 v[6:7], s[42:43], 0, v[14:15]
	global_store_short v[6:7], v11, off
	v_add_f32_e32 v7, 1.0, v18
	v_rcp_f32_e32 v7, v7
	v_lshlrev_b32_e32 v6, 16, v21
	v_mul_f32_e32 v6, 0x3fb8aa3b, v6
	v_exp_f32_e32 v14, v6
	v_mul_f32_e32 v6, 0xc1000000, v7
	v_mul_f32_e32 v6, v6, v17
	v_add_f32_e32 v7, v6, v6
	v_mul_f32_e32 v7, 0x3fb8aa3b, v7
	v_exp_f32_e32 v7, v7
	v_lshlrev_b32_e32 v15, 16, v11
	v_cndmask_b32_e64 v6, v6, 0, vcc
	v_fmac_f32_e32 v15, 0, v14
	v_sub_f32_e32 v7, 1.0, v7
	v_max_f32_e32 v7, 0, v7
	v_mul_f32_e32 v11, 0x4f800000, v7
	v_cmp_gt_f32_e64 s[40:41], s88, v7
	v_mul_f32_e32 v4, 0xc1000000, v4
	v_mul_f32_e32 v4, v4, v17
	v_cndmask_b32_e64 v7, v7, v11, s[40:41]
	v_sqrt_f32_e32 v11, v7
	v_add_f32_e32 v8, v8, v44
	v_mul_f32_e32 v8, 0xbfb8aa3b, v8
	v_exp_f32_e32 v8, v8
	v_add_u32_e32 v18, -1, v11
	v_fma_f32 v19, -v18, v11, v7
	v_cmp_ge_f32_e64 s[46:47], 0, v19
	v_add_u32_e32 v19, 1, v11
	v_lshl_add_u64 v[0:1], v[0:1], 0, v[12:13]
	v_cndmask_b32_e64 v18, v11, v18, s[46:47]
	v_fma_f32 v11, -v19, v11, v7
	v_cmp_lt_f32_e64 s[46:47], 0, v11
	v_lshlrev_b64 v[0:1], 1, v[0:1]
	s_nop 0
	v_cndmask_b32_e64 v11, v18, v19, s[46:47]
	v_mul_f32_e32 v18, 0x37800000, v11
	v_cndmask_b32_e64 v11, v11, v18, s[40:41]
	v_cmp_class_f32_e64 s[40:41], v7, v209
	ds_read_b32 v18, v69 offset:55488
	v_cvt_pk_bf16_f32 v19, v6, 0
	v_cndmask_b32_e64 v7, v11, v7, s[40:41]
	v_mul_f32_e32 v7, v10, v7
	v_mul_f32_e32 v7, v20, v7
	v_cndmask_b32_e64 v7, v7, 0, vcc
	v_cvt_pk_bf16_f32 v20, v7, 0
	v_lshl_add_u64 v[6:7], v[64:65], 0, v[12:13]
	v_lshlrev_b64 v[6:7], 1, v[6:7]
	v_lshl_add_u64 v[10:11], s[52:53], 0, v[6:7]
	v_lshl_add_u64 v[6:7], s[42:43], 0, v[6:7]
	global_store_short v[6:7], v20, off
	v_add_f32_e32 v6, v5, v5
	v_mul_f32_e32 v6, 0x3fb8aa3b, v6
	v_exp_f32_e32 v6, v6
	global_store_short v[10:11], v19, off
	v_lshlrev_b32_e32 v10, 16, v19
	v_add_f32_e32 v7, v9, v44
	v_sub_f32_e32 v6, 1.0, v6
	v_max_f32_e32 v6, 0, v6
	v_mul_f32_e32 v9, 0x4f800000, v6
	v_cmp_gt_f32_e64 s[40:41], s88, v6
	v_mul_f32_e32 v10, 0x3fb8aa3b, v10
	v_exp_f32_e32 v10, v10
	v_cndmask_b32_e64 v6, v6, v9, s[40:41]
	v_sqrt_f32_e32 v9, v6
	v_lshlrev_b32_e32 v19, 16, v20
	v_mul_f32_e32 v7, 0xbfb8aa3b, v7
	v_fmac_f32_e32 v19, v10, v15
	v_exp_f32_e32 v7, v7
	v_mul_f32_e32 v14, v14, v10
	v_add_u32_e32 v10, -1, v9
	v_fma_f32 v11, -v10, v9, v6
	v_cmp_ge_f32_e64 s[46:47], 0, v11
	v_add_u32_e32 v11, 1, v9
	v_add_f32_e32 v7, 1.0, v7
	v_cndmask_b32_e64 v10, v9, v10, s[46:47]
	v_fma_f32 v9, -v11, v9, v6
	v_cmp_lt_f32_e64 s[46:47], 0, v9
	v_rcp_f32_e32 v7, v7
	v_cndmask_b32_e64 v5, v5, 0, vcc
	v_cndmask_b32_e64 v9, v10, v11, s[46:47]
	v_mul_f32_e32 v10, 0x37800000, v9
	v_cndmask_b32_e64 v9, v9, v10, s[40:41]
	v_cmp_class_f32_e64 s[40:41], v6, v209
	v_cvt_pk_bf16_f32 v5, v5, 0
	s_nop 0
	v_cndmask_b32_e64 v6, v9, v6, s[40:41]
	v_mul_f32_e32 v6, v7, v6
	ds_read_b32 v9, v68 offset:55488
	s_waitcnt lgkmcnt(1)
; __device__ __forceinline__ unsigned f2bf(float f) { return pk2(f, 0.f) & 0xffffu; }
; __device__ __forceinline__ float sigm(float x) { return __builtin_amdgcn_rcpf(1.0f + __expf(-x)); }
; #define p (*kparams())
; __device__ __forceinline__ void lru_s1_item(CParams& p, int layer, int item, LAS unsigned char* lds) {
;     ...
;     for (int jt = 0; jt < 4; ++jt) { const int j = 16 * jt + r, ch = kb * 64 + j;
; #pragma unroll
;         for (int dir = 0; dir < 2; ++dir) {
;             const float ba = p.in[8][(layer * 2 + dir) * W + ch], bx = p.in[10][(layer * 2 + dir) * W + ch], lam = p.in[11][(layer * 2 + dir) * W + ch];
;             const float sp = log1pf(expf(-lam));
;             float Aq = 1.f, Bq = 0.f;
; #pragma unroll
;             for (int s = 0; s < 4; ++s) { const int q = dir ? 3 - s : s;
;                 const float rg = sigm(acc[(2 * dir) * 4 + jt][q] + ba), ig = sigm(acc[(2 * dir + 1) * 4 + jt][q] + bx);
;                 float la = -8.0f * rg * sp; float bv = sqrtf(fmaxf(1.0f - __expf(2.0f * la), 0.f)) * ig * XCf[(tok0 + q) * 64 + j];
;                 if ((t0 + q) < 0) { la = 0.f; bv = 0.f; }
;                 const unsigned lab = f2bf(la), bvb = f2bf(bv);
;                 const size_t ro = (size_t)row_bci(b, c, tok0 + q) * W + ch;
;                 LA[(size_t)dir * MP * W + ro] = (bf16_t)lab; BB[(size_t)dir * MP * W + ro] = (bf16_t)bvb;
;                 const float a = __expf(__uint_as_float(lab << 16)), bq = __uint_as_float(bvb << 16);
;                 Bq = a * Bq + bq; Aq *= a; }
;             const int g = 4 * wave + h;
;             AG[((g * 2 + dir) * 2 + 0) * 64 + j] = Aq; AG[((g * 2 + dir) * 2 + 1) * 64 + j] = Bq; } }
;     __syncthreads();
;     if (tid < 128) { const int dir = tid >> 6, jj = tid & 63; float At = 1.f, Bt = 0.f;
	v_mul_f32_e32 v6, v18, v6
	v_cndmask_b32_e64 v6, v6, 0, vcc
	v_cvt_pk_bf16_f32 v15, v6, 0
	v_lshl_add_u64 v[6:7], v[60:61], 0, v[12:13]
	v_lshlrev_b64 v[6:7], 1, v[6:7]
	v_lshl_add_u64 v[10:11], s[52:53], 0, v[6:7]
	v_lshl_add_u64 v[6:7], s[42:43], 0, v[6:7]
	global_store_short v[6:7], v15, off
	v_add_f32_e32 v7, v4, v4
	v_mul_f32_e32 v7, 0x3fb8aa3b, v7
	v_exp_f32_e32 v7, v7
	global_store_short v[10:11], v5, off
	v_lshlrev_b32_e32 v5, 16, v5
	v_mul_f32_e32 v5, 0x3fb8aa3b, v5
	v_sub_f32_e32 v7, 1.0, v7
	v_max_f32_e32 v7, 0, v7
	v_mul_f32_e32 v10, 0x4f800000, v7
	v_cmp_gt_f32_e64 s[40:41], s88, v7
	v_exp_f32_e32 v5, v5
	v_lshlrev_b32_e32 v6, 16, v15
	v_cndmask_b32_e64 v7, v7, v10, s[40:41]
	v_sqrt_f32_e32 v10, v7
	v_fmac_f32_e32 v6, v5, v19
	v_mul_f32_e32 v11, v5, v14
	v_add_f32_e32 v5, 1.0, v8
	v_add_u32_e32 v8, -1, v10
	v_fma_f32 v14, -v8, v10, v7
	v_cmp_ge_f32_e64 s[46:47], 0, v14
	v_add_u32_e32 v14, 1, v10
	v_rcp_f32_e32 v5, v5
	v_cndmask_b32_e64 v8, v10, v8, s[46:47]
	v_fma_f32 v10, -v14, v10, v7
	v_cmp_lt_f32_e64 s[46:47], 0, v10
	v_cndmask_b32_e64 v4, v4, 0, vcc
	s_nop 0
	v_cndmask_b32_e64 v8, v8, v14, s[46:47]
	v_mul_f32_e32 v10, 0x37800000, v8
	v_cndmask_b32_e64 v8, v8, v10, s[40:41]
	v_cmp_class_f32_e64 s[40:41], v7, v209
	s_nop 1
	v_cndmask_b32_e64 v7, v8, v7, s[40:41]
	v_mul_f32_e32 v5, v5, v7
	s_waitcnt lgkmcnt(0)
	v_mul_f32_e32 v5, v9, v5
	v_cndmask_b32_e64 v5, v5, 0, vcc
	v_cvt_pk_bf16_f32 v7, v4, 0
	v_cvt_pk_bf16_f32 v8, v5, 0
	v_lshl_add_u64 v[4:5], s[52:53], 0, v[0:1]
	global_store_short v[4:5], v7, off
	v_lshlrev_b32_e32 v4, 16, v7
	v_mul_f32_e32 v4, 0x3fb8aa3b, v4
	v_exp_f32_e32 v4, v4
	v_lshl_add_u64 v[0:1], s[42:43], 0, v[0:1]
	global_store_short v[0:1], v8, off
	v_lshlrev_b32_e32 v0, 16, v8
	v_fmac_f32_e32 v0, v4, v6
	v_mul_f32_e32 v1, v4, v11
	v_add3_u32 v4, s90, v16, v74
	v_cmp_gt_i32_e32 vcc, s4, v73
	ds_write2st64_b32 v4, v1, v0 offset0:2 offset1:3
	s_waitcnt lgkmcnt(0)
	s_barrier
	s_and_saveexec_b64 s[4:5], vcc
	s_cbranch_execz .LBB0_343
; #define p (*kparams())
; __device__ __forceinline__ void lru_s1_item(CParams& p, int layer, int item, LAS unsigned char* lds) {
;     ...
;     if (tid < 128) { const int dir = tid >> 6, jj = tid & 63; float At = 1.f, Bt = 0.f;
;         for (int s = 0; s < 32; ++s) { const int q = dir ? 31 - s : s; const float a = AG[((q * 2 + dir) * 2 + 0) * 64 + jj], bq = AG[((q * 2 + dir) * 2 + 1) * 64 + jj]; Bt = a * Bt + bq; At *= a; }
;         const size_t o = (size_t)((dir * 2 + b) * NCHK + c) * W + kb * 64 + jj;
;         ((float*)(p.ws + R_CA))[o] = At; ((float*)(p.ws + R_CB))[o] = Bt; }
	v_cmp_gt_u32_e32 vcc, 64, v73
	v_lshlrev_b32_e32 v0, 9, v72
	v_lshlrev_b32_e32 v1, 2, v3
	v_add3_u32 v6, s90, v0, v1
	v_cndmask_b32_e64 v0, v216, 0, vcc
	v_cndmask_b32_e32 v4, v231, v239, vcc
	v_add_u32_e32 v0, v6, v0
	v_add_u32_e32 v4, v6, v4
	ds_read2st64_b32 v[0:1], v0 offset1:1
	ds_read2st64_b32 v[4:5], v4 offset1:1
	v_mov_b32_e32 v8, 0x7400
	v_mov_b32_e32 v9, 0x800
	v_mov_b32_e32 v10, 0x7000
	s_waitcnt lgkmcnt(1)
	v_fma_f32 v1, 0, v0, v1
	s_waitcnt lgkmcnt(0)
	v_mul_f32_e32 v7, v0, v4
	v_cndmask_b32_e32 v0, v8, v9, vcc
	v_add_u32_e32 v0, v6, v0
	v_fmac_f32_e32 v5, v1, v4
	ds_read2st64_b32 v[0:1], v0 offset1:1
	v_mov_b32_e32 v11, 0xc00
	v_mov_b32_e32 v12, 0x6c00
	v_mov_b32_e32 v13, 0x6800
	v_mov_b32_e32 v14, 0x1400
	s_waitcnt lgkmcnt(0)
	v_mul_f32_e32 v7, v7, v0
	v_fmac_f32_e32 v1, v5, v0
	v_cndmask_b32_e32 v0, v10, v11, vcc
	v_add_u32_e32 v0, v6, v0
	ds_read2st64_b32 v[4:5], v0 offset1:1
	v_cndmask_b32_e32 v0, v12, v230, vcc
	v_add_u32_e32 v0, v6, v0
	v_mov_b32_e32 v15, 0x6400
	v_mov_b32_e32 v16, 0x1800
	s_waitcnt lgkmcnt(0)
	v_fmac_f32_e32 v5, v1, v4
	ds_read2st64_b32 v[0:1], v0 offset1:1
	v_mul_f32_e32 v7, v7, v4
	v_mov_b32_e32 v17, 0x6000
	v_mov_b32_e32 v18, 0x1c00
	v_mov_b32_e32 v19, 0x5c00
	s_waitcnt lgkmcnt(0)
	v_mul_f32_e32 v7, v7, v0
	v_fmac_f32_e32 v1, v5, v0
	v_cndmask_b32_e32 v0, v13, v14, vcc
	v_add_u32_e32 v0, v6, v0
	ds_read2st64_b32 v[4:5], v0 offset1:1
	v_cndmask_b32_e32 v0, v15, v16, vcc
	v_add_u32_e32 v0, v6, v0
	v_mov_b32_e32 v20, 0x5800
	v_mov_b32_e32 v21, 0x2400
	s_waitcnt lgkmcnt(0)
	v_fmac_f32_e32 v5, v1, v4
	ds_read2st64_b32 v[0:1], v0 offset1:1
	v_mul_f32_e32 v7, v7, v4
	v_mov_b32_e32 v22, 0x5400
	v_mov_b32_e32 v23, 0x2800
	v_mov_b32_e32 v24, 0x5000
	s_waitcnt lgkmcnt(0)
	v_mul_f32_e32 v7, v7, v0
	v_fmac_f32_e32 v1, v5, v0
	v_cndmask_b32_e32 v0, v17, v18, vcc
	v_add_u32_e32 v0, v6, v0
	ds_read2st64_b32 v[4:5], v0 offset1:1
	v_cndmask_b32_e32 v0, v19, v238, vcc
	v_add_u32_e32 v0, v6, v0
	v_mov_b32_e32 v25, 0x2c00
	v_mov_b32_e32 v26, 0x4c00
	s_waitcnt lgkmcnt(0)
	v_fmac_f32_e32 v5, v1, v4
	ds_read2st64_b32 v[0:1], v0 offset1:1
	v_mul_f32_e32 v7, v7, v4
	v_mov_b32_e32 v27, 0x3000
	v_mov_b32_e32 v28, 0x4800
	v_mov_b32_e32 v29, 0x4400
	s_waitcnt lgkmcnt(0)
	v_mul_f32_e32 v7, v7, v0
	v_fmac_f32_e32 v1, v5, v0
	v_cndmask_b32_e32 v0, v20, v21, vcc
	v_add_u32_e32 v0, v6, v0
	ds_read2st64_b32 v[4:5], v0 offset1:1
	v_cndmask_b32_e32 v0, v22, v23, vcc
	v_add_u32_e32 v0, v6, v0
	v_mov_b32_e32 v30, 0x3800
	v_mov_b32_e32 v31, 0x4000
	s_waitcnt lgkmcnt(0)
	v_fmac_f32_e32 v5, v1, v4
	ds_read2st64_b32 v[0:1], v0 offset1:1
	v_mul_f32_e32 v7, v7, v4
	s_waitcnt lgkmcnt(0)
	v_mul_f32_e32 v7, v7, v0
	v_fmac_f32_e32 v1, v5, v0
	v_cndmask_b32_e32 v0, v24, v25, vcc
	v_add_u32_e32 v0, v6, v0
	ds_read2st64_b32 v[4:5], v0 offset1:1
	v_cndmask_b32_e32 v0, v26, v27, vcc
	v_add_u32_e32 v0, v6, v0
	s_waitcnt lgkmcnt(0)
	v_fmac_f32_e32 v5, v1, v4
	ds_read2st64_b32 v[0:1], v0 offset1:1
	v_mul_f32_e32 v7, v7, v4
	s_waitcnt lgkmcnt(0)
	v_mul_f32_e32 v7, v7, v0
	v_fmac_f32_e32 v1, v5, v0
	v_cndmask_b32_e32 v0, v28, v247, vcc
	v_add_u32_e32 v0, v6, v0
	ds_read2st64_b32 v[4:5], v0 offset1:1
	v_cndmask_b32_e32 v0, v29, v30, vcc
	v_add_u32_e32 v0, v6, v0
	s_waitcnt lgkmcnt(0)
	v_fmac_f32_e32 v5, v1, v4
	ds_read2st64_b32 v[0:1], v0 offset1:1
	v_mul_f32_e32 v7, v7, v4
	s_waitcnt lgkmcnt(0)
	v_mul_f32_e32 v7, v7, v0
	v_fmac_f32_e32 v1, v5, v0
	v_cndmask_b32_e32 v0, v31, v252, vcc
	v_add_u32_e32 v0, v6, v0
	ds_read2st64_b32 v[4:5], v0 offset1:1
	v_cndmask_b32_e32 v0, v252, v31, vcc
	v_add_u32_e32 v0, v6, v0
	s_waitcnt lgkmcnt(0)
	v_fmac_f32_e32 v5, v1, v4
	ds_read2st64_b32 v[0:1], v0 offset1:1
	v_mul_f32_e32 v7, v7, v4
	s_waitcnt lgkmcnt(0)
	v_mul_f32_e32 v7, v7, v0
	v_fmac_f32_e32 v1, v5, v0
	v_cndmask_b32_e32 v0, v30, v29, vcc
	v_add_u32_e32 v0, v6, v0
	ds_read2st64_b32 v[4:5], v0 offset1:1
	v_cndmask_b32_e32 v0, v247, v28, vcc
	v_add_u32_e32 v0, v6, v0
	s_waitcnt lgkmcnt(0)
	v_fmac_f32_e32 v5, v1, v4
	ds_read2st64_b32 v[0:1], v0 offset1:1
	v_mul_f32_e32 v7, v7, v4
	s_waitcnt lgkmcnt(0)
	v_mul_f32_e32 v7, v7, v0
	v_fmac_f32_e32 v1, v5, v0
	v_cndmask_b32_e32 v0, v27, v26, vcc
	v_add_u32_e32 v0, v6, v0
	ds_read2st64_b32 v[4:5], v0 offset1:1
	v_cndmask_b32_e32 v0, v25, v24, vcc
	v_add_u32_e32 v0, v6, v0
	s_waitcnt lgkmcnt(0)
	v_fmac_f32_e32 v5, v1, v4
	ds_read2st64_b32 v[0:1], v0 offset1:1
	v_mul_f32_e32 v7, v7, v4
	s_waitcnt lgkmcnt(0)
	v_mul_f32_e32 v7, v7, v0
	v_fmac_f32_e32 v1, v5, v0
	v_cndmask_b32_e32 v0, v23, v22, vcc
	v_add_u32_e32 v0, v6, v0
	ds_read2st64_b32 v[4:5], v0 offset1:1
	v_cndmask_b32_e32 v0, v21, v20, vcc
	v_add_u32_e32 v0, v6, v0
	s_waitcnt lgkmcnt(0)
	v_fmac_f32_e32 v5, v1, v4
	ds_read2st64_b32 v[0:1], v0 offset1:1
	v_mul_f32_e32 v7, v7, v4
	s_waitcnt lgkmcnt(0)
	v_mul_f32_e32 v7, v7, v0
	v_fmac_f32_e32 v1, v5, v0
	v_cndmask_b32_e32 v0, v238, v19, vcc
	v_add_u32_e32 v0, v6, v0
	ds_read2st64_b32 v[4:5], v0 offset1:1
	v_cndmask_b32_e32 v0, v18, v17, vcc
	v_add_u32_e32 v0, v6, v0
	s_waitcnt lgkmcnt(0)
	v_fmac_f32_e32 v5, v1, v4
	ds_read2st64_b32 v[0:1], v0 offset1:1
	v_mul_f32_e32 v7, v7, v4
	s_waitcnt lgkmcnt(0)
	v_mul_f32_e32 v7, v7, v0
	v_fmac_f32_e32 v1, v5, v0
	v_cndmask_b32_e32 v0, v16, v15, vcc
	v_add_u32_e32 v0, v6, v0
	ds_read2st64_b32 v[4:5], v0 offset1:1
	v_cndmask_b32_e32 v0, v14, v13, vcc
	v_add_u32_e32 v0, v6, v0
	s_waitcnt lgkmcnt(0)
	v_fmac_f32_e32 v5, v1, v4
	ds_read2st64_b32 v[0:1], v0 offset1:1
	v_mul_f32_e32 v7, v7, v4
	s_waitcnt lgkmcnt(0)
	v_mul_f32_e32 v7, v7, v0
	v_fmac_f32_e32 v1, v5, v0
	v_cndmask_b32_e32 v0, v230, v12, vcc
	v_add_u32_e32 v0, v6, v0
	ds_read2st64_b32 v[4:5], v0 offset1:1
	v_cndmask_b32_e32 v0, v11, v10, vcc
	v_add_u32_e32 v0, v6, v0
	s_waitcnt lgkmcnt(0)
	v_fmac_f32_e32 v5, v1, v4
	ds_read2st64_b32 v[0:1], v0 offset1:1
	v_mul_f32_e32 v7, v7, v4
	s_waitcnt lgkmcnt(0)
	v_mul_f32_e32 v7, v7, v0
	v_fmac_f32_e32 v1, v5, v0
	v_cndmask_b32_e32 v0, v9, v8, vcc
	v_add_u32_e32 v0, v6, v0
	ds_read2st64_b32 v[4:5], v0 offset1:1
	v_cndmask_b32_e32 v0, v239, v231, vcc
	v_add_u32_e32 v0, v6, v0
	s_waitcnt lgkmcnt(0)
	v_fmac_f32_e32 v5, v1, v4
	ds_read2st64_b32 v[0:1], v0 offset1:1
	v_mul_f32_e32 v7, v7, v4
	s_waitcnt lgkmcnt(0)
	v_mul_f32_e32 v7, v7, v0
	v_fmac_f32_e32 v1, v5, v0
	v_cndmask_b32_e32 v0, 0, v216, vcc
	v_add_u32_e32 v0, v6, v0
	ds_read2st64_b32 v[4:5], v0 offset1:1
	v_lshl_add_u32 v0, v72, 1, s28
	v_lshl_add_u32 v0, v0, 6, v0
	v_add_u32_e32 v0, s30, v0
	s_waitcnt lgkmcnt(0)
	v_fmac_f32_e32 v5, v1, v4
	v_ashrrev_i32_e32 v1, 31, v0
	v_lshlrev_b64 v[0:1], 9, v[0:1]
	v_or3_b32 v0, v0, s29, v3
	v_lshl_add_u64 v[0:1], v[0:1], 2, s[34:35]
	v_add_co_u32_e32 v6, vcc, 0x3a0ea000, v0
	v_mul_f32_e32 v8, v7, v4
	s_nop 0
	v_addc_co_u32_e32 v7, vcc, 0, v1, vcc
	v_add_co_u32_e32 v0, vcc, 0x3a16c000, v0
	global_store_dword v[6:7], v8, off
	s_nop 0
	v_addc_co_u32_e32 v1, vcc, 0, v1, vcc
	global_store_dword v[0:1], v5, off
	s_branch .LBB0_343

; __device__ __forceinline__ float bf2f(bf16_t b) { return __uint_as_float(((unsigned)b) << 16); }
; __device__ __forceinline__ int opaque_tid() { int t = threadIdx.x; asm volatile("" : "+v"(t)); return t; }
; #define p (*kparams())
; __device__ __forceinline__ void conv3_16(const bf16_t* P, const float* cw, const float* cbias, int b, int t0, int col, float (&out)[16]) {
;     const int cc = col - 1024; const float w0 = cw[cc], w1 = cw[1536 + cc], w2 = cw[3072 + cc], bb = cbias[cc];
;     float xv[18];
; #pragma unroll
;     for (int q = 0; q < 18; ++q) { const int t = t0 - 1 + q; xv[q] = (t >= 0 && t < T) ? bf2f(P[(size_t)row_of(b, t) * NMIX + col]) : 0.f; }
; #pragma unroll
;     for (int tt = 0; tt < 16; ++tt) out[tt] = bb + w0 * xv[tt] + w1 * xv[tt + 1] + w2 * xv[tt + 2];
; }
; __device__ __forceinline__ void hy_s1_item(CParams& p, int layer, int item) {
;     const int cidx = item >> 3, cgp = item & 7, b = cidx / NCHK, c = cidx % NCHK;
;     const int tid = opaque_tid(), j = tid & 63, tq = tid >> 6, ch = cgp * 64 + j;
;     const int t0 = c * 128 + 16 * tq - 112;
;     if (t0 < 0) return;
;     const bf16_t* P = (const bf16_t*)(p.ws + R_PMIX);
;     const float* cw = p.in[12] + layer * 3 * 1536; const float* cbias = p.in[13] + layer * 1536;
;     float x1[16], vv[16];
;     conv3_16(P, cw, cbias, b, t0, 1024 + 512 + ch, x1); conv3_16(P, cw, cbias, b, t0, 1024 + 1024 + ch, vv);
.LBB0_392:
	s_ashr_i32 s4, s11, 3
	s_mul_hi_i32 s5, s4, 0x7e07e07f
	s_lshr_b32 s28, s5, 31
	s_ashr_i32 s36, s5, 5
	s_mov_b64 s[14:15], s[0:1]
	s_add_i32 s36, s36, s28
	v_mov_b32_e32 v1, v206
	s_mul_i32 s5, s36, 0x41
	s_sub_i32 s4, s4, s5
	v_ashrrev_i32_e32 v0, 2, v1
	v_and_b32_e32 v0, -16, v0
	v_lshl_add_u32 v0, s4, 7, v0
	v_cmp_lt_i32_e32 vcc, s93, v0
	s_and_saveexec_b64 s[4:5], vcc
	s_cbranch_execz .LBB0_391
	s_load_dwordx2 s[28:29], s[14:15], 0xe8
	s_load_dwordx4 s[48:51], s[14:15], 0x60
	s_and_b32 s30, s10, 0x1c0
	v_and_or_b32 v1, v1, 63, s30
	v_or_b32_e32 v3, 0x600, v1
	s_waitcnt lgkmcnt(0)
	s_add_u32 s30, s28, 0x19602000
	s_addc_u32 s31, s29, 0
	s_lshl_b64 s[14:15], s[34:35], 2
	s_add_u32 s46, s48, s14
	s_addc_u32 s47, s49, s15
	v_lshlrev_b32_e32 v4, 2, v3
	v_mov_b32_e32 v5, v2
	s_lshl_b64 s[14:15], s[42:43], 2
	v_lshl_add_u64 v[6:7], s[46:47], 0, v[4:5]
	s_add_u32 s44, s50, s14
	v_add_co_u32_e32 v6, vcc, 0x2000, v6
	s_addc_u32 s45, s51, s15
	v_lshlrev_b32_e32 v9, 2, v1
	v_addc_co_u32_e32 v7, vcc, 0, v7, vcc
	global_load_dword v4, v4, s[46:47] offset:2048
	s_nop 0
	global_load_dword v6, v[6:7], off
	s_nop 0
	global_load_dword v8, v9, s[46:47] offset:2048
	global_load_dword v10, v9, s[44:45] offset:2048
	v_add_u32_e32 v5, 0xffffff8f, v0
	s_lshl_b32 s95, s36, 13
	s_lshl_b32 s89, s36, 7
	s_movk_i32 s8, 0x2000
	s_add_i32 s39, s95, -16
	s_addk_i32 s89, 0x4070
	v_cmp_gt_u32_e64 s[40:41], s91, v5
	v_mov_b32_e32 v13, 0
	v_lshlrev_b32_e32 v38, 1, v3
	v_mov_b32_e32 v12, 0
	v_mov_b32_e32 v120, 0
	s_and_saveexec_b64 s[14:15], s[40:41]
	s_cbranch_execz .LBB0_395
	v_mov_b32_e32 v3, s39
	v_mov_b32_e32 v7, s89
	v_cmp_eq_u32_e32 vcc, 15, v5
	v_mov_b64_e32 v[14:15], s[30:31]
	v_mov_b32_e32 v39, v2
	v_cndmask_b32_e32 v3, v3, v7, vcc
	v_add_u32_e32 v3, v3, v5
	v_mad_i64_i32 v[14:15], s[48:49], v3, s26, v[14:15]
	v_lshl_add_u64 v[14:15], v[14:15], 0, v[38:39]
	global_load_ushort v120, v[14:15], off
.LBB0_395:
	s_or_b64 exec, exec, s[14:15]
	v_add_u32_e32 v3, 0xffffff90, v0
	v_cmp_gt_u32_e64 s[48:49], s91, v3
	v_mov_b32_e32 v121, 0
	s_and_saveexec_b64 s[14:15], s[48:49]
	s_cbranch_execz .LBB0_397
	v_mov_b32_e32 v7, s39
	v_mov_b32_e32 v9, s89
	v_cmp_eq_u32_e32 vcc, 0, v3
	v_mov_b64_e32 v[14:15], s[30:31]
	v_mov_b32_e32 v39, v2
	v_cndmask_b32_e32 v7, v7, v9, vcc
	v_add_u32_e32 v7, v7, v3
	v_mad_i64_i32 v[14:15], s[50:51], v7, s26, v[14:15]
	v_lshl_add_u64 v[14:15], v[14:15], 0, v[38:39]
	global_load_ushort v121, v[14:15], off
.LBB0_397:
	s_or_b64 exec, exec, s[14:15]
	s_movk_i32 s14, 0x200f
	v_cmp_gt_u32_e64 s[50:51], s14, v3
	v_mov_b32_e32 v15, 0
	v_mov_b32_e32 v17, 0
	v_mov_b32_e32 v122, 0
	s_and_saveexec_b64 s[14:15], s[50:51]
	s_cbranch_execz .LBB0_399
	v_mov_b32_e32 v7, s39
	v_mov_b32_e32 v9, s89
	v_cmp_eq_u32_e32 vcc, 0, v3
	s_movk_i32 s52, 0xff91
	v_mov_b64_e32 v[16:17], s[30:31]
	v_cndmask_b32_e32 v7, v7, v9, vcc
	v_add3_u32 v7, v0, v7, s52
	v_mad_i64_i32 v[16:17], s[52:53], v7, s26, v[16:17]
	v_mov_b32_e32 v39, v2
	v_lshl_add_u64 v[16:17], v[16:17], 0, v[38:39]
	global_load_ushort v122, v[16:17], off
.LBB0_399:
	s_or_b64 exec, exec, s[14:15]
	s_movk_i32 s14, 0x200e
	v_cmp_gt_u32_e64 s[52:53], s14, v3
	v_mov_b32_e32 v123, 0
	s_and_saveexec_b64 s[14:15], s[52:53]
	s_cbranch_execz .LBB0_401
	v_mov_b32_e32 v7, s39
	v_mov_b32_e32 v9, s89
	v_cmp_eq_u32_e32 vcc, 0, v3
	s_movk_i32 s54, 0xff92
	v_mov_b64_e32 v[14:15], s[30:31]
	v_cndmask_b32_e32 v7, v7, v9, vcc
	v_add3_u32 v7, v0, v7, s54
	v_mad_i64_i32 v[14:15], s[54:55], v7, s26, v[14:15]
	v_mov_b32_e32 v39, v2
	v_lshl_add_u64 v[14:15], v[14:15], 0, v[38:39]
	global_load_ushort v123, v[14:15], off
.LBB0_401:
	s_or_b64 exec, exec, s[14:15]
	s_movk_i32 s14, 0x200d
	v_cmp_gt_u32_e64 s[54:55], s14, v3
	v_mov_b32_e32 v19, 0
	v_mov_b32_e32 v21, 0
	v_mov_b32_e32 v124, 0
	s_and_saveexec_b64 s[14:15], s[54:55]
	s_cbranch_execz .LBB0_403
	v_mov_b32_e32 v7, s39
	v_mov_b32_e32 v9, s89
	v_cmp_eq_u32_e32 vcc, 0, v3
	s_movk_i32 s56, 0xff93
	v_mov_b64_e32 v[20:21], s[30:31]
	v_cndmask_b32_e32 v7, v7, v9, vcc
	v_add3_u32 v7, v0, v7, s56
	v_mad_i64_i32 v[20:21], s[56:57], v7, s26, v[20:21]
	v_mov_b32_e32 v39, v2
	v_lshl_add_u64 v[20:21], v[20:21], 0, v[38:39]
	global_load_ushort v124, v[20:21], off
.LBB0_403:
	s_or_b64 exec, exec, s[14:15]
	s_movk_i32 s14, 0x200c
	v_cmp_gt_u32_e64 s[56:57], s14, v3
	v_mov_b32_e32 v125, 0
	s_and_saveexec_b64 s[14:15], s[56:57]
	s_cbranch_execz .LBB0_405
	v_mov_b32_e32 v7, s39
	v_mov_b32_e32 v9, s89
	v_cmp_eq_u32_e32 vcc, 0, v3
	s_movk_i32 s58, 0xff94
	v_mov_b64_e32 v[18:19], s[30:31]
	v_cndmask_b32_e32 v7, v7, v9, vcc
	v_add3_u32 v7, v0, v7, s58
	v_mad_i64_i32 v[18:19], s[58:59], v7, s26, v[18:19]
	v_mov_b32_e32 v39, v2
	v_lshl_add_u64 v[18:19], v[18:19], 0, v[38:39]
	global_load_ushort v125, v[18:19], off
.LBB0_405:
	s_or_b64 exec, exec, s[14:15]
	s_movk_i32 s14, 0x200b
	v_cmp_gt_u32_e64 s[58:59], s14, v3
	v_mov_b32_e32 v23, 0
	v_mov_b32_e32 v25, 0
	v_mov_b32_e32 v126, 0
	s_and_saveexec_b64 s[14:15], s[58:59]
	s_cbranch_execz .LBB0_407
	v_mov_b32_e32 v7, s39
	v_mov_b32_e32 v9, s89
	v_cmp_eq_u32_e32 vcc, 0, v3
	s_movk_i32 s60, 0xff95
	v_mov_b64_e32 v[24:25], s[30:31]
	v_cndmask_b32_e32 v7, v7, v9, vcc
	v_add3_u32 v7, v0, v7, s60
	v_mad_i64_i32 v[24:25], s[60:61], v7, s26, v[24:25]
	v_mov_b32_e32 v39, v2
	v_lshl_add_u64 v[24:25], v[24:25], 0, v[38:39]
	global_load_ushort v126, v[24:25], off
.LBB0_407:
	s_or_b64 exec, exec, s[14:15]
	s_movk_i32 s14, 0x200a
	v_cmp_gt_u32_e64 s[60:61], s14, v3
	v_mov_b32_e32 v127, 0
	s_and_saveexec_b64 s[14:15], s[60:61]
	s_cbranch_execz .LBB0_409
	v_mov_b32_e32 v7, s39
	v_mov_b32_e32 v9, s89
	v_cmp_eq_u32_e32 vcc, 0, v3
	s_movk_i32 s62, 0xff96
	v_mov_b64_e32 v[22:23], s[30:31]
	v_cndmask_b32_e32 v7, v7, v9, vcc
	v_add3_u32 v7, v0, v7, s62
	v_mad_i64_i32 v[22:23], s[62:63], v7, s26, v[22:23]
	v_mov_b32_e32 v39, v2
	v_lshl_add_u64 v[22:23], v[22:23], 0, v[38:39]
	global_load_ushort v127, v[22:23], off
; __device__ __forceinline__ float bf2f(bf16_t b) { return __uint_as_float(((unsigned)b) << 16); }
; __device__ __forceinline__ void conv3_16(const bf16_t* P, const float* cw, const float* cbias, int b, int t0, int col, float (&out)[16]) {
;     const int cc = col - 1024; const float w0 = cw[cc], w1 = cw[1536 + cc], w2 = cw[3072 + cc], bb = cbias[cc];
;     float xv[18];
; #pragma unroll
;     for (int q = 0; q < 18; ++q) { const int t = t0 - 1 + q; xv[q] = (t >= 0 && t < T) ? bf2f(P[(size_t)row_of(b, t) * NMIX + col]) : 0.f; }
.LBB0_409:
	s_or_b64 exec, exec, s[14:15]
	s_movk_i32 s14, 0x2009
	v_cmp_gt_u32_e64 s[62:63], s14, v3
	v_mov_b32_e32 v27, 0
	v_mov_b32_e32 v29, 0
	v_mov_b32_e32 v128, 0
	s_and_saveexec_b64 s[14:15], s[62:63]
	s_cbranch_execz .LBB0_411
	v_mov_b32_e32 v7, s39
	v_mov_b32_e32 v9, s89
	v_cmp_eq_u32_e32 vcc, 0, v3
	s_movk_i32 s64, 0xff97
	v_mov_b64_e32 v[28:29], s[30:31]
	v_cndmask_b32_e32 v7, v7, v9, vcc
	v_add3_u32 v7, v0, v7, s64
	v_mad_i64_i32 v[28:29], s[64:65], v7, s26, v[28:29]
	v_mov_b32_e32 v39, v2
	v_lshl_add_u64 v[28:29], v[28:29], 0, v[38:39]
	global_load_ushort v128, v[28:29], off
.LBB0_411:
	s_or_b64 exec, exec, s[14:15]
	s_movk_i32 s14, 0x2008
	v_cmp_gt_u32_e64 s[64:65], s14, v3
	v_mov_b32_e32 v129, 0
	s_and_saveexec_b64 s[14:15], s[64:65]
	s_cbranch_execz .LBB0_413
	v_mov_b32_e32 v7, s39
	v_mov_b32_e32 v9, s89
	v_cmp_eq_u32_e32 vcc, 0, v3
	s_movk_i32 s66, 0xff98
	v_mov_b64_e32 v[26:27], s[30:31]
	v_cndmask_b32_e32 v7, v7, v9, vcc
	v_add3_u32 v7, v0, v7, s66
	v_mad_i64_i32 v[26:27], s[66:67], v7, s26, v[26:27]
	v_mov_b32_e32 v39, v2
	v_lshl_add_u64 v[26:27], v[26:27], 0, v[38:39]
	global_load_ushort v129, v[26:27], off
.LBB0_413:
	s_or_b64 exec, exec, s[14:15]
	s_movk_i32 s14, 0x2007
	v_cmp_gt_u32_e64 s[66:67], s14, v3
	v_mov_b32_e32 v31, 0
	v_mov_b32_e32 v33, 0
	v_mov_b32_e32 v130, 0
	s_and_saveexec_b64 s[14:15], s[66:67]
	s_cbranch_execz .LBB0_415
	v_mov_b32_e32 v7, s39
	v_mov_b32_e32 v9, s89
	v_cmp_eq_u32_e32 vcc, 0, v3
	s_movk_i32 s68, 0xff99
	v_mov_b64_e32 v[32:33], s[30:31]
	v_cndmask_b32_e32 v7, v7, v9, vcc
	v_add3_u32 v7, v0, v7, s68
	v_mad_i64_i32 v[32:33], s[68:69], v7, s26, v[32:33]
	v_mov_b32_e32 v39, v2
	v_lshl_add_u64 v[32:33], v[32:33], 0, v[38:39]
	global_load_ushort v130, v[32:33], off
.LBB0_415:
	s_or_b64 exec, exec, s[14:15]
	s_movk_i32 s14, 0x2006
	v_cmp_gt_u32_e64 s[68:69], s14, v3
	v_mov_b32_e32 v131, 0
	s_and_saveexec_b64 s[14:15], s[68:69]
	s_cbranch_execz .LBB0_417
	v_mov_b32_e32 v7, s39
	v_mov_b32_e32 v9, s89
	v_cmp_eq_u32_e32 vcc, 0, v3
	s_movk_i32 s70, 0xff9a
	v_mov_b64_e32 v[30:31], s[30:31]
	v_cndmask_b32_e32 v7, v7, v9, vcc
	v_add3_u32 v7, v0, v7, s70
	v_mad_i64_i32 v[30:31], s[70:71], v7, s26, v[30:31]
	v_mov_b32_e32 v39, v2
	v_lshl_add_u64 v[30:31], v[30:31], 0, v[38:39]
	global_load_ushort v131, v[30:31], off
.LBB0_417:
	s_or_b64 exec, exec, s[14:15]
	s_movk_i32 s14, 0x2005
	v_cmp_gt_u32_e64 s[70:71], s14, v3
	v_mov_b32_e32 v35, 0
	v_mov_b32_e32 v37, 0
	v_mov_b32_e32 v132, 0
	s_and_saveexec_b64 s[14:15], s[70:71]
	s_cbranch_execz .LBB0_419
	v_mov_b32_e32 v7, s39
	v_mov_b32_e32 v9, s89
	v_cmp_eq_u32_e32 vcc, 0, v3
	s_movk_i32 s72, 0xff9b
	v_mov_b64_e32 v[36:37], s[30:31]
	v_cndmask_b32_e32 v7, v7, v9, vcc
	v_add3_u32 v7, v0, v7, s72
	v_mad_i64_i32 v[36:37], s[72:73], v7, s26, v[36:37]
	v_mov_b32_e32 v39, v2
	v_lshl_add_u64 v[36:37], v[36:37], 0, v[38:39]
	global_load_ushort v132, v[36:37], off
.LBB0_419:
	s_or_b64 exec, exec, s[14:15]
	s_movk_i32 s14, 0x2004
	v_cmp_gt_u32_e64 s[72:73], s14, v3
	v_mov_b32_e32 v133, 0
	s_and_saveexec_b64 s[14:15], s[72:73]
	s_cbranch_execz .LBB0_421
	v_mov_b32_e32 v7, s39
	v_mov_b32_e32 v9, s89
	v_cmp_eq_u32_e32 vcc, 0, v3
	s_movk_i32 s74, 0xff9c
	v_mov_b64_e32 v[34:35], s[30:31]
	v_cndmask_b32_e32 v7, v7, v9, vcc
	v_add3_u32 v7, v0, v7, s74
	v_mad_i64_i32 v[34:35], s[74:75], v7, s26, v[34:35]
	v_mov_b32_e32 v39, v2
	v_lshl_add_u64 v[34:35], v[34:35], 0, v[38:39]
	global_load_ushort v133, v[34:35], off
.LBB0_421:
	s_or_b64 exec, exec, s[14:15]
	s_movk_i32 s14, 0x2003
	v_cmp_gt_u32_e64 s[74:75], s14, v3
	v_mov_b32_e32 v41, 0
	v_mov_b32_e32 v45, 0
	v_mov_b32_e32 v134, 0
	s_and_saveexec_b64 s[14:15], s[74:75]
	s_cbranch_execz .LBB0_423
	v_mov_b32_e32 v7, s39
	v_mov_b32_e32 v9, s89
	v_cmp_eq_u32_e32 vcc, 0, v3
	s_movk_i32 s76, 0xff9d
	v_mov_b64_e32 v[42:43], s[30:31]
	v_cndmask_b32_e32 v7, v7, v9, vcc
	v_add3_u32 v7, v0, v7, s76
	v_mad_i64_i32 v[42:43], s[76:77], v7, s26, v[42:43]
	v_mov_b32_e32 v39, v2
	v_lshl_add_u64 v[42:43], v[42:43], 0, v[38:39]
	global_load_ushort v134, v[42:43], off
.LBB0_423:
	s_or_b64 exec, exec, s[14:15]
	s_movk_i32 s14, 0x2002
	v_cmp_gt_u32_e64 s[76:77], s14, v3
	v_mov_b32_e32 v135, 0
	s_and_saveexec_b64 s[14:15], s[76:77]
	s_cbranch_execz .LBB0_425
	v_mov_b32_e32 v7, s39
	v_mov_b32_e32 v9, s89
	v_cmp_eq_u32_e32 vcc, 0, v3
	s_movk_i32 s78, 0xff9e
	v_mov_b64_e32 v[40:41], s[30:31]
	v_cndmask_b32_e32 v7, v7, v9, vcc
	v_add3_u32 v7, v0, v7, s78
	v_mad_i64_i32 v[40:41], s[78:79], v7, s26, v[40:41]
	v_mov_b32_e32 v39, v2
	v_lshl_add_u64 v[40:41], v[40:41], 0, v[38:39]
	global_load_ushort v135, v[40:41], off
.LBB0_425:
	s_or_b64 exec, exec, s[14:15]
	s_movk_i32 s14, 0x2001
	v_cmp_gt_u32_e64 s[78:79], s14, v3
	v_mov_b32_e32 v51, 0
	v_mov_b32_e32 v53, 0
	v_mov_b32_e32 v136, 0
	s_and_saveexec_b64 s[14:15], s[78:79]
	s_cbranch_execz .LBB0_427
	v_mov_b32_e32 v7, s39
	v_mov_b32_e32 v9, s89
	v_cmp_eq_u32_e32 vcc, 0, v3
	s_movk_i32 s80, 0xff9f
	v_mov_b64_e32 v[42:43], s[30:31]
	v_cndmask_b32_e32 v7, v7, v9, vcc
	v_add3_u32 v7, v0, v7, s80
	v_mad_i64_i32 v[42:43], s[80:81], v7, s26, v[42:43]
	v_mov_b32_e32 v39, v2
	v_lshl_add_u64 v[42:43], v[42:43], 0, v[38:39]
	global_load_ushort v136, v[42:43], off
.LBB0_427:
	s_or_b64 exec, exec, s[14:15]
	v_cmp_gt_u32_e64 s[80:81], s8, v3
	v_or_b32_e32 v14, s95, v3
	v_mov_b32_e32 v137, 0
	s_and_saveexec_b64 s[14:15], s[80:81]
	s_cbranch_execz .LBB0_429
	v_mov_b64_e32 v[42:43], s[30:31]
	v_mad_i64_i32 v[42:43], vcc, v14, s26, v[42:43]
	v_mov_b32_e32 v39, v2
	v_lshl_add_u64 v[38:39], v[42:43], 0, v[38:39]
	global_load_ushort v137, v[38:39], off
; __device__ __forceinline__ float bf2f(bf16_t b) { return __uint_as_float(((unsigned)b) << 16); }
; __device__ __forceinline__ void conv3_16(const bf16_t* P, const float* cw, const float* cbias, int b, int t0, int col, float (&out)[16]) {
;     const int cc = col - 1024; const float w0 = cw[cc], w1 = cw[1536 + cc], w2 = cw[3072 + cc], bb = cbias[cc];
;     float xv[18];
; #pragma unroll
;     for (int q = 0; q < 18; ++q) { const int t = t0 - 1 + q; xv[q] = (t >= 0 && t < T) ? bf2f(P[(size_t)row_of(b, t) * NMIX + col]) : 0.f; }
; __device__ __forceinline__ void hy_s1_item(CParams& p, int layer, int item) {
;     ...
;     conv3_16(P, cw, cbias, b, t0, 1024 + 512 + ch, x1); conv3_16(P, cw, cbias, b, t0, 1024 + 1024 + ch, vv);
.LBB0_429:
	s_or_b64 exec, exec, s[14:15]
	v_or_b32_e32 v7, 0x800, v1
	v_lshlrev_b32_e32 v42, 2, v7
	v_mov_b32_e32 v43, v2
	v_lshl_add_u64 v[46:47], s[46:47], 0, v[42:43]
	v_add_co_u32_e32 v46, vcc, 0x2000, v46
	v_lshl_or_b32 v9, v1, 2, v230
	s_nop 0
	v_addc_co_u32_e32 v47, vcc, 0, v47, vcc
	global_load_dword v38, v9, s[46:47]
	v_lshlrev_b32_e32 v54, 1, v7
	global_load_dword v42, v42, s[46:47] offset:2048
	s_nop 0
	global_load_dword v46, v[46:47], off
	s_nop 0
	global_load_dword v48, v9, s[44:45]
	v_mov_b32_e32 v55, v2
	v_lshl_add_u64 v[56:57], s[30:31], 0, v[54:55]
	v_mov_b32_e32 v55, 0
	v_mov_b32_e32 v54, 0
	v_mov_b32_e32 v138, 0
	s_and_saveexec_b64 s[14:15], s[40:41]
	s_cbranch_execz .LBB0_431
	v_mov_b32_e32 v7, s39
	v_mov_b32_e32 v9, s89
	v_cmp_eq_u32_e32 vcc, 15, v5
	s_nop 1
	v_cndmask_b32_e32 v7, v7, v9, vcc
	v_add_u32_e32 v5, v7, v5
	v_mad_i64_i32 v[58:59], s[30:31], v5, s26, v[56:57]
	global_load_ushort v138, v[58:59], off
.LBB0_431:
	s_or_b64 exec, exec, s[14:15]
	v_mov_b32_e32 v139, 0
	s_and_saveexec_b64 s[14:15], s[48:49]
	s_cbranch_execz .LBB0_433
	v_mov_b32_e32 v5, s39
	v_mov_b32_e32 v7, s89
	v_cmp_eq_u32_e32 vcc, 0, v3
	s_nop 1
	v_cndmask_b32_e32 v5, v5, v7, vcc
	v_add_u32_e32 v5, v5, v3
	v_mad_i64_i32 v[58:59], s[30:31], v5, s26, v[56:57]
	global_load_ushort v139, v[58:59], off
.LBB0_433:
	s_or_b64 exec, exec, s[14:15]
	v_mov_b32_e32 v5, 0
	v_mov_b32_e32 v7, 0
	v_mov_b32_e32 v140, 0
	s_and_saveexec_b64 s[14:15], s[50:51]
	s_cbranch_execz .LBB0_435
	v_mov_b32_e32 v7, s39
	v_mov_b32_e32 v9, s89
	v_cmp_eq_u32_e32 vcc, 0, v3
	s_movk_i32 s8, 0xff91
	s_nop 0
	v_cndmask_b32_e32 v7, v7, v9, vcc
	v_add3_u32 v7, v0, v7, s8
	v_mad_i64_i32 v[58:59], s[30:31], v7, s26, v[56:57]
	global_load_ushort v140, v[58:59], off
.LBB0_435:
	s_or_b64 exec, exec, s[14:15]
	v_mov_b32_e32 v141, 0
	s_and_saveexec_b64 s[14:15], s[52:53]
	s_cbranch_execz .LBB0_437
	v_mov_b32_e32 v5, s39
	v_mov_b32_e32 v9, s89
	v_cmp_eq_u32_e32 vcc, 0, v3
	s_movk_i32 s8, 0xff92
	s_nop 0
	v_cndmask_b32_e32 v5, v5, v9, vcc
	v_add3_u32 v5, v0, v5, s8
	v_mad_i64_i32 v[58:59], s[30:31], v5, s26, v[56:57]
	global_load_ushort v141, v[58:59], off
.LBB0_437:
	s_or_b64 exec, exec, s[14:15]
	v_mov_b32_e32 v9, 0
	v_mov_b32_e32 v11, 0
	v_mov_b32_e32 v142, 0
	s_and_saveexec_b64 s[14:15], s[54:55]
	s_cbranch_execz .LBB0_439
	v_mov_b32_e32 v11, s39
	v_mov_b32_e32 v16, s89
	v_cmp_eq_u32_e32 vcc, 0, v3
	s_movk_i32 s8, 0xff93
	s_nop 0
	v_cndmask_b32_e32 v11, v11, v16, vcc
	v_add3_u32 v11, v0, v11, s8
	v_mad_i64_i32 v[58:59], s[30:31], v11, s26, v[56:57]
	global_load_ushort v142, v[58:59], off
.LBB0_439:
	s_or_b64 exec, exec, s[14:15]
	v_mov_b32_e32 v143, 0
	s_and_saveexec_b64 s[14:15], s[56:57]
	s_cbranch_execz .LBB0_441
	v_mov_b32_e32 v9, s39
	v_mov_b32_e32 v16, s89
	v_cmp_eq_u32_e32 vcc, 0, v3
	s_movk_i32 s8, 0xff94
	s_nop 0
	v_cndmask_b32_e32 v9, v9, v16, vcc
	v_add3_u32 v9, v0, v9, s8
	v_mad_i64_i32 v[58:59], s[30:31], v9, s26, v[56:57]
	global_load_ushort v143, v[58:59], off
.LBB0_441:
	s_or_b64 exec, exec, s[14:15]
	v_mov_b32_e32 v59, 0
	v_mov_b32_e32 v61, 0
	v_mov_b32_e32 v144, 0
	s_and_saveexec_b64 s[14:15], s[58:59]
	s_cbranch_execz .LBB0_443
	v_mov_b32_e32 v16, s39
	v_mov_b32_e32 v18, s89
	v_cmp_eq_u32_e32 vcc, 0, v3
	s_movk_i32 s8, 0xff95
	s_nop 0
	v_cndmask_b32_e32 v16, v16, v18, vcc
	v_add3_u32 v16, v0, v16, s8
	v_mad_i64_i32 v[60:61], s[30:31], v16, s26, v[56:57]
	global_load_ushort v144, v[60:61], off
.LBB0_443:
	s_or_b64 exec, exec, s[14:15]
	v_mov_b32_e32 v145, 0
	s_and_saveexec_b64 s[14:15], s[60:61]
	s_cbranch_execz .LBB0_445
	v_mov_b32_e32 v16, s39
	v_mov_b32_e32 v18, s89
	v_cmp_eq_u32_e32 vcc, 0, v3
	s_movk_i32 s8, 0xff96
	s_nop 0
	v_cndmask_b32_e32 v16, v16, v18, vcc
	v_add3_u32 v16, v0, v16, s8
	v_mad_i64_i32 v[58:59], s[30:31], v16, s26, v[56:57]
	global_load_ushort v145, v[58:59], off
.LBB0_445:
	s_or_b64 exec, exec, s[14:15]
	v_mov_b32_e32 v63, 0
	v_mov_b32_e32 v65, 0
	v_mov_b32_e32 v146, 0
	s_and_saveexec_b64 s[14:15], s[62:63]
	s_cbranch_execz .LBB0_447
	v_mov_b32_e32 v16, s39
	v_mov_b32_e32 v18, s89
	v_cmp_eq_u32_e32 vcc, 0, v3
	s_movk_i32 s8, 0xff97
	s_nop 0
	v_cndmask_b32_e32 v16, v16, v18, vcc
	v_add3_u32 v16, v0, v16, s8
	v_mad_i64_i32 v[64:65], s[30:31], v16, s26, v[56:57]
	global_load_ushort v146, v[64:65], off
.LBB0_447:
	s_or_b64 exec, exec, s[14:15]
	v_mov_b32_e32 v147, 0
	s_and_saveexec_b64 s[14:15], s[64:65]
	s_cbranch_execz .LBB0_449
	v_mov_b32_e32 v16, s39
	v_mov_b32_e32 v18, s89
	v_cmp_eq_u32_e32 vcc, 0, v3
	s_movk_i32 s8, 0xff98
	s_nop 0
	v_cndmask_b32_e32 v16, v16, v18, vcc
	v_add3_u32 v16, v0, v16, s8
	v_mad_i64_i32 v[62:63], s[30:31], v16, s26, v[56:57]
	global_load_ushort v147, v[62:63], off
; __device__ __forceinline__ float bf2f(bf16_t b) { return __uint_as_float(((unsigned)b) << 16); }
; __device__ __forceinline__ void conv3_16(const bf16_t* P, const float* cw, const float* cbias, int b, int t0, int col, float (&out)[16]) {
;     const int cc = col - 1024; const float w0 = cw[cc], w1 = cw[1536 + cc], w2 = cw[3072 + cc], bb = cbias[cc];
;     float xv[18];
; #pragma unroll
;     for (int q = 0; q < 18; ++q) { const int t = t0 - 1 + q; xv[q] = (t >= 0 && t < T) ? bf2f(P[(size_t)row_of(b, t) * NMIX + col]) : 0.f; }
; #pragma unroll
;     for (int tt = 0; tt < 16; ++tt) out[tt] = bb + w0 * xv[tt] + w1 * xv[tt + 1] + w2 * xv[tt + 2];
.LBB0_449:
	s_or_b64 exec, exec, s[14:15]
	v_mov_b32_e32 v67, 0
	v_mov_b32_e32 v69, 0
	v_mov_b32_e32 v148, 0
	s_and_saveexec_b64 s[14:15], s[66:67]
	s_cbranch_execz .LBB0_451
	v_mov_b32_e32 v16, s39
	v_mov_b32_e32 v18, s89
	v_cmp_eq_u32_e32 vcc, 0, v3
	s_movk_i32 s8, 0xff99
	s_nop 0
	v_cndmask_b32_e32 v16, v16, v18, vcc
	v_add3_u32 v16, v0, v16, s8
	v_mad_i64_i32 v[68:69], s[30:31], v16, s26, v[56:57]
	global_load_ushort v148, v[68:69], off
.LBB0_451:
	s_or_b64 exec, exec, s[14:15]
	v_mov_b32_e32 v149, 0
	s_and_saveexec_b64 s[14:15], s[68:69]
	s_cbranch_execz .LBB0_453
	v_mov_b32_e32 v16, s39
	v_mov_b32_e32 v18, s89
	v_cmp_eq_u32_e32 vcc, 0, v3
	s_movk_i32 s8, 0xff9a
	s_nop 0
	v_cndmask_b32_e32 v16, v16, v18, vcc
	v_add3_u32 v16, v0, v16, s8
	v_mad_i64_i32 v[66:67], s[30:31], v16, s26, v[56:57]
	global_load_ushort v149, v[66:67], off
.LBB0_453:
	s_or_b64 exec, exec, s[14:15]
	v_mov_b32_e32 v71, 0
	v_mov_b32_e32 v73, 0
	v_mov_b32_e32 v150, 0
	s_and_saveexec_b64 s[14:15], s[70:71]
	s_cbranch_execz .LBB0_455
	v_mov_b32_e32 v16, s39
	v_mov_b32_e32 v18, s89
	v_cmp_eq_u32_e32 vcc, 0, v3
	s_movk_i32 s8, 0xff9b
	s_nop 0
	v_cndmask_b32_e32 v16, v16, v18, vcc
	v_add3_u32 v16, v0, v16, s8
	v_mad_i64_i32 v[72:73], s[30:31], v16, s26, v[56:57]
	global_load_ushort v150, v[72:73], off
.LBB0_455:
	s_or_b64 exec, exec, s[14:15]
	v_mov_b32_e32 v151, 0
	s_and_saveexec_b64 s[14:15], s[72:73]
	s_cbranch_execz .LBB0_457
	v_mov_b32_e32 v16, s39
	v_mov_b32_e32 v18, s89
	v_cmp_eq_u32_e32 vcc, 0, v3
	s_movk_i32 s8, 0xff9c
	s_nop 0
	v_cndmask_b32_e32 v16, v16, v18, vcc
	v_add3_u32 v16, v0, v16, s8
	v_mad_i64_i32 v[70:71], s[30:31], v16, s26, v[56:57]
	global_load_ushort v151, v[70:71], off
.LBB0_457:
	s_or_b64 exec, exec, s[14:15]
	v_mov_b32_e32 v75, 0
	v_mov_b32_e32 v77, 0
	v_mov_b32_e32 v152, 0
	s_and_saveexec_b64 s[14:15], s[74:75]
	s_cbranch_execz .LBB0_459
	v_mov_b32_e32 v16, s39
	v_mov_b32_e32 v18, s89
	v_cmp_eq_u32_e32 vcc, 0, v3
	s_movk_i32 s8, 0xff9d
	s_nop 0
	v_cndmask_b32_e32 v16, v16, v18, vcc
	v_add3_u32 v16, v0, v16, s8
	v_mad_i64_i32 v[76:77], s[30:31], v16, s26, v[56:57]
	global_load_ushort v152, v[76:77], off
.LBB0_459:
	s_or_b64 exec, exec, s[14:15]
	v_mov_b32_e32 v153, 0
	s_and_saveexec_b64 s[14:15], s[76:77]
	s_cbranch_execz .LBB0_461
	v_mov_b32_e32 v16, s39
	v_mov_b32_e32 v18, s89
	v_cmp_eq_u32_e32 vcc, 0, v3
	s_movk_i32 s8, 0xff9e
	s_nop 0
	v_cndmask_b32_e32 v16, v16, v18, vcc
	v_add3_u32 v16, v0, v16, s8
	v_mad_i64_i32 v[74:75], s[30:31], v16, s26, v[56:57]
	global_load_ushort v153, v[74:75], off
.LBB0_461:
	s_or_b64 exec, exec, s[14:15]
	v_mov_b32_e32 v79, 0
	v_mov_b32_e32 v81, 0
	v_mov_b32_e32 v154, 0
	s_and_saveexec_b64 s[14:15], s[78:79]
	s_cbranch_execz .LBB0_463
	v_mov_b32_e32 v16, s39
	v_mov_b32_e32 v18, s89
	v_cmp_eq_u32_e32 vcc, 0, v3
	s_movk_i32 s8, 0xff9f
	s_nop 0
	v_cndmask_b32_e32 v3, v16, v18, vcc
	v_add3_u32 v3, v0, v3, s8
	v_mad_i64_i32 v[80:81], s[30:31], v3, s26, v[56:57]
	global_load_ushort v154, v[80:81], off
.LBB0_463:
	s_or_b64 exec, exec, s[14:15]
	s_waitcnt vmcnt(0)
	v_lshlrev_b32_e32 v12, 16, v120
	v_lshlrev_b32_e32 v13, 16, v121
	v_lshlrev_b32_e32 v17, 16, v122
	v_lshlrev_b32_e32 v15, 16, v123
	v_lshlrev_b32_e32 v21, 16, v124
	v_lshlrev_b32_e32 v19, 16, v125
	v_lshlrev_b32_e32 v25, 16, v126
	v_lshlrev_b32_e32 v23, 16, v127
	v_lshlrev_b32_e32 v29, 16, v128
	v_lshlrev_b32_e32 v27, 16, v129
	v_lshlrev_b32_e32 v33, 16, v130
	v_lshlrev_b32_e32 v31, 16, v131
	v_lshlrev_b32_e32 v37, 16, v132
	v_lshlrev_b32_e32 v35, 16, v133
	v_lshlrev_b32_e32 v45, 16, v134
	v_lshlrev_b32_e32 v41, 16, v135
	v_lshlrev_b32_e32 v53, 16, v136
	v_lshlrev_b32_e32 v51, 16, v137
	v_lshlrev_b32_e32 v54, 16, v138
	v_lshlrev_b32_e32 v55, 16, v139
	v_lshlrev_b32_e32 v7, 16, v140
	v_lshlrev_b32_e32 v5, 16, v141
	v_lshlrev_b32_e32 v11, 16, v142
	v_lshlrev_b32_e32 v9, 16, v143
	v_lshlrev_b32_e32 v61, 16, v144
	v_lshlrev_b32_e32 v59, 16, v145
	v_lshlrev_b32_e32 v65, 16, v146
	v_lshlrev_b32_e32 v63, 16, v147
	v_lshlrev_b32_e32 v69, 16, v148
	v_lshlrev_b32_e32 v67, 16, v149
	v_lshlrev_b32_e32 v73, 16, v150
	v_lshlrev_b32_e32 v71, 16, v151
	v_lshlrev_b32_e32 v77, 16, v152
	v_lshlrev_b32_e32 v75, 16, v153
	v_lshlrev_b32_e32 v81, 16, v154
	s_and_saveexec_b64 s[14:15], s[80:81]
	s_cbranch_execz .LBB0_390
	v_mad_i64_i32 v[56:57], s[30:31], v14, s26, v[56:57]
	global_load_ushort v3, v[56:57], off
	s_waitcnt vmcnt(0)
	v_lshlrev_b32_e32 v79, 16, v3
	s_branch .LBB0_390

; __device__ __forceinline__ float bf2f(bf16_t b) { return __uint_as_float(((unsigned)b) << 16); }
; __device__ __forceinline__ int opaque_tid() { int t = threadIdx.x; asm volatile("" : "+v"(t)); return t; }
; #define p (*kparams())
; __device__ __forceinline__ void conv3_16(const bf16_t* P, const float* cw, const float* cbias, int b, int t0, int col, float (&out)[16]) {
;     const int cc = col - 1024; const float w0 = cw[cc], w1 = cw[1536 + cc], w2 = cw[3072 + cc], bb = cbias[cc];
;     float xv[18];
; #pragma unroll
;     for (int q = 0; q < 18; ++q) { const int t = t0 - 1 + q; xv[q] = (t >= 0 && t < T) ? bf2f(P[(size_t)row_of(b, t) * NMIX + col]) : 0.f; }
; __device__ __forceinline__ void hy_s3_item(CParams& p, int layer, int item) {
;     const int cidx = item >> 3, cgp = item & 7, b = cidx / NCHK, c = cidx % NCHK;
;     const int tid = opaque_tid(), j = tid & 63, tq = tid >> 6, ch = cgp * 64 + j;
;     const int t0 = c * 128 + 16 * tq - 112;
;     bf16_t* Z = (bf16_t*)(p.ws + OFF_Z);
;     if (t0 < 0) {
; #pragma unroll
;         for (int tt = 0; tt < 16; ++tt) Z[(size_t)row_bci(b, c, 16 * tq + tt) * D + 512 + ch] = 0;
;         return; }
;     const bf16_t* P = (const bf16_t*)(p.ws + R_PMIX);
;     const float* cw = p.in[12] + layer * 3 * 1536; const float* cbias = p.in[13] + layer * 1536;
;     float x0[16];
;     conv3_16(P, cw, cbias, b, t0, 1024 + ch, x0);
.LBB0_882:
	s_ashr_i32 s4, s10, 3
	s_mov_b64 s[14:15], s[0:1]
	s_mul_hi_i32 s5, s4, 0x7e07e07f
	v_mov_b32_e32 v0, v206
	s_lshr_b32 s11, s5, 31
	s_ashr_i32 s5, s5, 5
	s_load_dwordx2 s[30:31], s[14:15], 0xe8
	s_add_i32 s11, s5, s11
	s_mul_i32 s5, s11, 0x41
	s_sub_i32 s36, s4, s5
	v_ashrrev_i32_e32 v3, 2, v0
	s_and_b32 s4, s9, 0x1c0
	s_lshl_b32 s39, s36, 7
	v_and_b32_e32 v12, -16, v3
	v_and_or_b32 v1, v0, 63, s4
	v_add_u32_e32 v0, s39, v12
	s_waitcnt lgkmcnt(0)
	s_add_u32 s4, s30, 0xc300000
	s_addc_u32 s5, s31, 0
	v_cmp_lt_i32_e32 vcc, s93, v0
	s_and_saveexec_b64 s[28:29], vcc
	s_xor_b64 s[28:29], exec, s[28:29]
	s_cbranch_execz .LBB0_920
	s_load_dwordx4 s[44:47], s[14:15], 0x60
	s_add_u32 s40, s30, 0x19602000
	s_addc_u32 s41, s31, 0
	s_lshl_b64 s[14:15], s[34:35], 2
	v_or_b32_e32 v10, 0x400, v1
	s_waitcnt lgkmcnt(0)
	s_add_u32 s14, s44, s14
	s_addc_u32 s15, s45, s15
	v_lshlrev_b32_e32 v4, 2, v10
	v_mov_b32_e32 v5, v2
	v_lshlrev_b32_e32 v3, 2, v1
	s_waitcnt vmcnt(6)
	v_lshl_add_u64 v[8:9], s[14:15], 0, v[4:5]
	s_lshl_b64 s[44:45], s[42:43], 2
	global_load_dword v6, v3, s[14:15]
	global_load_dword v7, v4, s[14:15] offset:2048
	v_add_co_u32_e32 v4, vcc, 0x2000, v8
	s_add_u32 s44, s46, s44
	s_nop 0
	v_addc_co_u32_e32 v5, vcc, 0, v9, vcc
	s_addc_u32 s45, s47, s45
	global_load_dword v8, v[4:5], off
	s_nop 0
	global_load_dword v3, v3, s[44:45]
	v_add_u32_e32 v5, 0xffffff8f, v0
	s_lshl_b32 s44, s11, 13
	s_lshl_b32 s45, s11, 7
	s_add_i32 s46, s44, -16
	s_add_i32 s47, s45, 0x4070
	v_cmp_gt_u32_e32 vcc, s91, v5
	v_mov_b32_e32 v9, 0
	v_lshlrev_b32_e32 v4, 1, v10
	v_mov_b32_e32 v10, 0
	v_mov_b32_e32 v120, 0
	s_and_saveexec_b64 s[14:15], vcc
	s_cbranch_execz .LBB0_885
	v_mov_b32_e32 v10, s46
	v_mov_b32_e32 v11, s47
	v_cmp_eq_u32_e32 vcc, 15, v5
	s_nop 1
	v_cndmask_b32_e32 v10, v10, v11, vcc
	v_add_u32_e32 v5, v10, v5
	v_mov_b64_e32 v[10:11], s[40:41]
	v_mad_i64_i32 v[10:11], s[48:49], v5, s26, v[10:11]
	v_mov_b32_e32 v5, v2
	v_lshl_add_u64 v[10:11], v[10:11], 0, v[4:5]
	global_load_ushort v120, v[10:11], off
.LBB0_885:
	s_or_b64 exec, exec, s[14:15]
	v_add_u32_e32 v11, 0xffffff90, v0
	v_cmp_gt_u32_e32 vcc, s91, v11
	v_mov_b32_e32 v121, 0
	s_and_saveexec_b64 s[14:15], vcc
	s_cbranch_execz .LBB0_887
	v_mov_b32_e32 v5, s46
	v_mov_b32_e32 v9, s47
	v_cmp_eq_u32_e32 vcc, 0, v11
	v_mov_b64_e32 v[14:15], s[40:41]
	s_nop 0
	v_cndmask_b32_e32 v5, v5, v9, vcc
	v_add_u32_e32 v5, v5, v11
	v_mad_i64_i32 v[14:15], s[48:49], v5, s26, v[14:15]
	v_mov_b32_e32 v5, v2
	v_lshl_add_u64 v[14:15], v[14:15], 0, v[4:5]
	global_load_ushort v121, v[14:15], off
.LBB0_887:
	s_or_b64 exec, exec, s[14:15]
	s_movk_i32 s14, 0x200f
	v_cmp_gt_u32_e32 vcc, s14, v11
	v_mov_b32_e32 v13, 0
	v_mov_b32_e32 v14, 0
	v_mov_b32_e32 v122, 0
	s_and_saveexec_b64 s[14:15], vcc
	s_cbranch_execz .LBB0_889
	v_mov_b32_e32 v5, s46
	v_mov_b32_e32 v14, s47
	v_cmp_eq_u32_e32 vcc, 0, v11
	s_movk_i32 s48, 0xff91
	s_nop 0
	v_cndmask_b32_e32 v5, v5, v14, vcc
	v_add3_u32 v5, v0, v5, s48
	v_mov_b64_e32 v[14:15], s[40:41]
	v_mad_i64_i32 v[14:15], s[48:49], v5, s26, v[14:15]
	v_mov_b32_e32 v5, v2
	v_lshl_add_u64 v[14:15], v[14:15], 0, v[4:5]
	global_load_ushort v122, v[14:15], off
.LBB0_889:
	s_or_b64 exec, exec, s[14:15]
	s_movk_i32 s14, 0x200e
	v_cmp_gt_u32_e32 vcc, s14, v11
	v_mov_b32_e32 v123, 0
	s_and_saveexec_b64 s[14:15], vcc
	s_cbranch_execz .LBB0_891
	v_mov_b32_e32 v5, s46
	v_mov_b32_e32 v13, s47
	v_cmp_eq_u32_e32 vcc, 0, v11
	s_movk_i32 s48, 0xff92
	v_mov_b64_e32 v[16:17], s[40:41]
	v_cndmask_b32_e32 v5, v5, v13, vcc
	v_add3_u32 v5, v0, v5, s48
	v_mad_i64_i32 v[16:17], s[48:49], v5, s26, v[16:17]
	v_mov_b32_e32 v5, v2
	v_lshl_add_u64 v[16:17], v[16:17], 0, v[4:5]
	global_load_ushort v123, v[16:17], off
.LBB0_891:
	s_or_b64 exec, exec, s[14:15]
	s_movk_i32 s14, 0x200d
	v_cmp_gt_u32_e32 vcc, s14, v11
	v_mov_b32_e32 v15, 0
	v_mov_b32_e32 v16, 0
	v_mov_b32_e32 v124, 0
	s_and_saveexec_b64 s[14:15], vcc
	s_cbranch_execz .LBB0_893
	v_mov_b32_e32 v5, s46
	v_mov_b32_e32 v16, s47
	v_cmp_eq_u32_e32 vcc, 0, v11
	s_movk_i32 s48, 0xff93
	s_nop 0
	v_cndmask_b32_e32 v5, v5, v16, vcc
	v_add3_u32 v5, v0, v5, s48
	v_mov_b64_e32 v[16:17], s[40:41]
	v_mad_i64_i32 v[16:17], s[48:49], v5, s26, v[16:17]
	v_mov_b32_e32 v5, v2
	v_lshl_add_u64 v[16:17], v[16:17], 0, v[4:5]
	global_load_ushort v124, v[16:17], off
.LBB0_893:
	s_or_b64 exec, exec, s[14:15]
	s_movk_i32 s14, 0x200c
	v_cmp_gt_u32_e32 vcc, s14, v11
	v_mov_b32_e32 v125, 0
	s_and_saveexec_b64 s[14:15], vcc
	s_cbranch_execz .LBB0_895
	v_mov_b32_e32 v5, s46
	v_mov_b32_e32 v15, s47
	v_cmp_eq_u32_e32 vcc, 0, v11
	s_movk_i32 s48, 0xff94
	v_mov_b64_e32 v[18:19], s[40:41]
	v_cndmask_b32_e32 v5, v5, v15, vcc
	v_add3_u32 v5, v0, v5, s48
	v_mad_i64_i32 v[18:19], s[48:49], v5, s26, v[18:19]
	v_mov_b32_e32 v5, v2
	v_lshl_add_u64 v[18:19], v[18:19], 0, v[4:5]
	global_load_ushort v125, v[18:19], off
.LBB0_895:
	s_or_b64 exec, exec, s[14:15]
	s_movk_i32 s14, 0x200b
	v_cmp_gt_u32_e32 vcc, s14, v11
	v_mov_b32_e32 v17, 0
	v_mov_b32_e32 v18, 0
	v_mov_b32_e32 v126, 0
	s_and_saveexec_b64 s[14:15], vcc
	s_cbranch_execz .LBB0_897
	v_mov_b32_e32 v5, s46
	v_mov_b32_e32 v18, s47
	v_cmp_eq_u32_e32 vcc, 0, v11
	s_movk_i32 s48, 0xff95
	s_nop 0
	v_cndmask_b32_e32 v5, v5, v18, vcc
	v_add3_u32 v5, v0, v5, s48
	v_mov_b64_e32 v[18:19], s[40:41]
	v_mad_i64_i32 v[18:19], s[48:49], v5, s26, v[18:19]
	v_mov_b32_e32 v5, v2
	v_lshl_add_u64 v[18:19], v[18:19], 0, v[4:5]
	global_load_ushort v126, v[18:19], off
; __device__ __forceinline__ float bf2f(bf16_t b) { return __uint_as_float(((unsigned)b) << 16); }
; __device__ __forceinline__ void conv3_16(const bf16_t* P, const float* cw, const float* cbias, int b, int t0, int col, float (&out)[16]) {
;     const int cc = col - 1024; const float w0 = cw[cc], w1 = cw[1536 + cc], w2 = cw[3072 + cc], bb = cbias[cc];
;     float xv[18];
; #pragma unroll
;     for (int q = 0; q < 18; ++q) { const int t = t0 - 1 + q; xv[q] = (t >= 0 && t < T) ? bf2f(P[(size_t)row_of(b, t) * NMIX + col]) : 0.f; }
.LBB0_897:
	s_or_b64 exec, exec, s[14:15]
	s_movk_i32 s14, 0x200a
	v_cmp_gt_u32_e32 vcc, s14, v11
	v_mov_b32_e32 v127, 0
	s_and_saveexec_b64 s[14:15], vcc
	s_cbranch_execz .LBB0_899
	v_mov_b32_e32 v5, s46
	v_mov_b32_e32 v17, s47
	v_cmp_eq_u32_e32 vcc, 0, v11
	s_movk_i32 s48, 0xff96
	v_mov_b64_e32 v[20:21], s[40:41]
	v_cndmask_b32_e32 v5, v5, v17, vcc
	v_add3_u32 v5, v0, v5, s48
	v_mad_i64_i32 v[20:21], s[48:49], v5, s26, v[20:21]
	v_mov_b32_e32 v5, v2
	v_lshl_add_u64 v[20:21], v[20:21], 0, v[4:5]
	global_load_ushort v127, v[20:21], off
.LBB0_899:
	s_or_b64 exec, exec, s[14:15]
	s_movk_i32 s14, 0x2009
	v_cmp_gt_u32_e32 vcc, s14, v11
	v_mov_b32_e32 v19, 0
	v_mov_b32_e32 v20, 0
	v_mov_b32_e32 v128, 0
	s_and_saveexec_b64 s[14:15], vcc
	s_cbranch_execz .LBB0_901
	v_mov_b32_e32 v5, s46
	v_mov_b32_e32 v20, s47
	v_cmp_eq_u32_e32 vcc, 0, v11
	s_movk_i32 s48, 0xff97
	s_nop 0
	v_cndmask_b32_e32 v5, v5, v20, vcc
	v_add3_u32 v5, v0, v5, s48
	v_mov_b64_e32 v[20:21], s[40:41]
	v_mad_i64_i32 v[20:21], s[48:49], v5, s26, v[20:21]
	v_mov_b32_e32 v5, v2
	v_lshl_add_u64 v[20:21], v[20:21], 0, v[4:5]
	global_load_ushort v128, v[20:21], off
.LBB0_901:
	s_or_b64 exec, exec, s[14:15]
	s_movk_i32 s14, 0x2008
	v_cmp_gt_u32_e32 vcc, s14, v11
	v_mov_b32_e32 v129, 0
	s_and_saveexec_b64 s[14:15], vcc
	s_cbranch_execz .LBB0_903
	v_mov_b32_e32 v5, s46
	v_mov_b32_e32 v19, s47
	v_cmp_eq_u32_e32 vcc, 0, v11
	s_movk_i32 s48, 0xff98
	v_mov_b64_e32 v[22:23], s[40:41]
	v_cndmask_b32_e32 v5, v5, v19, vcc
	v_add3_u32 v5, v0, v5, s48
	v_mad_i64_i32 v[22:23], s[48:49], v5, s26, v[22:23]
	v_mov_b32_e32 v5, v2
	v_lshl_add_u64 v[22:23], v[22:23], 0, v[4:5]
	global_load_ushort v129, v[22:23], off
.LBB0_903:
	s_or_b64 exec, exec, s[14:15]
	s_movk_i32 s14, 0x2007
	v_cmp_gt_u32_e32 vcc, s14, v11
	v_mov_b32_e32 v28, 0
	v_mov_b32_e32 v29, 0
	v_mov_b32_e32 v130, 0
	s_and_saveexec_b64 s[14:15], vcc
	s_cbranch_execz .LBB0_905
	v_mov_b32_e32 v5, s46
	v_mov_b32_e32 v21, s47
	v_cmp_eq_u32_e32 vcc, 0, v11
	s_movk_i32 s48, 0xff99
	v_mov_b64_e32 v[22:23], s[40:41]
	v_cndmask_b32_e32 v5, v5, v21, vcc
	v_add3_u32 v5, v0, v5, s48
	v_mad_i64_i32 v[22:23], s[48:49], v5, s26, v[22:23]
	v_mov_b32_e32 v5, v2
	v_lshl_add_u64 v[22:23], v[22:23], 0, v[4:5]
	global_load_ushort v130, v[22:23], off
.LBB0_905:
	s_or_b64 exec, exec, s[14:15]
	s_movk_i32 s14, 0x2006
	v_cmp_gt_u32_e32 vcc, s14, v11
	v_mov_b32_e32 v131, 0
	s_and_saveexec_b64 s[14:15], vcc
	s_cbranch_execz .LBB0_907
	v_mov_b32_e32 v5, s46
	v_mov_b32_e32 v21, s47
	v_cmp_eq_u32_e32 vcc, 0, v11
	s_movk_i32 s48, 0xff9a
	v_mov_b64_e32 v[22:23], s[40:41]
	v_cndmask_b32_e32 v5, v5, v21, vcc
	v_add3_u32 v5, v0, v5, s48
	v_mad_i64_i32 v[22:23], s[48:49], v5, s26, v[22:23]
	v_mov_b32_e32 v5, v2
	v_lshl_add_u64 v[22:23], v[22:23], 0, v[4:5]
	global_load_ushort v131, v[22:23], off
.LBB0_907:
	s_or_b64 exec, exec, s[14:15]
	s_movk_i32 s14, 0x2005
	v_cmp_gt_u32_e32 vcc, s14, v11
	v_mov_b32_e32 v30, 0
	v_mov_b32_e32 v31, 0
	v_mov_b32_e32 v132, 0
	s_and_saveexec_b64 s[14:15], vcc
	s_cbranch_execz .LBB0_909
	v_mov_b32_e32 v5, s46
	v_mov_b32_e32 v21, s47
	v_cmp_eq_u32_e32 vcc, 0, v11
	s_movk_i32 s48, 0xff9b
	v_mov_b64_e32 v[22:23], s[40:41]
	v_cndmask_b32_e32 v5, v5, v21, vcc
	v_add3_u32 v5, v0, v5, s48
	v_mad_i64_i32 v[22:23], s[48:49], v5, s26, v[22:23]
	v_mov_b32_e32 v5, v2
	v_lshl_add_u64 v[22:23], v[22:23], 0, v[4:5]
	global_load_ushort v132, v[22:23], off
.LBB0_909:
	s_or_b64 exec, exec, s[14:15]
	s_movk_i32 s14, 0x2004
	v_cmp_gt_u32_e32 vcc, s14, v11
	v_mov_b32_e32 v133, 0
	s_and_saveexec_b64 s[14:15], vcc
	s_cbranch_execz .LBB0_911
	v_mov_b32_e32 v5, s46
	v_mov_b32_e32 v21, s47
	v_cmp_eq_u32_e32 vcc, 0, v11
	s_movk_i32 s48, 0xff9c
	v_mov_b64_e32 v[22:23], s[40:41]
	v_cndmask_b32_e32 v5, v5, v21, vcc
	v_add3_u32 v5, v0, v5, s48
	v_mad_i64_i32 v[22:23], s[48:49], v5, s26, v[22:23]
	v_mov_b32_e32 v5, v2
	v_lshl_add_u64 v[22:23], v[22:23], 0, v[4:5]
	global_load_ushort v133, v[22:23], off
.LBB0_911:
	s_or_b64 exec, exec, s[14:15]
	s_movk_i32 s14, 0x2003
	v_cmp_gt_u32_e32 vcc, s14, v11
	v_mov_b32_e32 v32, 0
	v_mov_b32_e32 v33, 0
	v_mov_b32_e32 v134, 0
	s_and_saveexec_b64 s[14:15], vcc
	s_cbranch_execz .LBB0_913
	v_mov_b32_e32 v5, s46
	v_mov_b32_e32 v21, s47
	v_cmp_eq_u32_e32 vcc, 0, v11
	s_movk_i32 s48, 0xff9d
	v_mov_b64_e32 v[22:23], s[40:41]
	v_cndmask_b32_e32 v5, v5, v21, vcc
	v_add3_u32 v5, v0, v5, s48
	v_mad_i64_i32 v[22:23], s[48:49], v5, s26, v[22:23]
	v_mov_b32_e32 v5, v2
	v_lshl_add_u64 v[22:23], v[22:23], 0, v[4:5]
	global_load_ushort v134, v[22:23], off
.LBB0_913:
	s_or_b64 exec, exec, s[14:15]
	s_movk_i32 s14, 0x2002
	v_cmp_gt_u32_e32 vcc, s14, v11
	v_mov_b32_e32 v135, 0
	s_and_saveexec_b64 s[14:15], vcc
	s_cbranch_execz .LBB0_915
	v_mov_b32_e32 v5, s46
	v_mov_b32_e32 v21, s47
	v_cmp_eq_u32_e32 vcc, 0, v11
	s_movk_i32 s48, 0xff9e
	v_mov_b64_e32 v[22:23], s[40:41]
	v_cndmask_b32_e32 v5, v5, v21, vcc
	v_add3_u32 v5, v0, v5, s48
	v_mad_i64_i32 v[22:23], s[48:49], v5, s26, v[22:23]
	v_mov_b32_e32 v5, v2
	v_lshl_add_u64 v[22:23], v[22:23], 0, v[4:5]
	global_load_ushort v135, v[22:23], off
.LBB0_915:
	s_or_b64 exec, exec, s[14:15]
	s_movk_i32 s14, 0x2001
	v_cmp_gt_u32_e32 vcc, s14, v11
	v_mov_b32_e32 v34, 0
	v_mov_b32_e32 v35, 0
	v_mov_b32_e32 v136, 0
	s_and_saveexec_b64 s[14:15], vcc
	s_cbranch_execz .LBB0_917
	v_mov_b32_e32 v5, s46
	v_mov_b32_e32 v21, s47
	v_cmp_eq_u32_e32 vcc, 0, v11
	s_movk_i32 s46, 0xff9f
	v_mov_b64_e32 v[22:23], s[40:41]
	v_cndmask_b32_e32 v5, v5, v21, vcc
	v_add3_u32 v5, v0, v5, s46
	v_mad_i64_i32 v[22:23], s[46:47], v5, s26, v[22:23]
	v_mov_b32_e32 v5, v2
	v_lshl_add_u64 v[22:23], v[22:23], 0, v[4:5]
	global_load_ushort v136, v[22:23], off
; __device__ __forceinline__ float bf2f(bf16_t b) { return __uint_as_float(((unsigned)b) << 16); }
; #define p (*kparams())
; __device__ __forceinline__ void conv3_16(const bf16_t* P, const float* cw, const float* cbias, int b, int t0, int col, float (&out)[16]) {
;     const int cc = col - 1024; const float w0 = cw[cc], w1 = cw[1536 + cc], w2 = cw[3072 + cc], bb = cbias[cc];
;     float xv[18];
; #pragma unroll
;     for (int q = 0; q < 18; ++q) { const int t = t0 - 1 + q; xv[q] = (t >= 0 && t < T) ? bf2f(P[(size_t)row_of(b, t) * NMIX + col]) : 0.f; }
; #pragma unroll
;     for (int tt = 0; tt < 16; ++tt) out[tt] = bb + w0 * xv[tt] + w1 * xv[tt + 1] + w2 * xv[tt + 2];
; __device__ __forceinline__ void hy_s3_item(CParams& p, int layer, int item) {
;     ...
;     const bf16_t* YT = (const bf16_t*)(p.ws + R_YT) + ((size_t)ch * 2 + b) * TF + (t0 + FOFF);
;     const u32x4 ya = *(const u32x4*)YT, yb = *(const u32x4*)(YT + 8);
.LBB0_917:
	s_or_b64 exec, exec, s[14:15]
	v_cmp_gt_u32_e32 vcc, s67, v11
	v_mov_b32_e32 v137, 0
	s_and_saveexec_b64 s[14:15], vcc
	s_cbranch_execz .LBB0_919
	v_or_b32_e32 v5, s44, v11
	v_mov_b64_e32 v[22:23], s[40:41]
	v_mad_i64_i32 v[22:23], s[40:41], v5, s26, v[22:23]
	v_mov_b32_e32 v5, v2
	v_lshl_add_u64 v[4:5], v[22:23], 0, v[4:5]
	global_load_ushort v137, v[4:5], off
.LBB0_919:
	s_or_b64 exec, exec, s[14:15]
	s_waitcnt vmcnt(0)
	v_lshlrev_b32_e32 v10, 16, v120
	v_lshlrev_b32_e32 v9, 16, v121
	v_lshlrev_b32_e32 v14, 16, v122
	v_lshlrev_b32_e32 v13, 16, v123
	v_lshlrev_b32_e32 v16, 16, v124
	v_lshlrev_b32_e32 v15, 16, v125
	v_lshlrev_b32_e32 v18, 16, v126
	v_lshlrev_b32_e32 v17, 16, v127
	v_lshlrev_b32_e32 v20, 16, v128
	v_lshlrev_b32_e32 v19, 16, v129
	v_lshlrev_b32_e32 v29, 16, v130
	v_lshlrev_b32_e32 v28, 16, v131
	v_lshlrev_b32_e32 v31, 16, v132
	v_lshlrev_b32_e32 v30, 16, v133
	v_lshlrev_b32_e32 v33, 16, v134
	v_lshlrev_b32_e32 v32, 16, v135
	v_lshlrev_b32_e32 v35, 16, v136
	v_lshlrev_b32_e32 v34, 16, v137
	s_waitcnt vmcnt(0)
	v_fma_f32 v22, v6, v18, v3
	v_fmac_f32_e32 v22, v7, v17
	v_fma_f32 v21, v6, v17, v3
	v_fma_f32 v24, v6, v16, v3
	v_fmac_f32_e32 v22, v8, v20
	v_fmac_f32_e32 v21, v7, v20
	v_fma_f32 v20, v6, v20, v3
	v_fmac_f32_e32 v24, v7, v15
	v_fma_f32 v23, v6, v15, v3
	v_fmac_f32_e32 v21, v8, v19
	v_fmac_f32_e32 v20, v7, v19
	v_fma_f32 v19, v6, v19, v3
	v_fmac_f32_e32 v24, v8, v18
	v_fmac_f32_e32 v23, v7, v18
	v_fmac_f32_e32 v19, v7, v29
	v_fma_f32 v18, v6, v29, v3
	v_fmac_f32_e32 v23, v8, v17
	v_fmac_f32_e32 v19, v8, v28
	v_fmac_f32_e32 v18, v7, v28
	v_fma_f32 v17, v6, v28, v3
	v_lshlrev_b32_e32 v28, 1, v1
	v_add_u32_e32 v1, s11, v28
	v_mov_b64_e32 v[4:5], s[30:31]
	s_movk_i32 s14, 0x4100
	v_mad_i64_i32 v[4:5], s[14:15], v1, s14, v[4:5]
	v_mov_b32_e32 v1, v2
	v_fma_f32 v36, v6, v10, v3
	v_fma_f32 v26, v6, v14, v3
	v_fma_f32 v25, v6, v13, v3
	v_lshl_add_u64 v[0:1], v[0:1], 1, v[4:5]
	s_mov_b64 s[14:15], 0x3a270000
	v_fmac_f32_e32 v36, v7, v9
	v_fma_f32 v27, v6, v9, v3
	v_fmac_f32_e32 v26, v7, v13
	v_fmac_f32_e32 v25, v7, v16
	v_lshl_add_u64 v[4:5], v[0:1], 0, s[14:15]
	s_mov_b32 s14, 0x3a270000
	v_fmac_f32_e32 v36, v8, v14
	v_fmac_f32_e32 v27, v7, v14
	v_fmac_f32_e32 v26, v8, v16
	v_fmac_f32_e32 v25, v8, v15
	v_fma_f32 v16, v6, v31, v3
	v_fma_f32 v15, v6, v30, v3
	v_fma_f32 v14, v6, v33, v3
	v_fmac_f32_e32 v3, v6, v32
	v_add_co_u32_e32 v0, vcc, s14, v0
	v_fmac_f32_e32 v17, v7, v31
	v_fmac_f32_e32 v16, v7, v30
	v_fmac_f32_e32 v15, v7, v33
	v_fmac_f32_e32 v14, v7, v32
	v_fmac_f32_e32 v3, v7, v35
	v_addc_co_u32_e32 v1, vcc, 0, v1, vcc
	v_fmac_f32_e32 v27, v8, v13
	v_fmac_f32_e32 v20, v8, v29
	v_fmac_f32_e32 v18, v8, v31
	v_fmac_f32_e32 v17, v8, v30
	v_fmac_f32_e32 v16, v8, v33
	v_fmac_f32_e32 v15, v8, v32
	v_fmac_f32_e32 v14, v8, v35
	v_fmac_f32_e32 v3, v8, v34
	global_load_dwordx4 v[8:11], v[0:1], off
	s_nop 0
	global_load_dwordx4 v[4:7], v[4:5], off offset:16
	s_add_i32 s14, s44, s39
	s_addk_i32 s45, 0x4000
	s_addk_i32 s14, 0xff80
	s_cmp_eq_u32 s36, 0
	s_cselect_b32 s14, s45, s14
	v_add_u32_e32 v0, s14, v12
	v_mov_b32_e32 v29, v2
	v_lshl_add_u64 v[12:13], s[4:5], 0, v[28:29]
	s_waitcnt vmcnt(1)
; __device__ __forceinline__ unsigned f2bf(float f) { return pk2(f, 0.f) & 0xffffu; }
; __device__ __forceinline__ void hy_s3_item(CParams& p, int layer, int item) {
;     ...
; #pragma unroll
;     for (int tt = 0; tt < 16; ++tt) { const unsigned wv = (tt < 8) ? ya[tt >> 1] : yb[(tt - 8) >> 1];
;         const float y = (tt & 1) ? __uint_as_float(wv & 0xffff0000u) : __uint_as_float(wv << 16);
;         Z[(size_t)row_bci(b, c, 16 * tq + tt) * D + 512 + ch] = (bf16_t)f2bf(x0[tt] * y); }
	v_lshlrev_b32_e32 v1, 16, v8
	v_mul_f32_e32 v1, v36, v1
	v_cvt_pk_bf16_f32 v30, v1, s0
	v_ashrrev_i32_e32 v1, 31, v0
	v_lshlrev_b64 v[28:29], 12, v[0:1]
	v_lshl_add_u64 v[28:29], v[12:13], 0, v[28:29]
	global_store_short v[28:29], v30, off offset:1024
	v_or_b32_e32 v28, 1, v0
	v_and_b32_e32 v1, 0xffff0000, v8
	v_ashrrev_i32_e32 v29, 31, v28
	v_mul_f32_e32 v1, v27, v1
	v_lshlrev_b64 v[28:29], 12, v[28:29]
	v_cvt_pk_bf16_f32 v1, v1, s0
	v_lshl_add_u64 v[28:29], v[12:13], 0, v[28:29]
	global_store_short v[28:29], v1, off offset:1024
	v_lshlrev_b32_e32 v1, 16, v9
	v_mul_f32_e32 v1, v26, v1
	v_or_b32_e32 v26, 2, v0
	v_ashrrev_i32_e32 v27, 31, v26
	v_lshlrev_b64 v[26:27], 12, v[26:27]
	v_cvt_pk_bf16_f32 v1, v1, s0
	v_lshl_add_u64 v[26:27], v[12:13], 0, v[26:27]
	v_or_b32_e32 v8, 3, v0
	global_store_short v[26:27], v1, off offset:1024
	v_and_b32_e32 v1, 0xffff0000, v9
	v_ashrrev_i32_e32 v9, 31, v8
	v_mul_f32_e32 v1, v25, v1
	v_lshlrev_b64 v[8:9], 12, v[8:9]
	v_cvt_pk_bf16_f32 v1, v1, s0
	v_lshl_add_u64 v[8:9], v[12:13], 0, v[8:9]
	global_store_short v[8:9], v1, off offset:1024
	v_or_b32_e32 v8, 4, v0
	v_lshlrev_b32_e32 v1, 16, v10
	v_ashrrev_i32_e32 v9, 31, v8
	v_mul_f32_e32 v1, v24, v1
	v_lshlrev_b64 v[8:9], 12, v[8:9]
	v_cvt_pk_bf16_f32 v1, v1, s0
	v_lshl_add_u64 v[8:9], v[12:13], 0, v[8:9]
	global_store_short v[8:9], v1, off offset:1024
	v_or_b32_e32 v8, 5, v0
	v_and_b32_e32 v1, 0xffff0000, v10
	v_ashrrev_i32_e32 v9, 31, v8
	v_mul_f32_e32 v1, v23, v1
	v_lshlrev_b64 v[8:9], 12, v[8:9]
	v_cvt_pk_bf16_f32 v1, v1, s0
	v_lshl_add_u64 v[8:9], v[12:13], 0, v[8:9]
	global_store_short v[8:9], v1, off offset:1024
	v_or_b32_e32 v8, 6, v0
	v_lshlrev_b32_e32 v1, 16, v11
	v_ashrrev_i32_e32 v9, 31, v8
	v_mul_f32_e32 v1, v22, v1
	v_lshlrev_b64 v[8:9], 12, v[8:9]
	v_cvt_pk_bf16_f32 v1, v1, s0
	v_lshl_add_u64 v[8:9], v[12:13], 0, v[8:9]
	global_store_short v[8:9], v1, off offset:1024
	v_or_b32_e32 v8, 7, v0
	v_and_b32_e32 v1, 0xffff0000, v11
	v_ashrrev_i32_e32 v9, 31, v8
	v_mul_f32_e32 v1, v21, v1
	v_lshlrev_b64 v[8:9], 12, v[8:9]
	v_cvt_pk_bf16_f32 v1, v1, s0
	v_lshl_add_u64 v[8:9], v[12:13], 0, v[8:9]
	global_store_short v[8:9], v1, off offset:1024
	v_or_b32_e32 v8, 8, v0
	s_waitcnt vmcnt(8)
	v_lshlrev_b32_e32 v1, 16, v4
	v_ashrrev_i32_e32 v9, 31, v8
	v_mul_f32_e32 v1, v20, v1
	v_lshlrev_b64 v[8:9], 12, v[8:9]
	v_cvt_pk_bf16_f32 v1, v1, s0
	v_lshl_add_u64 v[8:9], v[12:13], 0, v[8:9]
	global_store_short v[8:9], v1, off offset:1024
	v_or_b32_e32 v8, 9, v0
	v_and_b32_e32 v1, 0xffff0000, v4
	v_ashrrev_i32_e32 v9, 31, v8
	v_mul_f32_e32 v1, v19, v1
	v_lshlrev_b64 v[8:9], 12, v[8:9]
	v_cvt_pk_bf16_f32 v1, v1, s0
	v_lshl_add_u64 v[8:9], v[12:13], 0, v[8:9]
	global_store_short v[8:9], v1, off offset:1024
	v_or_b32_e32 v8, 10, v0
	v_lshlrev_b32_e32 v1, 16, v5
	v_ashrrev_i32_e32 v9, 31, v8
	v_mul_f32_e32 v1, v18, v1
	v_lshlrev_b64 v[8:9], 12, v[8:9]
	v_cvt_pk_bf16_f32 v1, v1, s0
	v_lshl_add_u64 v[8:9], v[12:13], 0, v[8:9]
	v_or_b32_e32 v4, 11, v0
	global_store_short v[8:9], v1, off offset:1024
	v_and_b32_e32 v1, 0xffff0000, v5
	v_ashrrev_i32_e32 v5, 31, v4
	v_mul_f32_e32 v1, v17, v1
	v_lshlrev_b64 v[4:5], 12, v[4:5]
	v_cvt_pk_bf16_f32 v1, v1, s0
	v_lshl_add_u64 v[4:5], v[12:13], 0, v[4:5]
	global_store_short v[4:5], v1, off offset:1024
	v_or_b32_e32 v4, 12, v0
	v_lshlrev_b32_e32 v1, 16, v6
	v_ashrrev_i32_e32 v5, 31, v4
	v_mul_f32_e32 v1, v16, v1
	v_lshlrev_b64 v[4:5], 12, v[4:5]
	v_cvt_pk_bf16_f32 v1, v1, s0
	v_lshl_add_u64 v[4:5], v[12:13], 0, v[4:5]
	global_store_short v[4:5], v1, off offset:1024
	v_or_b32_e32 v4, 13, v0
	v_and_b32_e32 v1, 0xffff0000, v6
	v_ashrrev_i32_e32 v5, 31, v4
	v_mul_f32_e32 v1, v15, v1
	v_lshlrev_b64 v[4:5], 12, v[4:5]
	v_cvt_pk_bf16_f32 v1, v1, s0
	v_lshl_add_u64 v[4:5], v[12:13], 0, v[4:5]
	global_store_short v[4:5], v1, off offset:1024
	v_or_b32_e32 v4, 14, v0
	v_lshlrev_b32_e32 v1, 16, v7
	v_ashrrev_i32_e32 v5, 31, v4
	v_mul_f32_e32 v1, v14, v1
	v_lshlrev_b64 v[4:5], 12, v[4:5]
	v_cvt_pk_bf16_f32 v1, v1, s0
	v_lshl_add_u64 v[4:5], v[12:13], 0, v[4:5]
	global_store_short v[4:5], v1, off offset:1024
	v_and_b32_e32 v1, 0xffff0000, v7
	v_mul_f32_e32 v1, v3, v1
	v_or_b32_e32 v0, 15, v0
	v_cvt_pk_bf16_f32 v3, v1, s0
	v_ashrrev_i32_e32 v1, 31, v0
	v_lshlrev_b64 v[0:1], 12, v[0:1]
	v_lshl_add_u64 v[0:1], v[12:13], 0, v[0:1]
	global_store_short v[0:1], v3, off offset:1024
